# loadprio + packed SwiGLU epilogue + GU loop full-line LDS layout (16 rows x 128B sub-tiles, pair-preserving swizzle, full 128B lines per DMA)
# baseline (speedup 1.0000x reference)
; #define PG8_STAGE(bufoff, gbase, voff) do { _Pragma("unroll") for (int _i = 0; _i < 2; ++_i) \
;         __builtin_amdgcn_global_load_lds((const unsigned*)((const char*)(gbase) + (voff)[_i]), (PG8_LAS unsigned*)(lds + (bufoff) + ldsw + _i * 8192), 16, 0, 0); } while (0)
; #define PG8_WAIT_V(n) asm volatile("s_waitcnt vmcnt(" #n ")" ::: "memory")
; #define PG8_BAR __builtin_amdgcn_s_barrier()
; template <class Epi, class Sched, bool ALIGN_EPI = false, bool SP2 = false>
; __device__ __forceinline__ void gemm_phase(PG8_LAS unsigned char* lds, const Gemm g, const Sched& S, const Epi& E, int tid_in) {
;     ...
;     for (int i = 0; i < 2; ++i) { int R, C; stage_rc(tid * 16 + i * 8192, R, C); const int Rb = Epi::PERM ? ((R & ~31) + perm32(R & 31)) : R;
;         voffA[i] = (unsigned)(R * K + C) * 2u; voffB[i] = (unsigned)(Rb * K + C) * 2u; }
;     const size_t kstep = (size_t)(BK * 2);
;     const size_t hstep = (size_t)HALF * K * 2;
;     const size_t tstep = 2 * hstep;
;     const unsigned ldsw = (unsigned)wid * 1024u;
;     const int aoff = lds_byte(wr * 64 + fr, fq * 8), boff = lds_byte(wc * 32 + fr, fq * 8);
;     ...
;         PG8_WAIT_V(2); PG8_BAR;
;         PG8_STAGE(PG8_SB(1, 0), cB + kstep, voffB); PG8_STAGE(PG8_SA(1, 0), cA + kstep, voffA); PG8_STAGE(PG8_SB(1, 1), cB + hstep + kstep, voffB);
;         PG8_WAIT_V(6); PG8_BAR;
.LBB0_104:
	s_add_i32 m0, s18, 0x18000
	v_lshl_add_u64 v[6:7], v[6:7], 0, s[70:71]
	s_waitcnt vmcnt(2)
	s_barrier
	global_load_lds_dwordx4 v[6:7], off
	v_lshl_add_u64 v[6:7], v[8:9], 0, s[70:71]
	s_add_i32 m0, s18, 0x1a000
	s_add_i32 s22, s18, 0x8000
	global_load_lds_dwordx4 v[6:7], off
	v_lshl_add_u64 v[6:7], v[10:11], 0, s[70:71]
	s_mov_b32 m0, s22
	s_add_i32 s23, s18, 0xa000
	global_load_lds_dwordx4 v[6:7], off
	v_lshl_add_u64 v[6:7], v[12:13], 0, s[70:71]
	s_mov_b32 m0, s23
	s_lshl_b32 s10, s10, 1
	global_load_lds_dwordx4 v[6:7], off
	v_lshl_add_u64 v[6:7], v[2:3], 0, s[86:87]
	s_add_i32 m0, s18, 0x1c000
	v_lshl_add_u64 v[8:9], v[6:7], 0, v[128:129]
	global_load_lds_dwordx4 v[8:9], off
	v_lshl_add_u64 v[6:7], v[6:7], 0, v[144:145]
	s_add_i32 m0, s18, 0x1e000
	s_mov_b32 s11, s49
	global_load_lds_dwordx4 v[6:7], off
	v_lshl_add_u64 v[0:1], v[0:1], 0, s[10:11]
	v_lshl_add_u64 v[150:151], v[0:1], 0, s[40:41]
	v_lshrrev_b32_e32 v1, 1, v14
	v_and_b32_e32 v1, 24, v1
	v_and_b32_e32 v0, 15, v14
	v_lshlrev_b32_e32 v6, 1, v1
	v_lshl_or_b32 v163, s9, 6, v0
	v_lshl_or_b32 v0, v0, 6, v6
	v_lshlrev_b32_e32 v6, 2, v14
	s_sext_i32_i8 s3, s4
	s_lshl_b32 s4, s9, 13
	v_and_b32_e32 v6, 32, v6
	v_bitop3_b32 v7, v0, s4, v6 bitop3:0xde
	s_lshl_b32 s4, s8, 5
	s_and_b32 s4, s4, 0x60
	s_lshl_b32 s8, s4, 7
	v_bitop3_b32 v168, v0, s8, v6 bitop3:0xde
	v_add_u32_e32 v173, 0x10000, v168
	v_lshlrev_b32_e32 v0, 15, v15
	v_and_b32_e32 v0, 0xffff0000, v0
	v_or_b32_e32 v169, s4, v1
	v_lshl_add_u32 v0, v16, 12, v0
	v_and_b32_e32 v1, 1, v15
	v_lshl_or_b32 v0, v1, 6, v0
	v_lshl_add_u32 v152, v17, 1, v0
	v_lshlrev_b32_e32 v0, 15, v19
	v_and_b32_e32 v0, 0xffff0000, v0
	s_waitcnt vmcnt(6)
	v_lshl_add_u32 v0, v18, 12, v0
	v_and_b32_e32 v1, 1, v19
	s_cmpk_lt_u32 s5, 0x100
	v_lshl_or_b32 v0, v1, 6, v0
	s_cselect_b64 s[8:9], -1, 0
	v_mov_b32_e32 v153, v129
	v_lshl_add_u32 v154, v20, 1, v0
	v_mov_b32_e32 v155, v129
	s_mov_b32 s24, 0
	v_add_u32_e32 v175, 0, v7
	s_barrier
	s_branch .LBB0_107

; #define PG8_STAGE(bufoff, gbase, voff) do { _Pragma("unroll") for (int _i = 0; _i < 2; ++_i) \
;         __builtin_amdgcn_global_load_lds((const unsigned*)((const char*)(gbase) + (voff)[_i]), (PG8_LAS unsigned*)(lds + (bufoff) + ldsw + _i * 8192), 16, 0, 0); } while (0)
; #define PG8_LDA(dst, b, h) do { _Pragma("unroll") for (int m = 0; m < 4; ++m) _Pragma("unroll") for (int k = 0; k < 2; ++k) dst[m][k] = *(const PG8_LAS bf16x8*)(lds + PG8_SA(b, h) + aoff + m * 2048 + k * 1024); } while (0)
; #define PG8_LDB(dst, b, h) do { _Pragma("unroll") for (int n = 0; n < 2; ++n) _Pragma("unroll") for (int k = 0; k < 2; ++k) dst[n][k] = *(const PG8_LAS bf16x8*)(lds + PG8_SB(b, h) + boff + n * 2048 + k * 1024); } while (0)
; #define PG8_MMA(ai, bj, At, Bt) do { __builtin_amdgcn_s_setprio(1); _Pragma("unroll") for (int m = 0; m < 4; ++m) _Pragma("unroll") for (int n = 0; n < 2; ++n) _Pragma("unroll") for (int k = 0; k < 2; ++k) \
;         acc[ai][bj][m][n] = __builtin_amdgcn_mfma_f32_16x16x32_bf16(Bt[n][k], At[m][k], acc[ai][bj][m][n], 0, 0, 0); __builtin_amdgcn_s_setprio(0); } while (0)
; #define PG8_WAIT_V(n) asm volatile("s_waitcnt vmcnt(" #n ")" ::: "memory")
; #define PG8_WAIT_L(n) asm volatile("s_waitcnt lgkmcnt(" #n ")" ::: "memory")
; #define PG8_BAR __builtin_amdgcn_s_barrier()
; #define PG8_SCHED __builtin_amdgcn_sched_barrier(0)
; template <class Epi, class Sched, bool ALIGN_EPI = false, bool SP2 = false>
; __device__ __forceinline__ void gemm_phase(PG8_LAS unsigned char* lds, const Gemm g, const Sched& S, const Epi& E, int tid_in) {
;     ...
;             PG8_LDB(B0, 0, 0); PG8_LDB(B1, 0, 1); PG8_SCHED; PG8_LDA(At, 0, 0); PG8_STAGE(PG8_SA(1, 1), a1 + hstep, voffA);
;             PG8_WAIT_V(8); PG8_WAIT_L(0); PG8_BAR; PG8_MMA(0, 0, At, B0); PG8_MMA(0, 1, At, B1); PG8_BAR; PG8_SCHED;
;             PG8_LDA(At, 0, 1); PG8_STAGE(PG8_SB(0, 0), b2, voffB); PG8_STAGE(PG8_SB(0, 1), b2 + hstep, voffB); PG8_STAGE(PG8_SA(0, 0), a2, voffA);
;             PG8_WAIT_V(8); PG8_WAIT_L(0); PG8_BAR; PG8_MMA(1, 0, At, B0); PG8_MMA(1, 1, At, B1); PG8_BAR; PG8_SCHED;
.LBB0_110:
	s_cmp_eq_u32 s11, 28
	s_cselect_b64 vcc, -1, 0
	s_add_i32 s13, 0, 0x10000
	s_add_i32 s14, 0, 0x14000
	v_lshl_add_u64 v[176:177], v[166:167], 0, s[52:53]
	v_cndmask_b32_e32 v241, v177, v131, vcc
	v_cndmask_b32_e32 v240, v176, v160, vcc
	ds_read_b128 v[176:179], v173
	ds_read_b128 v[180:183], v173 offset:1024
	ds_read_b128 v[184:187], v173 offset:2048
	ds_read_b128 v[188:191], v173 offset:3072
	ds_read_b128 v[192:195], v173 offset:16384
	ds_read_b128 v[196:199], v173 offset:17408
	ds_read_b128 v[200:203], v173 offset:18432
	ds_read_b128 v[204:207], v173 offset:19456
	v_cndmask_b32_e32 v243, v165, v161, vcc
	v_cndmask_b32_e32 v242, v164, v162, vcc
	v_lshl_add_u64 v[244:245], v[166:167], 0, v[154:155]
	s_add_i32 m0, s18, 0xc000
	ds_read_b128 v[208:211], v175
	ds_read_b128 v[212:215], v175 offset:1024
	ds_read_b128 v[216:219], v175 offset:2048
	ds_read_b128 v[220:223], v175 offset:3072
	ds_read_b128 v[224:227], v175 offset:4096
	ds_read_b128 v[228:231], v175 offset:5120
	ds_read_b128 v[232:235], v175 offset:6144
	ds_read_b128 v[236:239], v175 offset:7168
	global_load_lds_dwordx4 v[244:245], off
	v_lshl_add_u64 v[244:245], v[166:167], 0, v[152:153]
	s_add_i32 m0, s18, 0xe000
	s_nop 0
	global_load_lds_dwordx4 v[244:245], off
	s_setprio 0
	s_waitcnt vmcnt(8) lgkmcnt(0)
	s_barrier
	v_mfma_f32_16x16x32_bf16 v[124:127], v[176:179], v[208:211], v[124:127]
	v_mfma_f32_16x16x32_bf16 v[120:123], v[184:187], v[208:211], v[120:123]
	v_mfma_f32_16x16x32_bf16 v[116:119], v[176:179], v[216:219], v[116:119]
	v_mfma_f32_16x16x32_bf16 v[108:111], v[184:187], v[216:219], v[108:111]
	v_mfma_f32_16x16x32_bf16 v[100:103], v[176:179], v[224:227], v[100:103]
	v_mfma_f32_16x16x32_bf16 v[92:95], v[184:187], v[224:227], v[92:95]
	v_mfma_f32_16x16x32_bf16 v[84:87], v[176:179], v[232:235], v[84:87]
	v_mfma_f32_16x16x32_bf16 v[76:79], v[184:187], v[232:235], v[76:79]
	v_mfma_f32_16x16x32_bf16 v[124:127], v[180:183], v[212:215], v[124:127]
	v_mfma_f32_16x16x32_bf16 v[120:123], v[188:191], v[212:215], v[120:123]
	v_mfma_f32_16x16x32_bf16 v[116:119], v[180:183], v[220:223], v[116:119]
	v_mfma_f32_16x16x32_bf16 v[108:111], v[188:191], v[220:223], v[108:111]
	v_mfma_f32_16x16x32_bf16 v[100:103], v[180:183], v[228:231], v[100:103]
	v_mfma_f32_16x16x32_bf16 v[92:95], v[188:191], v[228:231], v[92:95]
	v_mfma_f32_16x16x32_bf16 v[84:87], v[180:183], v[236:239], v[84:87]
	v_mfma_f32_16x16x32_bf16 v[76:79], v[188:191], v[236:239], v[76:79]
	v_mfma_f32_16x16x32_bf16 v[112:115], v[192:195], v[208:211], v[112:115]
	v_mfma_f32_16x16x32_bf16 v[104:107], v[200:203], v[208:211], v[104:107]
	v_mfma_f32_16x16x32_bf16 v[96:99], v[192:195], v[216:219], v[96:99]
	v_mfma_f32_16x16x32_bf16 v[88:91], v[200:203], v[216:219], v[88:91]
	v_mfma_f32_16x16x32_bf16 v[80:83], v[192:195], v[224:227], v[80:83]
	v_mfma_f32_16x16x32_bf16 v[72:75], v[200:203], v[224:227], v[72:75]
	v_mfma_f32_16x16x32_bf16 v[68:71], v[192:195], v[232:235], v[68:71]
	v_mfma_f32_16x16x32_bf16 v[64:67], v[200:203], v[232:235], v[64:67]
	v_mfma_f32_16x16x32_bf16 v[112:115], v[196:199], v[212:215], v[112:115]
	v_mfma_f32_16x16x32_bf16 v[104:107], v[204:207], v[212:215], v[104:107]
	v_mfma_f32_16x16x32_bf16 v[96:99], v[196:199], v[220:223], v[96:99]
	v_mfma_f32_16x16x32_bf16 v[88:91], v[204:207], v[220:223], v[88:91]
	v_mfma_f32_16x16x32_bf16 v[80:83], v[196:199], v[228:231], v[80:83]
	v_mfma_f32_16x16x32_bf16 v[72:75], v[204:207], v[228:231], v[72:75]
	v_mfma_f32_16x16x32_bf16 v[68:71], v[196:199], v[236:239], v[68:71]
	v_mfma_f32_16x16x32_bf16 v[64:67], v[204:207], v[236:239], v[64:67]
	s_barrier
	s_setprio 1
	s_add_i32 s13, s13, s0
	v_lshl_add_u64 v[244:245], v[242:243], 0, v[128:129]
	s_mov_b32 m0, s13
	ds_read_b128 v[208:211], v175 offset:16384
	ds_read_b128 v[212:215], v175 offset:17408
	ds_read_b128 v[216:219], v175 offset:18432
	ds_read_b128 v[220:223], v175 offset:19456
	ds_read_b128 v[224:227], v175 offset:20480
	ds_read_b128 v[228:231], v175 offset:21504
	ds_read_b128 v[232:235], v175 offset:22528
	ds_read_b128 v[236:239], v175 offset:23552
	global_load_lds_dwordx4 v[244:245], off
	v_lshl_add_u64 v[246:247], v[242:243], 0, v[144:145]
	s_add_i32 m0, s13, 0x2000
	v_lshl_add_u64 v[248:249], v[242:243], 0, s[98:99]
	s_add_i32 s13, s14, s0
	global_load_lds_dwordx4 v[246:247], off
	v_lshl_add_u64 v[250:251], v[248:249], 0, v[128:129]
	s_mov_b32 m0, s13
	v_lshl_add_u64 v[248:249], v[248:249], 0, v[144:145]
	global_load_lds_dwordx4 v[250:251], off
	s_add_i32 m0, s13, 0x2000
	v_lshl_add_u64 v[250:251], v[240:241], 0, v[146:147]
	global_load_lds_dwordx4 v[248:249], off
	v_lshl_add_u64 v[248:249], v[240:241], 0, v[148:149]
	s_mov_b32 m0, s18
	s_nop 0
	global_load_lds_dwordx4 v[248:249], off
	s_mov_b32 m0, s19
	s_nop 0
	global_load_lds_dwordx4 v[250:251], off
	s_setprio 0
	s_waitcnt vmcnt(8) lgkmcnt(0)
	s_barrier
; #define PG8_STAGE(bufoff, gbase, voff) do { _Pragma("unroll") for (int _i = 0; _i < 2; ++_i) \
;         __builtin_amdgcn_global_load_lds((const unsigned*)((const char*)(gbase) + (voff)[_i]), (PG8_LAS unsigned*)(lds + (bufoff) + ldsw + _i * 8192), 16, 0, 0); } while (0)
; #define PG8_LDA(dst, b, h) do { _Pragma("unroll") for (int m = 0; m < 4; ++m) _Pragma("unroll") for (int k = 0; k < 2; ++k) dst[m][k] = *(const PG8_LAS bf16x8*)(lds + PG8_SA(b, h) + aoff + m * 2048 + k * 1024); } while (0)
; #define PG8_LDB(dst, b, h) do { _Pragma("unroll") for (int n = 0; n < 2; ++n) _Pragma("unroll") for (int k = 0; k < 2; ++k) dst[n][k] = *(const PG8_LAS bf16x8*)(lds + PG8_SB(b, h) + boff + n * 2048 + k * 1024); } while (0)
; #define PG8_MMA(ai, bj, At, Bt) do { __builtin_amdgcn_s_setprio(1); _Pragma("unroll") for (int m = 0; m < 4; ++m) _Pragma("unroll") for (int n = 0; n < 2; ++n) _Pragma("unroll") for (int k = 0; k < 2; ++k) \
;         acc[ai][bj][m][n] = __builtin_amdgcn_mfma_f32_16x16x32_bf16(Bt[n][k], At[m][k], acc[ai][bj][m][n], 0, 0, 0); __builtin_amdgcn_s_setprio(0); } while (0)
; #define PG8_WAIT_V(n) asm volatile("s_waitcnt vmcnt(" #n ")" ::: "memory")
; #define PG8_WAIT_L(n) asm volatile("s_waitcnt lgkmcnt(" #n ")" ::: "memory")
; #define PG8_BAR __builtin_amdgcn_s_barrier()
; #define PG8_SCHED __builtin_amdgcn_sched_barrier(0)
; template <class Epi, class Sched, bool ALIGN_EPI = false, bool SP2 = false>
; __device__ __forceinline__ void gemm_phase(PG8_LAS unsigned char* lds, const Gemm g, const Sched& S, const Epi& E, int tid_in) {
;     ...
;             PG8_WAIT_V(8); PG8_WAIT_L(0); PG8_BAR; PG8_MMA(1, 0, At, B0); PG8_MMA(1, 1, At, B1); PG8_BAR; PG8_SCHED;
;             PG8_LDB(B0, 1, 0); PG8_LDB(B1, 1, 1); PG8_SCHED; PG8_LDA(At, 1, 0); PG8_STAGE(PG8_SA(0, 1), a2 + hstep, voffA);
;             PG8_WAIT_V(8); PG8_WAIT_L(0); PG8_BAR; PG8_MMA(0, 0, At, B0); PG8_MMA(0, 1, At, B1); PG8_BAR; PG8_SCHED;
	v_mfma_f32_16x16x32_bf16 v[60:63], v[176:179], v[208:211], v[60:63]
	v_mfma_f32_16x16x32_bf16 v[56:59], v[184:187], v[208:211], v[56:59]
	v_mfma_f32_16x16x32_bf16 v[52:55], v[176:179], v[216:219], v[52:55]
	v_mfma_f32_16x16x32_bf16 v[44:47], v[184:187], v[216:219], v[44:47]
	v_mfma_f32_16x16x32_bf16 v[36:39], v[176:179], v[224:227], v[36:39]
	v_mfma_f32_16x16x32_bf16 v[28:31], v[184:187], v[224:227], v[28:31]
	v_mfma_f32_16x16x32_bf16 v[20:23], v[176:179], v[232:235], v[20:23]
	v_mfma_f32_16x16x32_bf16 v[12:15], v[184:187], v[232:235], v[12:15]
	v_mfma_f32_16x16x32_bf16 v[60:63], v[180:183], v[212:215], v[60:63]
	v_mfma_f32_16x16x32_bf16 v[56:59], v[188:191], v[212:215], v[56:59]
	v_mfma_f32_16x16x32_bf16 v[52:55], v[180:183], v[220:223], v[52:55]
	v_mfma_f32_16x16x32_bf16 v[44:47], v[188:191], v[220:223], v[44:47]
	v_mfma_f32_16x16x32_bf16 v[36:39], v[180:183], v[228:231], v[36:39]
	v_mfma_f32_16x16x32_bf16 v[28:31], v[188:191], v[228:231], v[28:31]
	v_mfma_f32_16x16x32_bf16 v[20:23], v[180:183], v[236:239], v[20:23]
	v_mfma_f32_16x16x32_bf16 v[12:15], v[188:191], v[236:239], v[12:15]
	v_mfma_f32_16x16x32_bf16 v[48:51], v[192:195], v[208:211], v[48:51]
	v_mfma_f32_16x16x32_bf16 v[40:43], v[200:203], v[208:211], v[40:43]
	v_mfma_f32_16x16x32_bf16 v[32:35], v[192:195], v[216:219], v[32:35]
	v_mfma_f32_16x16x32_bf16 v[24:27], v[200:203], v[216:219], v[24:27]
	v_mfma_f32_16x16x32_bf16 v[16:19], v[192:195], v[224:227], v[16:19]
	v_mfma_f32_16x16x32_bf16 v[8:11], v[200:203], v[224:227], v[8:11]
	v_mfma_f32_16x16x32_bf16 v[4:7], v[192:195], v[232:235], v[4:7]
	v_mfma_f32_16x16x32_bf16 v[0:3], v[200:203], v[232:235], v[0:3]
	v_mfma_f32_16x16x32_bf16 v[48:51], v[196:199], v[212:215], v[48:51]
	v_mfma_f32_16x16x32_bf16 v[40:43], v[204:207], v[212:215], v[40:43]
	v_mfma_f32_16x16x32_bf16 v[32:35], v[196:199], v[220:223], v[32:35]
	v_mfma_f32_16x16x32_bf16 v[24:27], v[204:207], v[220:223], v[24:27]
	v_mfma_f32_16x16x32_bf16 v[16:19], v[196:199], v[228:231], v[16:19]
	v_mfma_f32_16x16x32_bf16 v[8:11], v[204:207], v[228:231], v[8:11]
	v_mfma_f32_16x16x32_bf16 v[4:7], v[196:199], v[236:239], v[4:7]
	v_mfma_f32_16x16x32_bf16 v[0:3], v[204:207], v[236:239], v[0:3]
	s_barrier
	s_setprio 1
	s_add_i32 s13, 0, 0x18000
	s_add_i32 s14, 0, 0x1c000
	ds_read_b128 v[176:179], v173 offset:32768
	ds_read_b128 v[180:183], v173 offset:33792
	ds_read_b128 v[184:187], v173 offset:34816
	ds_read_b128 v[188:191], v173 offset:35840
	ds_read_b128 v[192:195], v173 offset:49152
	ds_read_b128 v[196:199], v173 offset:50176
	ds_read_b128 v[200:203], v173 offset:51200
	ds_read_b128 v[204:207], v173 offset:52224
	v_lshl_add_u64 v[240:241], v[240:241], 0, s[98:99]
	s_mov_b32 m0, s20
	v_lshl_add_u64 v[252:253], v[240:241], 0, v[148:149]
	ds_read_b128 v[208:211], v175 offset:32768
	ds_read_b128 v[212:215], v175 offset:33792
	ds_read_b128 v[216:219], v175 offset:34816
	ds_read_b128 v[220:223], v175 offset:35840
	ds_read_b128 v[224:227], v175 offset:36864
	ds_read_b128 v[228:231], v175 offset:37888
	ds_read_b128 v[232:235], v175 offset:38912
	ds_read_b128 v[236:239], v175 offset:39936
	global_load_lds_dwordx4 v[252:253], off
	v_lshl_add_u64 v[240:241], v[240:241], 0, v[146:147]
	s_mov_b32 m0, s21
	s_nop 0
	global_load_lds_dwordx4 v[240:241], off
	s_setprio 0
	s_waitcnt vmcnt(8) lgkmcnt(0)
	s_barrier
	v_mfma_f32_16x16x32_bf16 v[124:127], v[176:179], v[208:211], v[124:127]
	v_mfma_f32_16x16x32_bf16 v[120:123], v[184:187], v[208:211], v[120:123]
	v_mfma_f32_16x16x32_bf16 v[116:119], v[176:179], v[216:219], v[116:119]
	v_mfma_f32_16x16x32_bf16 v[108:111], v[184:187], v[216:219], v[108:111]
	v_mfma_f32_16x16x32_bf16 v[100:103], v[176:179], v[224:227], v[100:103]
	v_mfma_f32_16x16x32_bf16 v[92:95], v[184:187], v[224:227], v[92:95]
	v_mfma_f32_16x16x32_bf16 v[84:87], v[176:179], v[232:235], v[84:87]
	v_mfma_f32_16x16x32_bf16 v[76:79], v[184:187], v[232:235], v[76:79]
	v_mfma_f32_16x16x32_bf16 v[124:127], v[180:183], v[212:215], v[124:127]
	v_mfma_f32_16x16x32_bf16 v[120:123], v[188:191], v[212:215], v[120:123]
	v_mfma_f32_16x16x32_bf16 v[116:119], v[180:183], v[220:223], v[116:119]
	v_mfma_f32_16x16x32_bf16 v[108:111], v[188:191], v[220:223], v[108:111]
	v_mfma_f32_16x16x32_bf16 v[100:103], v[180:183], v[228:231], v[100:103]
	v_mfma_f32_16x16x32_bf16 v[92:95], v[188:191], v[228:231], v[92:95]
	v_mfma_f32_16x16x32_bf16 v[84:87], v[180:183], v[236:239], v[84:87]
	v_mfma_f32_16x16x32_bf16 v[76:79], v[188:191], v[236:239], v[76:79]
	v_mfma_f32_16x16x32_bf16 v[112:115], v[192:195], v[208:211], v[112:115]
	v_mfma_f32_16x16x32_bf16 v[104:107], v[200:203], v[208:211], v[104:107]
	v_mfma_f32_16x16x32_bf16 v[96:99], v[192:195], v[216:219], v[96:99]
	v_mfma_f32_16x16x32_bf16 v[88:91], v[200:203], v[216:219], v[88:91]
	v_mfma_f32_16x16x32_bf16 v[80:83], v[192:195], v[224:227], v[80:83]
	v_mfma_f32_16x16x32_bf16 v[72:75], v[200:203], v[224:227], v[72:75]
	v_mfma_f32_16x16x32_bf16 v[68:71], v[192:195], v[232:235], v[68:71]
	v_mfma_f32_16x16x32_bf16 v[64:67], v[200:203], v[232:235], v[64:67]
	v_mfma_f32_16x16x32_bf16 v[112:115], v[196:199], v[212:215], v[112:115]
	v_mfma_f32_16x16x32_bf16 v[104:107], v[204:207], v[212:215], v[104:107]
	v_mfma_f32_16x16x32_bf16 v[96:99], v[196:199], v[220:223], v[96:99]
	v_mfma_f32_16x16x32_bf16 v[88:91], v[204:207], v[220:223], v[88:91]
	v_mfma_f32_16x16x32_bf16 v[80:83], v[196:199], v[228:231], v[80:83]
	v_mfma_f32_16x16x32_bf16 v[72:75], v[204:207], v[228:231], v[72:75]
	v_mfma_f32_16x16x32_bf16 v[68:71], v[196:199], v[236:239], v[68:71]
	v_mfma_f32_16x16x32_bf16 v[64:67], v[204:207], v[236:239], v[64:67]
	s_barrier
; #define PG8_STAGE(bufoff, gbase, voff) do { _Pragma("unroll") for (int _i = 0; _i < 2; ++_i) \
;         __builtin_amdgcn_global_load_lds((const unsigned*)((const char*)(gbase) + (voff)[_i]), (PG8_LAS unsigned*)(lds + (bufoff) + ldsw + _i * 8192), 16, 0, 0); } while (0)
; #define PG8_LDA(dst, b, h) do { _Pragma("unroll") for (int m = 0; m < 4; ++m) _Pragma("unroll") for (int k = 0; k < 2; ++k) dst[m][k] = *(const PG8_LAS bf16x8*)(lds + PG8_SA(b, h) + aoff + m * 2048 + k * 1024); } while (0)
; #define PG8_MMA(ai, bj, At, Bt) do { __builtin_amdgcn_s_setprio(1); _Pragma("unroll") for (int m = 0; m < 4; ++m) _Pragma("unroll") for (int n = 0; n < 2; ++n) _Pragma("unroll") for (int k = 0; k < 2; ++k) \
;         acc[ai][bj][m][n] = __builtin_amdgcn_mfma_f32_16x16x32_bf16(Bt[n][k], At[m][k], acc[ai][bj][m][n], 0, 0, 0); __builtin_amdgcn_s_setprio(0); } while (0)
; #define PG8_WAIT_V(n) asm volatile("s_waitcnt vmcnt(" #n ")" ::: "memory")
; #define PG8_WAIT_L(n) asm volatile("s_waitcnt lgkmcnt(" #n ")" ::: "memory")
; #define PG8_BAR __builtin_amdgcn_s_barrier()
; #define PG8_SCHED __builtin_amdgcn_sched_barrier(0)
; template <class Epi, class Sched, bool ALIGN_EPI = false, bool SP2 = false>
; __device__ __forceinline__ void gemm_phase(PG8_LAS unsigned char* lds, const Gemm g, const Sched& S, const Epi& E, int tid_in) {
;     ...
;         for (int t = 0; t < nt; t += 2) {
;             const bool last = (t == nt - 2);
;     ...
;             PG8_LDA(At, 1, 1); PG8_STAGE(PG8_SB(1, 0), b3, voffB); PG8_STAGE(PG8_SB(1, 1), b3 + hstep, voffB); PG8_STAGE(PG8_SA(1, 0), a3, voffA);
;             PG8_WAIT_V(8); PG8_WAIT_L(0); PG8_BAR; PG8_MMA(1, 0, At, B0); PG8_MMA(1, 1, At, B1); PG8_BAR; PG8_SCHED;
	s_setprio 1
	s_add_i32 s13, s13, s0
	v_lshl_add_u64 v[240:241], v[244:245], 0, s[70:71]
	s_mov_b32 m0, s13
	ds_read_b128 v[208:211], v175 offset:49152
	ds_read_b128 v[212:215], v175 offset:50176
	ds_read_b128 v[216:219], v175 offset:51200
	ds_read_b128 v[220:223], v175 offset:52224
	ds_read_b128 v[224:227], v175 offset:53248
	ds_read_b128 v[228:231], v175 offset:54272
	ds_read_b128 v[232:235], v175 offset:55296
	ds_read_b128 v[236:239], v175 offset:56320
	global_load_lds_dwordx4 v[240:241], off
	v_lshl_add_u64 v[240:241], v[246:247], 0, s[70:71]
	s_add_i32 m0, s13, 0x2000
	s_add_i32 s13, s14, s0
	global_load_lds_dwordx4 v[240:241], off
	v_lshl_add_u64 v[240:241], v[242:243], 0, s[86:87]
	v_lshl_add_u64 v[242:243], v[240:241], 0, v[128:129]
	s_mov_b32 m0, s13
	v_lshl_add_u64 v[240:241], v[240:241], 0, v[144:145]
	global_load_lds_dwordx4 v[242:243], off
	s_add_i32 m0, s13, 0x2000
	s_nop 0
	global_load_lds_dwordx4 v[240:241], off
	v_lshl_add_u64 v[240:241], v[248:249], 0, s[70:71]
	s_mov_b32 m0, s22
	s_nop 0
	global_load_lds_dwordx4 v[240:241], off
	v_lshl_add_u64 v[240:241], v[250:251], 0, s[70:71]
	s_mov_b32 m0, s23
	s_nop 0
	global_load_lds_dwordx4 v[240:241], off
	s_setprio 0
	s_waitcnt vmcnt(8) lgkmcnt(0)
	s_barrier
	v_mfma_f32_16x16x32_bf16 v[60:63], v[176:179], v[208:211], v[60:63]
	v_mfma_f32_16x16x32_bf16 v[56:59], v[184:187], v[208:211], v[56:59]
	v_mfma_f32_16x16x32_bf16 v[52:55], v[176:179], v[216:219], v[52:55]
	v_mfma_f32_16x16x32_bf16 v[44:47], v[184:187], v[216:219], v[44:47]
	v_mfma_f32_16x16x32_bf16 v[36:39], v[176:179], v[224:227], v[36:39]
	v_mfma_f32_16x16x32_bf16 v[28:31], v[184:187], v[224:227], v[28:31]
	v_mfma_f32_16x16x32_bf16 v[20:23], v[176:179], v[232:235], v[20:23]
	v_mfma_f32_16x16x32_bf16 v[12:15], v[184:187], v[232:235], v[12:15]
	v_mfma_f32_16x16x32_bf16 v[60:63], v[180:183], v[212:215], v[60:63]
	v_mfma_f32_16x16x32_bf16 v[56:59], v[188:191], v[212:215], v[56:59]
	v_mfma_f32_16x16x32_bf16 v[52:55], v[180:183], v[220:223], v[52:55]
	v_mfma_f32_16x16x32_bf16 v[44:47], v[188:191], v[220:223], v[44:47]
	v_mfma_f32_16x16x32_bf16 v[36:39], v[180:183], v[228:231], v[36:39]
	v_mfma_f32_16x16x32_bf16 v[28:31], v[188:191], v[228:231], v[28:31]
	v_mfma_f32_16x16x32_bf16 v[20:23], v[180:183], v[236:239], v[20:23]
	v_mfma_f32_16x16x32_bf16 v[12:15], v[188:191], v[236:239], v[12:15]
	v_mfma_f32_16x16x32_bf16 v[48:51], v[192:195], v[208:211], v[48:51]
	v_mfma_f32_16x16x32_bf16 v[40:43], v[200:203], v[208:211], v[40:43]
	v_mfma_f32_16x16x32_bf16 v[32:35], v[192:195], v[216:219], v[32:35]
	v_mfma_f32_16x16x32_bf16 v[24:27], v[200:203], v[216:219], v[24:27]
	v_mfma_f32_16x16x32_bf16 v[16:19], v[192:195], v[224:227], v[16:19]
	v_mfma_f32_16x16x32_bf16 v[8:11], v[200:203], v[224:227], v[8:11]
	v_mfma_f32_16x16x32_bf16 v[4:7], v[192:195], v[232:235], v[4:7]
	v_mfma_f32_16x16x32_bf16 v[0:3], v[200:203], v[232:235], v[0:3]
	v_mfma_f32_16x16x32_bf16 v[48:51], v[196:199], v[212:215], v[48:51]
	v_mfma_f32_16x16x32_bf16 v[40:43], v[204:207], v[212:215], v[40:43]
	v_mfma_f32_16x16x32_bf16 v[32:35], v[196:199], v[220:223], v[32:35]
	v_mfma_f32_16x16x32_bf16 v[24:27], v[204:207], v[220:223], v[24:27]
	v_mfma_f32_16x16x32_bf16 v[16:19], v[196:199], v[228:231], v[16:19]
	v_mfma_f32_16x16x32_bf16 v[8:11], v[204:207], v[228:231], v[8:11]
	v_mfma_f32_16x16x32_bf16 v[4:7], v[196:199], v[236:239], v[4:7]
	v_mfma_f32_16x16x32_bf16 v[0:3], v[204:207], v[236:239], v[0:3]
	s_barrier
	s_setprio 1
	s_add_i32 s11, s11, 2
	v_lshl_add_u64 v[164:165], v[164:165], 0, s[82:83]
	s_cmp_gt_u32 s11, 29
	v_lshl_add_u64 v[166:167], v[166:167], 0, s[82:83]
	s_cbranch_scc0 .LBB0_110
	s_setprio 0
	s_and_b64 vcc, exec, s[8:9]
	s_cbranch_vccz .LBB0_113
	s_barrier

; __device__ __forceinline__ void attn_phase(LAS unsigned char* lds, bf16_t* Z, bf16_t* OB12, float* LSE, int it0, int sA, int sB, int nit, int tid) {
;     ...
; #pragma unroll
;             for (int qt = 0; qt < 2; ++qt) { const int i = 32 * c + 16 * qt + l15; const size_t tok = (size_t)b * SEQ + (size_t)((n * 128 + i) * d + e);
;                 const float inv = 1.0f / lrow[qt];
;                 bf16_t* op = (br == 0 ? Z + tok * ZP + NIN : OB12 + (size_t)b * SEQ * D + (size_t)(br - 1) * SEQ * QD + (tok - (size_t)b * SEQ) * QD) + head * 128 + 4 * quad;
; #pragma unroll
;                 for (int ht = 0; ht < 8; ++ht) { const f32x4 o = oacc[ht][qt] * inv; *(u32x2*)(op + 16 * ht) = (u32x2){pk2(o.x, o.y), pk2(o.z, o.w)}; }
;                 if (quad == 0) LSE[((size_t)br * T + tok) * 8 + head] = mrow[qt] * 0.6931471805599453f + __logf(lrow[qt]); }
.LBB0_231:
	s_waitcnt lgkmcnt(1)
	v_add_f32_e32 v67, v67, v68
	v_div_scale_f32 v70, s[2:3], v67, v67, 1.0
	v_rcp_f32_e32 v71, v70
	v_mad_u64_u32 v[68:69], s[2:3], v126, s91, 0
	v_mad_i32_i24 v69, v127, s91, v69
	v_fma_f32 v73, -v70, v71, 1.0
	v_fmac_f32_e32 v71, v73, v71
	v_div_scale_f32 v73, vcc, 1.0, v67, 1.0
	v_mul_f32_e32 v74, v73, v71
	v_fma_f32 v75, -v70, v74, v73
	v_fmac_f32_e32 v74, v75, v71
	v_fma_f32 v70, -v70, v74, v73
	v_div_fmas_f32 v70, v70, v71, v74
	v_lshl_add_u64 v[68:69], v[104:105], 0, v[68:69]
	v_lshlrev_b64 v[74:75], 11, v[140:141]
	v_lshl_add_u64 v[68:69], v[68:69], 0, s[80:81]
	v_lshl_add_u64 v[74:75], v[118:119], 0, v[74:75]
	v_div_fixup_f32 v70, v70, v67, 1.0
	v_cndmask_b32_e64 v69, v75, v69, s[22:23]
	v_cndmask_b32_e64 v68, v74, v68, s[22:23]
	s_lshl_b32 s48, s4, 1
	v_lshl_add_u64 v[68:69], v[68:69], 0, s[48:49]
	v_pk_mul_f32 v[54:55], v[70:71], v[54:55] op_sel_hi:[0,1]
	v_pk_mul_f32 v[52:53], v[70:71], v[52:53] op_sel_hi:[0,1]
	v_lshl_add_u64 v[68:69], v[68:69], 0, v[128:129]
	v_cvt_pk_bf16_f32 v52, v52, v53
	v_cvt_pk_bf16_f32 v53, v54, v55
	flat_store_dwordx2 v[68:69], v[52:53]
	v_pk_mul_f32 v[52:53], v[70:71], v[62:63] op_sel_hi:[0,1]
	v_pk_mul_f32 v[54:55], v[70:71], v[60:61] op_sel_hi:[0,1]
	v_cvt_pk_bf16_f32 v54, v54, v55
	v_cvt_pk_bf16_f32 v55, v52, v53
	flat_store_dwordx2 v[68:69], v[54:55] offset:32
	v_pk_mul_f32 v[52:53], v[70:71], v[58:59] op_sel_hi:[0,1]
	v_pk_mul_f32 v[54:55], v[70:71], v[56:57] op_sel_hi:[0,1]
	v_pk_mul_f32 v[50:51], v[70:71], v[50:51] op_sel_hi:[0,1]
	v_pk_mul_f32 v[48:49], v[70:71], v[48:49] op_sel_hi:[0,1]
	v_pk_mul_f32 v[46:47], v[70:71], v[46:47] op_sel_hi:[0,1]
	v_pk_mul_f32 v[44:45], v[70:71], v[44:45] op_sel_hi:[0,1]
	v_pk_mul_f32 v[42:43], v[70:71], v[42:43] op_sel_hi:[0,1]
	v_pk_mul_f32 v[40:41], v[70:71], v[40:41] op_sel_hi:[0,1]
	v_pk_mul_f32 v[38:39], v[70:71], v[38:39] op_sel_hi:[0,1]
	v_pk_mul_f32 v[36:37], v[70:71], v[36:37] op_sel_hi:[0,1]
	v_pk_mul_f32 v[34:35], v[70:71], v[34:35] op_sel_hi:[0,1]
	v_pk_mul_f32 v[32:33], v[70:71], v[32:33] op_sel_hi:[0,1]
	v_cvt_pk_bf16_f32 v54, v54, v55
	v_cvt_pk_bf16_f32 v55, v52, v53
	v_cvt_pk_bf16_f32 v48, v48, v49
	v_cvt_pk_bf16_f32 v49, v50, v51
	v_cvt_pk_bf16_f32 v44, v44, v45
	v_cvt_pk_bf16_f32 v45, v46, v47
	v_cvt_pk_bf16_f32 v40, v40, v41
	v_cvt_pk_bf16_f32 v41, v42, v43
	v_cvt_pk_bf16_f32 v36, v36, v37
	v_cvt_pk_bf16_f32 v37, v38, v39
	v_cvt_pk_bf16_f32 v32, v32, v33
	v_cvt_pk_bf16_f32 v33, v34, v35
	flat_store_dwordx2 v[68:69], v[54:55] offset:64
	flat_store_dwordx2 v[68:69], v[48:49] offset:96
	flat_store_dwordx2 v[68:69], v[44:45] offset:128
	flat_store_dwordx2 v[68:69], v[40:41] offset:160
	flat_store_dwordx2 v[68:69], v[36:37] offset:192
	flat_store_dwordx2 v[68:69], v[32:33] offset:224
	s_and_saveexec_b64 s[2:3], s[6:7]
	s_cbranch_execz .LBB0_233
	v_cmp_gt_f32_e32 vcc, s92, v67
	s_nop 1
	v_cndmask_b32_e64 v32, 0, 32, vcc
	v_ldexp_f32 v32, v67, v32
	v_log_f32_e32 v34, v32
	v_lshlrev_b64 v[32:33], 5, v[126:127]
	v_lshl_add_u64 v[32:33], v[120:121], 0, v[32:33]
	v_mul_f32_e32 v35, 0x3f317217, v34
	v_fma_f32 v35, v34, s93, -v35
	v_fmac_f32_e32 v35, 0x3377d1cf, v34
	v_fmac_f32_e32 v35, 0x3f317217, v34
	v_cmp_lt_f32_e64 s[24:25], |v34|, s33
	s_nop 1
	v_cndmask_b32_e64 v34, v34, v35, s[24:25]
	v_mov_b32_e32 v173, 0x41b17218
	v_cndmask_b32_e32 v35, 0, v173, vcc
	v_sub_f32_e32 v34, v34, v35
	v_fmac_f32_e32 v34, 0x3f317218, v72
	flat_store_dword v[32:33], v34
.LBB0_233:
	s_or_b64 exec, exec, s[2:3]
	s_waitcnt lgkmcnt(0)
	v_add_f32_e32 v32, v65, v66
	v_div_scale_f32 v33, s[2:3], v32, v32, 1.0
	v_rcp_f32_e32 v36, v33
	v_mad_u64_u32 v[34:35], s[2:3], v122, s91, 0
	v_mad_i32_i24 v35, v123, s91, v35
	v_fma_f32 v37, -v33, v36, 1.0
	v_fmac_f32_e32 v36, v37, v36
	v_div_scale_f32 v37, vcc, 1.0, v32, 1.0
	v_mul_f32_e32 v38, v37, v36
	v_fma_f32 v39, -v33, v38, v37
	v_fmac_f32_e32 v38, v39, v36
	v_fma_f32 v33, -v33, v38, v37
	v_div_fmas_f32 v33, v33, v36, v38
	v_lshl_add_u64 v[34:35], v[104:105], 0, v[34:35]
	v_lshlrev_b64 v[38:39], 11, v[124:125]
	v_lshl_add_u64 v[34:35], v[34:35], 0, s[80:81]
	v_lshl_add_u64 v[38:39], v[118:119], 0, v[38:39]
	v_div_fixup_f32 v36, v33, v32, 1.0
	v_cndmask_b32_e64 v35, v39, v35, s[22:23]
	v_cndmask_b32_e64 v34, v38, v34, s[22:23]
	v_lshl_add_u64 v[34:35], v[34:35], 0, s[48:49]
	v_pk_mul_f32 v[30:31], v[36:37], v[30:31] op_sel_hi:[0,1]
	v_pk_mul_f32 v[28:29], v[36:37], v[28:29] op_sel_hi:[0,1]
	v_pk_mul_f32 v[26:27], v[36:37], v[26:27] op_sel_hi:[0,1]
	v_pk_mul_f32 v[24:25], v[36:37], v[24:25] op_sel_hi:[0,1]
	v_pk_mul_f32 v[22:23], v[36:37], v[22:23] op_sel_hi:[0,1]
	v_pk_mul_f32 v[20:21], v[36:37], v[20:21] op_sel_hi:[0,1]
	v_pk_mul_f32 v[18:19], v[36:37], v[18:19] op_sel_hi:[0,1]
	v_pk_mul_f32 v[16:17], v[36:37], v[16:17] op_sel_hi:[0,1]
	v_pk_mul_f32 v[14:15], v[36:37], v[14:15] op_sel_hi:[0,1]
	v_pk_mul_f32 v[12:13], v[36:37], v[12:13] op_sel_hi:[0,1]
	v_pk_mul_f32 v[10:11], v[36:37], v[10:11] op_sel_hi:[0,1]
	v_pk_mul_f32 v[8:9], v[36:37], v[8:9] op_sel_hi:[0,1]
	v_pk_mul_f32 v[6:7], v[36:37], v[6:7] op_sel_hi:[0,1]
	v_pk_mul_f32 v[4:5], v[36:37], v[4:5] op_sel_hi:[0,1]
	v_pk_mul_f32 v[2:3], v[36:37], v[2:3] op_sel_hi:[0,1]
	v_pk_mul_f32 v[0:1], v[36:37], v[0:1] op_sel_hi:[0,1]
	v_lshl_add_u64 v[34:35], v[34:35], 0, v[128:129]
	v_cvt_pk_bf16_f32 v28, v28, v29
	v_cvt_pk_bf16_f32 v29, v30, v31
	v_cvt_pk_bf16_f32 v24, v24, v25
	v_cvt_pk_bf16_f32 v25, v26, v27
	v_cvt_pk_bf16_f32 v20, v20, v21
	v_cvt_pk_bf16_f32 v21, v22, v23
	v_cvt_pk_bf16_f32 v16, v16, v17
	v_cvt_pk_bf16_f32 v17, v18, v19
	v_cvt_pk_bf16_f32 v12, v12, v13
	v_cvt_pk_bf16_f32 v13, v14, v15
	v_cvt_pk_bf16_f32 v8, v8, v9
	v_cvt_pk_bf16_f32 v9, v10, v11
	v_cvt_pk_bf16_f32 v4, v4, v5
	v_cvt_pk_bf16_f32 v5, v6, v7
	v_cvt_pk_bf16_f32 v0, v0, v1
	v_cvt_pk_bf16_f32 v1, v2, v3
	flat_store_dwordx2 v[34:35], v[28:29]
	flat_store_dwordx2 v[34:35], v[24:25] offset:32
	flat_store_dwordx2 v[34:35], v[20:21] offset:64
	flat_store_dwordx2 v[34:35], v[16:17] offset:96
	flat_store_dwordx2 v[34:35], v[12:13] offset:128
	flat_store_dwordx2 v[34:35], v[8:9] offset:160
	flat_store_dwordx2 v[34:35], v[4:5] offset:192
	flat_store_dwordx2 v[34:35], v[0:1] offset:224
	s_and_saveexec_b64 s[2:3], s[6:7]
	s_cbranch_execz .LBB0_202
	v_cmp_gt_f32_e32 vcc, s92, v32
	s_nop 1
	v_cndmask_b32_e64 v0, 0, 32, vcc
	v_ldexp_f32 v0, v32, v0
	v_log_f32_e32 v2, v0
	v_lshlrev_b64 v[0:1], 5, v[122:123]
	v_lshl_add_u64 v[0:1], v[120:121], 0, v[0:1]
	v_mul_f32_e32 v3, 0x3f317217, v2
	v_fma_f32 v3, v2, s93, -v3
	v_fmac_f32_e32 v3, 0x3377d1cf, v2
	v_fmac_f32_e32 v3, 0x3f317217, v2
	v_cmp_lt_f32_e64 s[24:25], |v2|, s33
	s_nop 1
	v_cndmask_b32_e64 v2, v2, v3, s[24:25]
	v_mov_b32_e32 v173, 0x41b17218
	v_cndmask_b32_e32 v3, 0, v173, vcc
	v_sub_f32_e32 v2, v2, v3
	v_fmac_f32_e32 v2, 0x3f317218, v64
	flat_store_dword v[0:1], v2
	s_branch .LBB0_202

; __device__ __forceinline__ float bflo(unsigned w) { return __uint_as_float(w << 16); }
; __device__ __forceinline__ void combine_phase(const bf16_t* Z, const bf16_t* OB12, const float* LSE, const float* convw, const float* ga, const float* gc, bf16_t* XN, int boff, int row0, int rstride, int nrows, int lane) {
;     ...
;         for (int j = 0; j < 2; ++j) { const int chunk = lane + 64 * j, col = chunk * 8, head = chunk >> 4;
;             const float l0 = LSE[((size_t)0 * T + t) * 8 + head], l1 = LSE[((size_t)1 * T + t) * 8 + head], l2 = LSE[((size_t)2 * T + t) * 8 + head];
;             const float mx = fmaxf(l0, fmaxf(l1, l2)); float w0 = __expf(l0 - mx), w1 = __expf(l1 - mx), w2 = __expf(l2 - mx); const float inv = 1.0f / (w0 + w1 + w2); w0 *= inv; w1 *= inv; w2 *= inv;
;             const u32x4 o0 = *(const u32x4*)(Z + (size_t)t * ZP + NIN + col), o1 = *(const u32x4*)(OB12 + (size_t)(t >> 11) * SEQ * D + (size_t)s * QD + col), o2 = *(const u32x4*)(OB12 + (size_t)(t >> 11) * SEQ * D + (size_t)SEQ * QD + (size_t)s * QD + col);
; #pragma unroll
;             for (int w = 0; w < 4; ++w) { const float a0 = w0 * bflo(o0[w]) + w1 * bflo(o1[w]) + w2 * bflo(o2[w]), a1 = w0 * bfhi(o0[w]) + w1 * bfhi(o1[w]) + w2 * bfhi(o2[w]);
;                 av[j][2 * w] = a0; av[j][2 * w + 1] = a1; ssa += a0 * a0 + a1 * a1; } }
; #pragma unroll
;         for (int j = 0; j < 2; ++j) { const int ch = (lane + 64 * j) * 8; const bf16_t* zr = Z + (size_t)t * ZP;
;             const u32x4 hc0 = *(const u32x4*)(zr + 1536 + ch), bg0 = *(const u32x4*)(zr + 2560 + ch), cg0 = *(const u32x4*)(zr + 3584 + ch);
;             u32x4 hc1 = (u32x4){0u, 0u, 0u, 0u}, cg1 = hc1, hc2 = hc1, cg2 = hc1;
;             if (s >= 1) { hc1 = *(const u32x4*)(zr - ZP + 1536 + ch); cg1 = *(const u32x4*)(zr - ZP + 3584 + ch); }
;             if (s >= 2) { hc2 = *(const u32x4*)(zr - 2 * ZP + 1536 + ch); cg2 = *(const u32x4*)(zr - 2 * ZP + 3584 + ch); }
;             float wk[3][8];
; #pragma unroll
;             for (int k = 0; k < 3; ++k) { const f32x4 a = *(const f32x4*)(convw + k * QD + ch), b2 = *(const f32x4*)(convw + k * QD + ch + 4);
;                 wk[k][0] = a.x; wk[k][1] = a.y; wk[k][2] = a.z; wk[k][3] = a.w; wk[k][4] = b2.x; wk[k][5] = b2.y; wk[k][6] = b2.z; wk[k][7] = b2.w; }
; #pragma unroll
;             for (int w = 0; w < 4; ++w) {
.LBB0_311:
	s_waitcnt vmcnt(0) lgkmcnt(0)
	v_lshlrev_b32_e32 v152, 16, v60
	v_and_b32_e32 v153, 0xffff0000, v60
	v_lshlrev_b32_e32 v166, 16, v56
	v_and_b32_e32 v167, 0xffff0000, v56
	v_pk_mul_f32 v[152:153], v[166:167], v[152:153]
	v_lshlrev_b32_e32 v166, 16, v64
	v_pk_mul_f32 v[100:101], v[152:153], v[100:101]
	v_lshlrev_b32_e32 v152, 16, v68
	v_and_b32_e32 v153, 0xffff0000, v68
	v_and_b32_e32 v167, 0xffff0000, v64
	v_pk_mul_f32 v[152:153], v[152:153], v[166:167]
	v_lshlrev_b32_e32 v60, 16, v61
	v_pk_fma_f32 v[96:97], v[152:153], v[96:97], v[100:101]
	v_lshlrev_b32_e32 v100, 16, v76
	v_and_b32_e32 v101, 0xffff0000, v76
	v_lshlrev_b32_e32 v152, 16, v72
	v_and_b32_e32 v153, 0xffff0000, v72
	v_and_b32_e32 v61, 0xffff0000, v61
	v_lshlrev_b32_e32 v56, 16, v57
	v_and_b32_e32 v57, 0xffff0000, v57
	v_pk_mul_f32 v[100:101], v[100:101], v[152:153]
	v_pk_mul_f32 v[56:57], v[56:57], v[60:61]
	v_lshlrev_b32_e32 v60, 16, v69
	v_and_b32_e32 v61, 0xffff0000, v69
	v_lshlrev_b32_e32 v64, 16, v65
	v_and_b32_e32 v65, 0xffff0000, v65
	v_pk_fma_f32 v[92:93], v[92:93], v[100:101], v[96:97]
	v_lshlrev_b32_e32 v96, 16, v52
	v_and_b32_e32 v97, 0xffff0000, v52
	v_pk_mul_f32 v[56:57], v[56:57], v[102:103]
	v_pk_mul_f32 v[60:61], v[60:61], v[64:65]
	v_pk_mul_f32 v[92:93], v[92:93], v[96:97]
	v_pk_fma_f32 v[56:57], v[60:61], v[98:99], v[56:57]
	v_lshlrev_b32_e32 v60, 16, v77
	v_and_b32_e32 v61, 0xffff0000, v77
	v_lshlrev_b32_e32 v64, 16, v73
	v_and_b32_e32 v65, 0xffff0000, v73
	v_mul_f32_e32 v52, v93, v93
	v_pk_mul_f32 v[60:61], v[60:61], v[64:65]
	v_pk_fma_f32 v[96:97], v[92:93], v[92:93], v[52:53] op_sel_hi:[1,1,0]
	v_pk_fma_f32 v[56:57], v[94:95], v[60:61], v[56:57]
	v_lshlrev_b32_e32 v52, 16, v53
	v_and_b32_e32 v53, 0xffff0000, v53
	v_pk_mul_f32 v[52:53], v[56:57], v[52:53]
	v_lshlrev_b32_e32 v64, 16, v58
	v_mul_f32_e32 v56, v53, v53
	v_pk_fma_f32 v[60:61], v[52:53], v[52:53], v[56:57] op_sel_hi:[1,1,0]
	v_lshlrev_b32_e32 v56, 16, v62
	v_and_b32_e32 v57, 0xffff0000, v62
	v_and_b32_e32 v65, 0xffff0000, v58
	v_pk_mul_f32 v[56:57], v[64:65], v[56:57]
	v_lshlrev_b32_e32 v64, 16, v70
	v_and_b32_e32 v65, 0xffff0000, v70
	v_lshlrev_b32_e32 v68, 16, v66
	v_and_b32_e32 v69, 0xffff0000, v66
	v_pk_mul_f32 v[56:57], v[56:57], v[88:89]
	v_pk_mul_f32 v[64:65], v[64:65], v[68:69]
	v_lshlrev_b32_e32 v68, 16, v74
	v_pk_fma_f32 v[56:57], v[64:65], v[84:85], v[56:57]
	v_lshlrev_b32_e32 v64, 16, v78
	v_and_b32_e32 v65, 0xffff0000, v78
	v_and_b32_e32 v69, 0xffff0000, v74
	v_pk_mul_f32 v[64:65], v[64:65], v[68:69]
	v_lshlrev_b32_e32 v62, 16, v63
	v_pk_fma_f32 v[56:57], v[80:81], v[64:65], v[56:57]
	v_lshlrev_b32_e32 v64, 16, v54
	v_and_b32_e32 v65, 0xffff0000, v54
	v_max3_f32 v54, v164, v163, v162
	v_sub_f32_e32 v61, v164, v54
	v_mul_f32_e32 v61, 0x3fb8aa3b, v61
	v_exp_f32_e32 v69, v61
	v_sub_f32_e32 v61, v163, v54
	v_mul_f32_e32 v61, 0x3fb8aa3b, v61
	v_sub_f32_e32 v54, v162, v54
	v_and_b32_e32 v63, 0xffff0000, v63
	v_lshlrev_b32_e32 v58, 16, v59
	v_and_b32_e32 v59, 0xffff0000, v59
	v_exp_f32_e32 v68, v61
	v_mul_f32_e32 v54, 0x3fb8aa3b, v54
	v_pk_mul_f32 v[58:59], v[58:59], v[62:63]
	v_lshlrev_b32_e32 v62, 16, v71
	v_and_b32_e32 v63, 0xffff0000, v71
	v_lshlrev_b32_e32 v66, 16, v67
	v_and_b32_e32 v67, 0xffff0000, v67
	v_exp_f32_e32 v61, v54
	v_pk_mul_f32 v[58:59], v[58:59], v[90:91]
	v_pk_mul_f32 v[62:63], v[62:63], v[66:67]
	v_lshlrev_b32_e32 v66, 16, v75
	v_pk_fma_f32 v[58:59], v[62:63], v[86:87], v[58:59]
	v_lshlrev_b32_e32 v62, 16, v79
	v_and_b32_e32 v63, 0xffff0000, v79
	v_and_b32_e32 v67, 0xffff0000, v75
	v_pk_mul_f32 v[62:63], v[62:63], v[66:67]
	v_add_f32_e32 v54, v69, v68
	v_pk_fma_f32 v[58:59], v[82:83], v[62:63], v[58:59]
	v_add_f32_e32 v62, v61, v54
	v_div_scale_f32 v63, s[2:3], v62, v62, 1.0
	v_rcp_f32_e32 v66, v63
	v_lshlrev_b32_e32 v54, 16, v55
	v_and_b32_e32 v55, 0xffff0000, v55
	v_pk_mul_f32 v[54:55], v[58:59], v[54:55]
	v_fma_f32 v58, -v63, v66, 1.0
	v_fmac_f32_e32 v66, v58, v66
	v_div_scale_f32 v58, vcc, 1.0, v62, 1.0
	v_mul_f32_e32 v59, v58, v66
	v_fma_f32 v67, -v63, v59, v58
	v_fmac_f32_e32 v59, v67, v66
	v_fma_f32 v58, -v63, v59, v58
	v_div_fmas_f32 v58, v58, v66, v59
	v_div_fixup_f32 v58, v58, v62, 1.0
	v_pk_mul_f32 v[68:69], v[68:69], v[58:59] op_sel_hi:[1,0]
	v_lshlrev_b32_e32 v62, 16, v44
	v_and_b32_e32 v63, 0xffff0000, v48
	v_mul_f32_e32 v70, v61, v58
	v_lshlrev_b32_e32 v58, 16, v48
	v_and_b32_e32 v59, 0xffff0000, v44
	v_pk_mul_f32 v[62:63], v[68:69], v[62:63] op_sel:[1,0] op_sel_hi:[0,1]
	v_lshlrev_b32_e32 v66, 16, v32
	v_and_b32_e32 v67, 0xffff0000, v32
	v_pk_fma_f32 v[58:59], v[68:69], v[58:59], v[62:63]
	v_lshlrev_b32_e32 v44, 16, v45
	v_pk_fma_f32 v[58:59], v[70:71], v[66:67], v[58:59] op_sel_hi:[0,1,1]
	v_and_b32_e32 v67, 0xffff0000, v45
	v_and_b32_e32 v45, 0xffff0000, v49
	v_mul_f32_e32 v32, v59, v59
	v_lshlrev_b32_e32 v66, 16, v49
	v_pk_mul_f32 v[44:45], v[68:69], v[44:45] op_sel:[1,0] op_sel_hi:[0,1]
	v_pk_fma_f32 v[62:63], v[58:59], v[58:59], v[32:33] op_sel_hi:[1,1,0]
	v_lshlrev_b32_e32 v32, 16, v33
	v_and_b32_e32 v33, 0xffff0000, v33
	v_pk_fma_f32 v[44:45], v[68:69], v[66:67], v[44:45]
	flat_load_dwordx4 v[74:77], v[140:141]
	flat_load_dwordx4 v[78:81], v[142:143]
	v_pk_fma_f32 v[32:33], v[70:71], v[32:33], v[44:45] op_sel_hi:[0,1,1]
	v_mul_f32_e32 v44, v33, v33
	v_lshlrev_b32_e32 v66, 16, v46
	v_and_b32_e32 v67, 0xffff0000, v50
	v_max3_f32 v61, v161, v160, v159
	v_pk_fma_f32 v[48:49], v[32:33], v[32:33], v[44:45] op_sel_hi:[1,1,0]
	v_lshlrev_b32_e32 v44, 16, v50
	v_and_b32_e32 v45, 0xffff0000, v46
	v_pk_mul_f32 v[66:67], v[68:69], v[66:67] op_sel:[1,0] op_sel_hi:[0,1]
	v_sub_f32_e32 v50, v161, v61
	flat_load_dwordx4 v[82:85], v[124:125]
; __device__ __forceinline__ float bflo(unsigned w) { return __uint_as_float(w << 16); }
; __device__ __forceinline__ void combine_phase(const bf16_t* Z, const bf16_t* OB12, const float* LSE, const float* convw, const float* ga, const float* gc, bf16_t* XN, int boff, int row0, int rstride, int nrows, int lane) {
;     ...
;         for (int j = 0; j < 2; ++j) { const int chunk = lane + 64 * j, col = chunk * 8, head = chunk >> 4;
;             const float l0 = LSE[((size_t)0 * T + t) * 8 + head], l1 = LSE[((size_t)1 * T + t) * 8 + head], l2 = LSE[((size_t)2 * T + t) * 8 + head];
;             const float mx = fmaxf(l0, fmaxf(l1, l2)); float w0 = __expf(l0 - mx), w1 = __expf(l1 - mx), w2 = __expf(l2 - mx); const float inv = 1.0f / (w0 + w1 + w2); w0 *= inv; w1 *= inv; w2 *= inv;
;             const u32x4 o0 = *(const u32x4*)(Z + (size_t)t * ZP + NIN + col), o1 = *(const u32x4*)(OB12 + (size_t)(t >> 11) * SEQ * D + (size_t)s * QD + col), o2 = *(const u32x4*)(OB12 + (size_t)(t >> 11) * SEQ * D + (size_t)SEQ * QD + (size_t)s * QD + col);
; #pragma unroll
;             for (int w = 0; w < 4; ++w) { const float a0 = w0 * bflo(o0[w]) + w1 * bflo(o1[w]) + w2 * bflo(o2[w]), a1 = w0 * bfhi(o0[w]) + w1 * bfhi(o1[w]) + w2 * bfhi(o2[w]);
;                 av[j][2 * w] = a0; av[j][2 * w + 1] = a1; ssa += a0 * a0 + a1 * a1; } }
; #pragma unroll
;         for (int j = 0; j < 2; ++j) { const int ch = (lane + 64 * j) * 8; const bf16_t* zr = Z + (size_t)t * ZP;
;             const u32x4 hc0 = *(const u32x4*)(zr + 1536 + ch), bg0 = *(const u32x4*)(zr + 2560 + ch), cg0 = *(const u32x4*)(zr + 3584 + ch);
;             u32x4 hc1 = (u32x4){0u, 0u, 0u, 0u}, cg1 = hc1, hc2 = hc1, cg2 = hc1;
;             if (s >= 1) { hc1 = *(const u32x4*)(zr - ZP + 1536 + ch); cg1 = *(const u32x4*)(zr - ZP + 3584 + ch); }
;             if (s >= 2) { hc2 = *(const u32x4*)(zr - 2 * ZP + 1536 + ch); cg2 = *(const u32x4*)(zr - 2 * ZP + 3584 + ch); }
;             float wk[3][8];
; #pragma unroll
;             for (int k = 0; k < 3; ++k) { const f32x4 a = *(const f32x4*)(convw + k * QD + ch), b2 = *(const f32x4*)(convw + k * QD + ch + 4);
;                 wk[k][0] = a.x; wk[k][1] = a.y; wk[k][2] = a.z; wk[k][3] = a.w; wk[k][4] = b2.x; wk[k][5] = b2.y; wk[k][6] = b2.z; wk[k][7] = b2.w; }
; #pragma unroll
;             for (int w = 0; w < 4; ++w) {
	flat_load_dwordx4 v[86:89], v[126:127]
	v_lshlrev_b32_e32 v72, 16, v34
	v_and_b32_e32 v73, 0xffff0000, v34
	v_pk_fma_f32 v[44:45], v[68:69], v[44:45], v[66:67]
	v_mul_f32_e32 v50, 0x3fb8aa3b, v50
	v_pk_fma_f32 v[44:45], v[70:71], v[72:73], v[44:45] op_sel_hi:[0,1,1]
	v_lshlrev_b32_e32 v72, 16, v51
	v_and_b32_e32 v73, 0xffff0000, v47
	v_lshlrev_b32_e32 v46, 16, v47
	v_and_b32_e32 v47, 0xffff0000, v51
	v_exp_f32_e32 v51, v50
	v_sub_f32_e32 v50, v160, v61
	flat_load_dwordx4 v[98:101], v[110:111] offset:2048
	flat_load_dwordx4 v[160:163], v[110:111] offset:2064
	v_mul_f32_e32 v50, 0x3fb8aa3b, v50
	v_sub_f32_e32 v61, v159, v61
	v_exp_f32_e32 v50, v50
	v_mul_f32_e32 v61, 0x3fb8aa3b, v61
	v_exp_f32_e32 v61, v61
	v_pk_mul_f32 v[46:47], v[68:69], v[46:47] op_sel:[1,0] op_sel_hi:[0,1]
	v_add_f32_e32 v63, v51, v50
	v_pk_fma_f32 v[46:47], v[68:69], v[72:73], v[46:47]
	v_add_f32_e32 v63, v61, v63
	v_div_scale_f32 v68, s[2:3], v63, v63, 1.0
	v_rcp_f32_e32 v69, v68
	v_lshlrev_b32_e32 v34, 16, v35
	v_and_b32_e32 v35, 0xffff0000, v35
	v_pk_fma_f32 v[70:71], v[70:71], v[34:35], v[46:47] op_sel_hi:[0,1,1]
	v_fma_f32 v34, -v68, v69, 1.0
	v_fmac_f32_e32 v69, v34, v69
	v_div_scale_f32 v34, vcc, 1.0, v63, 1.0
	v_mul_f32_e32 v35, v34, v69
	v_fma_f32 v46, -v68, v35, v34
	v_fmac_f32_e32 v35, v46, v69
	v_fma_f32 v34, -v68, v35, v34
	v_div_fmas_f32 v34, v34, v69, v35
	v_div_fixup_f32 v34, v34, v63, 1.0
	v_pk_mul_f32 v[72:73], v[50:51], v[34:35] op_sel_hi:[1,0]
	v_lshlrev_b32_e32 v46, 16, v8
	v_and_b32_e32 v47, 0xffff0000, v20
	v_mul_f32_e32 v68, v61, v34
	v_lshlrev_b32_e32 v34, 16, v20
	v_and_b32_e32 v35, 0xffff0000, v8
	v_pk_mul_f32 v[46:47], v[72:73], v[46:47] op_sel:[1,0] op_sel_hi:[0,1]
	v_lshlrev_b32_e32 v50, 16, v12
	v_and_b32_e32 v51, 0xffff0000, v12
	v_pk_fma_f32 v[34:35], v[72:73], v[34:35], v[46:47]
	v_and_b32_e32 v47, 0xffff0000, v9
	v_pk_fma_f32 v[34:35], v[68:69], v[50:51], v[34:35] op_sel_hi:[0,1,1]
	v_mul_f32_e32 v8, v34, v34
	v_pk_fma_f32 v[90:91], v[34:35], v[34:35], v[8:9] op_sel_hi:[1,1,0]
	v_lshlrev_b32_e32 v8, 16, v9
	v_and_b32_e32 v9, 0xffff0000, v21
	v_lshlrev_b32_e32 v46, 16, v21
	v_pk_mul_f32 v[8:9], v[72:73], v[8:9] op_sel:[1,0] op_sel_hi:[0,1]
	v_lshlrev_b32_e32 v12, 16, v13
	v_and_b32_e32 v13, 0xffff0000, v13
	v_pk_fma_f32 v[8:9], v[72:73], v[46:47], v[8:9]
	v_lshlrev_b32_e32 v20, 16, v14
	v_pk_fma_f32 v[46:47], v[68:69], v[12:13], v[8:9] op_sel_hi:[0,1,1]
	v_mul_f32_e32 v8, v46, v46
	v_lshlrev_b32_e32 v12, 16, v10
	v_and_b32_e32 v13, 0xffff0000, v22
	v_pk_fma_f32 v[94:95], v[46:47], v[46:47], v[8:9] op_sel_hi:[1,1,0]
	v_lshlrev_b32_e32 v8, 16, v22
	v_and_b32_e32 v9, 0xffff0000, v10
	v_pk_mul_f32 v[12:13], v[72:73], v[12:13] op_sel:[1,0] op_sel_hi:[0,1]
	v_and_b32_e32 v21, 0xffff0000, v14
	v_pk_fma_f32 v[8:9], v[72:73], v[8:9], v[12:13]
	v_lshlrev_b32_e32 v10, 16, v11
	v_pk_fma_f32 v[50:51], v[68:69], v[20:21], v[8:9] op_sel_hi:[0,1,1]
	v_mul_f32_e32 v8, v50, v50
	v_pk_fma_f32 v[102:103], v[50:51], v[50:51], v[8:9] op_sel_hi:[1,1,0]
	v_and_b32_e32 v9, 0xffff0000, v11
	v_and_b32_e32 v11, 0xffff0000, v23
	v_lshlrev_b32_e32 v8, 16, v23
	v_pk_mul_f32 v[10:11], v[72:73], v[10:11] op_sel:[1,0] op_sel_hi:[0,1]
	v_pk_fma_f32 v[8:9], v[72:73], v[8:9], v[10:11]
	v_lshlrev_b32_e32 v72, 16, v27
	v_and_b32_e32 v73, 0xffff0000, v27
	v_lshlrev_b32_e32 v164, 16, v19
	v_and_b32_e32 v165, 0xffff0000, v19
	v_pk_mul_f32 v[72:73], v[164:165], v[72:73]
	v_lshlrev_b32_e32 v164, 16, v31
	s_waitcnt vmcnt(0) lgkmcnt(0)
	v_pk_mul_f32 v[72:73], v[72:73], v[80:81]
	v_lshlrev_b32_e32 v80, 16, v3
	v_and_b32_e32 v81, 0xffff0000, v3
	v_and_b32_e32 v165, 0xffff0000, v31
	v_pk_mul_f32 v[80:81], v[80:81], v[164:165]
	v_and_b32_e32 v27, 0xffff0000, v18
	v_pk_fma_f32 v[72:73], v[80:81], v[88:89], v[72:73]
	v_lshlrev_b32_e32 v80, 16, v39
	v_and_b32_e32 v81, 0xffff0000, v39
	v_lshlrev_b32_e32 v88, 16, v43
	v_and_b32_e32 v89, 0xffff0000, v43
	v_pk_mul_f32 v[80:81], v[80:81], v[88:89]
	v_and_b32_e32 v3, 0xffff0000, v30
	v_pk_fma_f32 v[72:73], v[162:163], v[80:81], v[72:73]
	v_lshlrev_b32_e32 v80, 16, v7
	v_and_b32_e32 v81, 0xffff0000, v7
	v_pk_mul_f32 v[72:73], v[72:73], v[80:81]
	v_lshlrev_b32_e32 v80, 16, v26
	v_and_b32_e32 v81, 0xffff0000, v26
	v_lshlrev_b32_e32 v26, 16, v18
	v_pk_mul_f32 v[18:19], v[26:27], v[80:81]
	v_lshlrev_b32_e32 v26, 16, v2
	v_and_b32_e32 v27, 0xffff0000, v2
	v_lshlrev_b32_e32 v2, 16, v30
	v_pk_mul_f32 v[18:19], v[18:19], v[78:79]
	v_pk_mul_f32 v[2:3], v[26:27], v[2:3]
	v_lshlrev_b32_e32 v26, 16, v42
	v_pk_fma_f32 v[2:3], v[2:3], v[86:87], v[18:19]
	v_lshlrev_b32_e32 v18, 16, v38
	v_and_b32_e32 v19, 0xffff0000, v38
	v_and_b32_e32 v27, 0xffff0000, v42
	v_pk_mul_f32 v[18:19], v[18:19], v[26:27]
	v_lshlrev_b32_e32 v26, 16, v17
	v_pk_fma_f32 v[2:3], v[160:161], v[18:19], v[2:3]
	v_lshlrev_b32_e32 v18, 16, v6
	v_and_b32_e32 v19, 0xffff0000, v6
	v_pk_mul_f32 v[18:19], v[2:3], v[18:19]
	v_mov_b32_e32 v6, v73
	v_mov_b32_e32 v7, v19
	v_mov_b32_e32 v2, v72
	v_mov_b32_e32 v3, v18
	v_pk_mul_f32 v[6:7], v[6:7], v[6:7]
	v_and_b32_e32 v27, 0xffff0000, v17
	v_pk_fma_f32 v[2:3], v[2:3], v[2:3], v[6:7]
	v_lshlrev_b32_e32 v6, 16, v25
	v_and_b32_e32 v7, 0xffff0000, v25
	v_pk_mul_f32 v[6:7], v[26:27], v[6:7]
	v_lshlrev_b32_e32 v26, 16, v1
	v_and_b32_e32 v27, 0xffff0000, v1
	v_lshlrev_b32_e32 v30, 16, v29
	v_and_b32_e32 v31, 0xffff0000, v29
	v_pk_mul_f32 v[6:7], v[6:7], v[76:77]
	v_pk_mul_f32 v[26:27], v[26:27], v[30:31]
	v_lshlrev_b32_e32 v30, 16, v41
	v_pk_fma_f32 v[6:7], v[26:27], v[84:85], v[6:7]
	v_lshlrev_b32_e32 v26, 16, v37
	v_and_b32_e32 v27, 0xffff0000, v37
	v_and_b32_e32 v31, 0xffff0000, v41
	v_pk_mul_f32 v[26:27], v[26:27], v[30:31]
	v_lshlrev_b32_e32 v10, 16, v15
; __device__ __forceinline__ float bflo(unsigned w) { return __uint_as_float(w << 16); }
; __device__ __forceinline__ float bfhi(unsigned w) { return __uint_as_float(w & 0xffff0000u); }
; __device__ __forceinline__ void combine_phase(const bf16_t* Z, const bf16_t* OB12, const float* LSE, const float* convw, const float* ga, const float* gc, bf16_t* XN, int boff, int row0, int rstride, int nrows, int lane) {
;     ...
;             for (int w = 0; w < 4; ++w) {
;                 const float y0 = wk[2][2 * w] * (bflo(cg0[w]) * bflo(hc0[w])) + wk[1][2 * w] * (bflo(cg1[w]) * bflo(hc1[w])) + wk[0][2 * w] * (bflo(cg2[w]) * bflo(hc2[w]));
;                 const float y1 = wk[2][2 * w + 1] * (bfhi(cg0[w]) * bfhi(hc0[w])) + wk[1][2 * w + 1] * (bfhi(cg1[w]) * bfhi(hc1[w])) + wk[0][2 * w + 1] * (bfhi(cg2[w]) * bfhi(hc2[w]));
;                 const float c0 = bflo(bg0[w]) * y0, c1 = bfhi(bg0[w]) * y1; cv[j][2 * w] = c0; cv[j][2 * w + 1] = c1; ssc += c0 * c0 + c1 * c1; } }
;         const float ra = rsqrtf(wave_sum(ssa) * (1.f / QD) + EPS), rc = rsqrtf(wave_sum(ssc) * (1.f / QD) + EPS);
; #pragma unroll
;         for (int j = 0; j < 2; ++j) { const int col = (lane + 64 * j) * 8;
;             const f32x4 g0 = *(const f32x4*)(ga + col), g1 = *(const f32x4*)(ga + col + 4), h0 = *(const f32x4*)(gc + col), h1 = *(const f32x4*)(gc + col + 4);
;             u32x4 oa, oc;
;             oa.x = pk2(av[j][0] * ra * g0.x, av[j][1] * ra * g0.y); oa.y = pk2(av[j][2] * ra * g0.z, av[j][3] * ra * g0.w); oa.z = pk2(av[j][4] * ra * g1.x, av[j][5] * ra * g1.y); oa.w = pk2(av[j][6] * ra * g1.z, av[j][7] * ra * g1.w);
;             oc.x = pk2(cv[j][0] * rc * h0.x, cv[j][1] * rc * h0.y); oc.y = pk2(cv[j][2] * rc * h0.z, cv[j][3] * rc * h0.w); oc.z = pk2(cv[j][4] * rc * h1.x, cv[j][5] * rc * h1.y); oc.w = pk2(cv[j][6] * rc * h1.z, cv[j][7] * rc * h1.w);
;             bf16_t* xo = XN + (size_t)t * D + (size_t)(t >> 11) * boff;
;             *(u32x4*)(xo + col) = oa; *(u32x4*)(xo + QD + col) = oc; }
	v_pk_fma_f32 v[6:7], v[100:101], v[26:27], v[6:7]
	v_lshlrev_b32_e32 v26, 16, v5
	v_and_b32_e32 v27, 0xffff0000, v5
	v_and_b32_e32 v11, 0xffff0000, v15
	v_pk_mul_f32 v[26:27], v[6:7], v[26:27]
	v_lshlrev_b32_e32 v6, 16, v24
	v_and_b32_e32 v7, 0xffff0000, v24
	v_lshlrev_b32_e32 v24, 16, v16
	v_and_b32_e32 v25, 0xffff0000, v16
	v_pk_fma_f32 v[68:69], v[68:69], v[10:11], v[8:9] op_sel_hi:[0,1,1]
	v_pk_mul_f32 v[6:7], v[24:25], v[6:7]
	v_lshlrev_b32_e32 v16, 16, v0
	v_and_b32_e32 v17, 0xffff0000, v0
	v_lshlrev_b32_e32 v0, 16, v28
	v_and_b32_e32 v1, 0xffff0000, v28
	v_mul_f32_e32 v8, v68, v68
	v_pk_mul_f32 v[6:7], v[6:7], v[74:75]
	v_pk_mul_f32 v[0:1], v[16:17], v[0:1]
	v_pk_fma_f32 v[152:153], v[68:69], v[68:69], v[8:9] op_sel_hi:[1,1,0]
	flat_load_dwordx4 v[20:23], v[112:113]
	flat_load_dwordx4 v[12:15], v[112:113] offset:16
	flat_load_dwordx4 v[8:11], v[114:115]
	v_pk_fma_f32 v[0:1], v[0:1], v[82:83], v[6:7]
	v_lshlrev_b32_e32 v6, 16, v36
	v_and_b32_e32 v7, 0xffff0000, v36
	v_lshlrev_b32_e32 v16, 16, v40
	v_and_b32_e32 v17, 0xffff0000, v40
	v_pk_mul_f32 v[6:7], v[6:7], v[16:17]
	v_pk_mul_f32 v[56:57], v[56:57], v[64:65]
	v_pk_fma_f32 v[0:1], v[98:99], v[6:7], v[0:1]
	v_lshlrev_b32_e32 v6, 16, v4
	v_and_b32_e32 v7, 0xffff0000, v4
	v_pk_mul_f32 v[16:17], v[0:1], v[6:7]
	v_mov_b32_e32 v4, v27
	v_mov_b32_e32 v5, v17
	v_pk_mul_f32 v[64:65], v[56:57], v[56:57]
	v_pk_mul_f32 v[66:67], v[44:45], v[44:45]
	v_mov_b32_e32 v0, v26
	v_mov_b32_e32 v1, v16
	v_pk_mul_f32 v[4:5], v[4:5], v[4:5]
	v_mov_b32_e32 v6, v55
	v_mov_b32_e32 v7, v71
	v_pk_fma_f32 v[0:1], v[0:1], v[0:1], v[4:5]
	v_mov_b32_e32 v4, v54
	v_mov_b32_e32 v5, v70
	v_pk_mul_f32 v[6:7], v[6:7], v[6:7]
	v_mov_b32_e32 v97, v66
	v_mov_b32_e32 v61, v67
	v_mov_b32_e32 v24, v64
	v_mov_b32_e32 v25, v62
	v_pk_mov_b32 v[28:29], v[64:65], v[48:49] op_sel:[1,0]
	v_pk_fma_f32 v[4:5], v[4:5], v[4:5], v[6:7]
	v_pk_add_f32 v[6:7], v[96:97], v[60:61]
	v_pk_add_f32 v[24:25], v[24:25], v[28:29]
	v_mov_b32_e32 v90, v1
	v_pk_add_f32 v[6:7], v[6:7], v[24:25]
	v_mov_b32_e32 v1, v95
	v_pk_add_f32 v[4:5], v[4:5], v[6:7]
	v_mov_b32_e32 v102, v3
	v_pk_add_f32 v[4:5], v[4:5], v[90:91]
	v_mov_b32_e32 v3, v153
	v_pk_add_f32 v[0:1], v[0:1], v[4:5]
	s_mov_b32 s2, 0x3a800000
	v_pk_add_f32 v[0:1], v[102:103], v[0:1]
	v_lshl_add_u64 v[28:29], v[104:105], 0, v[144:145]
	v_pk_add_f32 v[4:5], v[2:3], v[0:1]
	flat_load_dwordx4 v[0:3], v[114:115] offset:16
	ds_bpermute_b32 v7, v131, v5
	ds_bpermute_b32 v6, v131, v4
	s_waitcnt lgkmcnt(0)
	v_pk_add_f32 v[4:5], v[4:5], v[6:7]
	ds_bpermute_b32 v7, v154, v5
	ds_bpermute_b32 v6, v154, v4
	s_waitcnt lgkmcnt(0)
	v_pk_add_f32 v[4:5], v[4:5], v[6:7]
	ds_bpermute_b32 v7, v155, v5
	ds_bpermute_b32 v6, v155, v4
	s_waitcnt lgkmcnt(0)
	v_pk_add_f32 v[4:5], v[4:5], v[6:7]
	ds_bpermute_b32 v7, v156, v5
	ds_bpermute_b32 v6, v156, v4
	s_waitcnt lgkmcnt(0)
	v_pk_add_f32 v[4:5], v[4:5], v[6:7]
	ds_bpermute_b32 v7, v157, v5
	ds_bpermute_b32 v6, v157, v4
	s_waitcnt lgkmcnt(0)
	v_pk_add_f32 v[4:5], v[4:5], v[6:7]
	ds_bpermute_b32 v7, v158, v5
	ds_bpermute_b32 v6, v158, v4
	s_waitcnt lgkmcnt(0)
	v_pk_add_f32 v[4:5], v[4:5], v[6:7]
	s_nop 0
	v_mov_b32_e32 v130, 0x358637bd
	v_pk_fma_f32 v[24:25], v[4:5], s[2:3], v[130:131] op_sel_hi:[1,0,0]
	s_mov_b32 s2, 0x22c00000
	v_mul_f32_e32 v4, 0x4b800000, v25
	v_cmp_gt_f32_e32 vcc, s92, v25
	s_nop 1
	v_cndmask_b32_e32 v4, v25, v4, vcc
	v_rsq_f32_e32 v4, v4
	s_nop 0
	v_mul_f32_e32 v5, 0x45800000, v4
	v_cndmask_b32_e32 v30, v4, v5, vcc
	v_pk_mul_f32 v[4:5], v[58:59], v[30:31] op_sel_hi:[1,0]
	v_pk_mul_f32 v[6:7], v[32:33], v[30:31] op_sel_hi:[1,0]
	s_waitcnt vmcnt(0)
	v_pk_mul_f32 v[4:5], v[20:21], v[4:5]
	v_pk_mul_f32 v[6:7], v[22:23], v[6:7]
	v_cvt_pk_bf16_f32 v4, v4, v5
	v_cvt_pk_bf16_f32 v5, v6, v7
	v_pk_mul_f32 v[6:7], v[44:45], v[30:31] op_sel_hi:[1,0]
	v_cmp_gt_f32_e32 vcc, s92, v24
	v_pk_mul_f32 v[6:7], v[12:13], v[6:7]
	v_pk_mul_f32 v[12:13], v[70:71], v[30:31] op_sel_hi:[1,0]
	v_cvt_pk_bf16_f32 v6, v6, v7
	v_pk_mul_f32 v[12:13], v[14:15], v[12:13]
	v_add_co_u32_e64 v20, s[6:7], s2, v28
	v_cvt_pk_bf16_f32 v7, v12, v13
	v_mul_f32_e32 v12, 0x4b800000, v24
	v_cndmask_b32_e32 v12, v24, v12, vcc
	v_rsq_f32_e32 v12, v12
	v_addc_co_u32_e64 v21, s[6:7], 0, v29, s[6:7]
	flat_store_dwordx4 v[20:21], v[4:7]
	v_readlane_b32 s2, v255, 6
	s_add_i32 s8, s8, s2
	v_mul_f32_e32 v4, 0x45800000, v12
	v_cndmask_b32_e32 v22, v12, v4, vcc
	v_pk_mul_f32 v[4:5], v[92:93], v[22:23] op_sel_hi:[1,0]
	v_pk_mul_f32 v[6:7], v[52:53], v[22:23] op_sel_hi:[1,0]
	v_pk_mul_f32 v[4:5], v[8:9], v[4:5]
	v_pk_mul_f32 v[6:7], v[10:11], v[6:7]
	v_cvt_pk_bf16_f32 v4, v4, v5
	v_cvt_pk_bf16_f32 v5, v6, v7
	v_pk_mul_f32 v[6:7], v[56:57], v[22:23] op_sel_hi:[1,0]
	v_readlane_b32 s2, v254, 13
	v_pk_mul_f32 v[0:1], v[0:1], v[6:7]
	v_pk_mul_f32 v[24:25], v[34:35], v[30:31] op_sel_hi:[1,0]
	v_cvt_pk_bf16_f32 v6, v0, v1
	v_pk_mul_f32 v[0:1], v[54:55], v[22:23] op_sel_hi:[1,0]
	v_readlane_b32 s3, v255, 7
	v_pk_mul_f32 v[0:1], v[2:3], v[0:1]
	s_cmp_lt_u32 s0, s2
	v_cvt_pk_bf16_f32 v7, v0, v1
	flat_store_dwordx4 v[20:21], v[4:7] offset:2048
	flat_load_dwordx4 v[0:3], v[112:113] offset:2048
	s_nop 0
	flat_load_dwordx4 v[4:7], v[112:113] offset:2064
	flat_load_dwordx4 v[8:11], v[114:115] offset:2048
	flat_load_dwordx4 v[12:15], v[114:115] offset:2064
	s_cselect_b64 s[2:3], -1, 0
	s_cmpk_lt_i32 s8, 0x4000
	s_cselect_b64 s[6:7], -1, 0
	s_and_b64 s[2:3], s[2:3], s[6:7]
	v_readlane_b32 s6, v255, 0
	v_readlane_b32 s7, v255, 1
	s_add_i32 s0, s0, 1
	s_and_b64 vcc, exec, s[2:3]
	v_lshl_add_u64 v[144:145], v[144:145], 0, s[6:7]
	v_readlane_b32 s6, v254, 54
	v_readlane_b32 s7, v254, 55
	s_waitcnt vmcnt(0) lgkmcnt(0)
	v_pk_mul_f32 v[0:1], v[24:25], v[0:1]
	v_pk_mul_f32 v[24:25], v[46:47], v[30:31] op_sel_hi:[1,0]
	v_cvt_pk_bf16_f32 v0, v0, v1
	v_pk_mul_f32 v[2:3], v[24:25], v[2:3]
	v_lshl_add_u64 v[146:147], v[146:147], 0, s[6:7]
	v_cvt_pk_bf16_f32 v1, v2, v3
	v_pk_mul_f32 v[2:3], v[50:51], v[30:31] op_sel_hi:[1,0]
	v_readlane_b32 s6, v255, 8
	v_pk_mul_f32 v[2:3], v[2:3], v[4:5]
	v_pk_mul_f32 v[4:5], v[68:69], v[30:31] op_sel_hi:[1,0]
	v_cvt_pk_bf16_f32 v2, v2, v3
	v_pk_mul_f32 v[4:5], v[4:5], v[6:7]
	v_pk_mul_f32 v[6:7], v[26:27], v[22:23] op_sel_hi:[1,0]
	v_cvt_pk_bf16_f32 v3, v4, v5
	v_pk_mul_f32 v[4:5], v[16:17], v[22:23] op_sel_hi:[1,0]
	v_pk_mul_f32 v[6:7], v[10:11], v[6:7]
	v_pk_mul_f32 v[4:5], v[8:9], v[4:5]
	v_pk_mul_f32 v[8:9], v[72:73], v[22:23] op_sel_hi:[1,0]
	v_cvt_pk_bf16_f32 v4, v4, v5
	v_cvt_pk_bf16_f32 v5, v6, v7
	v_pk_mul_f32 v[6:7], v[18:19], v[22:23] op_sel_hi:[1,0]
	v_readlane_b32 s7, v255, 9
	v_pk_mul_f32 v[6:7], v[12:13], v[6:7]
	v_pk_mul_f32 v[8:9], v[14:15], v[8:9]
	v_lshl_add_u64 v[148:149], v[148:149], 0, s[6:7]
	v_lshl_add_u64 v[150:151], v[150:151], 0, s[6:7]
	v_cvt_pk_bf16_f32 v6, v6, v7
	v_cvt_pk_bf16_f32 v7, v8, v9
	flat_store_dwordx4 v[20:21], v[0:3] offset:1024
	flat_store_dwordx4 v[20:21], v[4:7] offset:3072
	s_cbranch_vccz .LBB0_321

; #define PG8_STAGE(bufoff, gbase, voff) do { _Pragma("unroll") for (int _i = 0; _i < 2; ++_i) \
;         __builtin_amdgcn_global_load_lds((const unsigned*)((const char*)(gbase) + (voff)[_i]), (PG8_LAS unsigned*)(lds + (bufoff) + ldsw + _i * 8192), 16, 0, 0); } while (0)
; #define PG8_WAIT_V(n) asm volatile("s_waitcnt vmcnt(" #n ")" ::: "memory")
; #define PG8_BAR __builtin_amdgcn_s_barrier()
; template <class Epi, class Sched, bool ALIGN_EPI = false, bool SP2 = false>
; __device__ __forceinline__ void gemm_phase(PG8_LAS unsigned char* lds, const Gemm g, const Sched& S, const Epi& E, int tid_in) {
;     ...
;     const unsigned ldsw = (unsigned)wid * 1024u;
;     const int aoff = lds_byte(wr * 64 + fr, fq * 8), boff = lds_byte(wc * 32 + fr, fq * 8);
;     ...
;         PG8_WAIT_V(2); PG8_BAR;
;         PG8_STAGE(PG8_SB(1, 0), cB + kstep, voffB); PG8_STAGE(PG8_SA(1, 0), cA + kstep, voffA); PG8_STAGE(PG8_SB(1, 1), cB + hstep + kstep, voffB);
;         PG8_WAIT_V(6); PG8_BAR;
.LBB0_395:
	v_lshl_add_u64 v[150:151], v[4:5], 0, s[56:57]
	v_lshrrev_b32_e32 v5, 1, v20
	v_and_b32_e32 v21, 24, v5
	v_and_b32_e32 v4, 15, v20
	v_lshlrev_b32_e32 v5, 1, v21
	v_lshl_or_b32 v163, s6, 6, v4
	v_lshl_or_b32 v4, v4, 6, v5
	v_lshlrev_b32_e32 v5, 2, v20
	s_lshl_b32 s3, s3, 5
	s_lshl_b32 s6, s6, 13
	v_and_b32_e32 v5, 32, v5
	s_and_b32 s3, s3, 0x60
	v_bitop3_b32 v20, v4, s6, v5 bitop3:0xde
	s_lshl_b32 s6, s3, 7
	v_bitop3_b32 v168, v4, s6, v5 bitop3:0xde
	v_add_u32_e32 v173, 0x10000, v168
	s_add_i32 m0, s16, 0x18000
	v_lshl_add_u64 v[4:5], v[6:7], 0, s[70:71]
	s_waitcnt vmcnt(2)
	s_barrier
	global_load_lds_dwordx4 v[4:5], off
	v_lshl_add_u64 v[4:5], v[8:9], 0, s[70:71]
	s_add_i32 m0, s16, 0x1a000
	s_add_i32 s20, s16, 0x8000
	global_load_lds_dwordx4 v[4:5], off
	v_lshl_add_u64 v[4:5], v[10:11], 0, s[70:71]
	s_mov_b32 m0, s20
	s_add_i32 s21, s16, 0xa000
	global_load_lds_dwordx4 v[4:5], off
	v_lshl_add_u64 v[4:5], v[12:13], 0, s[70:71]
	s_mov_b32 m0, s21
	v_or_b32_e32 v169, s3, v21
	global_load_lds_dwordx4 v[4:5], off
	v_lshl_add_u64 v[4:5], v[0:1], 0, s[86:87]
	s_add_i32 m0, s16, 0x1c000
	v_lshl_add_u64 v[6:7], v[4:5], 0, v[128:129]
	global_load_lds_dwordx4 v[6:7], off
	v_lshl_add_u64 v[4:5], v[4:5], 0, v[144:145]
	s_add_i32 m0, s16, 0x1e000
	s_cmpk_lt_u32 s2, 0x100
	global_load_lds_dwordx4 v[4:5], off
	v_lshlrev_b32_e32 v4, 15, v14
	v_and_b32_e32 v4, 0xffff0000, v4
	v_lshl_add_u32 v4, v15, 12, v4
	v_and_b32_e32 v5, 1, v14
	v_lshl_or_b32 v4, v5, 6, v4
	v_lshl_add_u32 v152, v16, 1, v4
	v_lshlrev_b32_e32 v4, 15, v18
	v_and_b32_e32 v4, 0xffff0000, v4
	s_waitcnt vmcnt(6)
	v_lshl_add_u32 v4, v17, 12, v4
	v_and_b32_e32 v5, 1, v18
	v_lshl_or_b32 v4, v5, 6, v4
	v_readlane_b32 s2, v254, 44
	s_cselect_b64 s[10:11], -1, 0
	v_mov_b32_e32 v153, v129
	v_lshl_add_u32 v154, v19, 1, v4
	v_mov_b32_e32 v155, v129
	s_mov_b32 s22, 0
	v_add_u32_e32 v175, 0, v20
	v_readlane_b32 s23, v254, 48
	s_mov_b32 s24, s2
	s_barrier
	v_readlane_b32 s3, v254, 45
	s_branch .LBB0_398

; #define PG8_STAGE(bufoff, gbase, voff) do { _Pragma("unroll") for (int _i = 0; _i < 2; ++_i) \
;         __builtin_amdgcn_global_load_lds((const unsigned*)((const char*)(gbase) + (voff)[_i]), (PG8_LAS unsigned*)(lds + (bufoff) + ldsw + _i * 8192), 16, 0, 0); } while (0)
; #define PG8_LDA(dst, b, h) do { _Pragma("unroll") for (int m = 0; m < 4; ++m) _Pragma("unroll") for (int k = 0; k < 2; ++k) dst[m][k] = *(const PG8_LAS bf16x8*)(lds + PG8_SA(b, h) + aoff + m * 2048 + k * 1024); } while (0)
; #define PG8_LDB(dst, b, h) do { _Pragma("unroll") for (int n = 0; n < 2; ++n) _Pragma("unroll") for (int k = 0; k < 2; ++k) dst[n][k] = *(const PG8_LAS bf16x8*)(lds + PG8_SB(b, h) + boff + n * 2048 + k * 1024); } while (0)
; #define PG8_MMA(ai, bj, At, Bt) do { __builtin_amdgcn_s_setprio(1); _Pragma("unroll") for (int m = 0; m < 4; ++m) _Pragma("unroll") for (int n = 0; n < 2; ++n) _Pragma("unroll") for (int k = 0; k < 2; ++k) \
;         acc[ai][bj][m][n] = __builtin_amdgcn_mfma_f32_16x16x32_bf16(Bt[n][k], At[m][k], acc[ai][bj][m][n], 0, 0, 0); __builtin_amdgcn_s_setprio(0); } while (0)
; #define PG8_WAIT_V(n) asm volatile("s_waitcnt vmcnt(" #n ")" ::: "memory")
; #define PG8_WAIT_L(n) asm volatile("s_waitcnt lgkmcnt(" #n ")" ::: "memory")
; template <class Epi, class Sched, bool ALIGN_EPI = false, bool SP2 = false>
; __device__ __forceinline__ void gemm_phase(PG8_LAS unsigned char* lds, const Gemm g, const Sched& S, const Epi& E, int tid_in) {
;     ...
;             const bool last = (t == nt - 2);
;             const char* a1 = cA + (size_t)(t + 1) * kstep;
;             const char* a2 = last ? nA : cA + (size_t)(t + 2) * kstep; const char* b2 = last ? nB : cB + (size_t)(t + 2) * kstep;
;             const char* a3 = a2 + kstep; const char* b3 = b2 + kstep;
;             if (last && has_next) S.a_ready(nxt);
;             if constexpr (SP2) {
;             PG8_LDB(B0, 0, 0); PG8_LDB(B1, 0, 1); PG8_SCHED; PG8_LDA(At, 0, 0); PG8_STAGE(PG8_SA(1, 1), a1 + hstep, voffA);
;             PG8_WAIT_V(8); PG8_WAIT_L(0); PG8_BAR; PG8_MMA(0, 0, At, B0); PG8_MMA(0, 1, At, B1); PG8_BAR; PG8_SCHED;
;             PG8_LDA(At, 0, 1); PG8_STAGE(PG8_SB(0, 0), b2, voffB); PG8_STAGE(PG8_SB(0, 1), b2 + hstep, voffB); PG8_STAGE(PG8_SA(0, 0), a2, voffA);
;             PG8_WAIT_V(8); PG8_WAIT_L(0); PG8_BAR; PG8_MMA(1, 0, At, B0); PG8_MMA(1, 1, At, B1); PG8_BAR; PG8_SCHED;
.LBB0_405:
	s_cmp_eq_u32 s2, 28
	s_cselect_b64 vcc, -1, 0
	s_add_i32 s3, 0, 0x10000
	s_add_i32 s13, 0, 0x14000
	v_lshl_add_u64 v[176:177], v[166:167], 0, s[52:53]
	v_cndmask_b32_e32 v241, v177, v131, vcc
	v_cndmask_b32_e32 v240, v176, v160, vcc
	ds_read_b128 v[176:179], v173
	ds_read_b128 v[180:183], v173 offset:1024
	ds_read_b128 v[184:187], v173 offset:2048
	ds_read_b128 v[188:191], v173 offset:3072
	ds_read_b128 v[192:195], v173 offset:16384
	ds_read_b128 v[196:199], v173 offset:17408
	ds_read_b128 v[200:203], v173 offset:18432
	ds_read_b128 v[204:207], v173 offset:19456
	v_cndmask_b32_e32 v243, v165, v161, vcc
	v_cndmask_b32_e32 v242, v164, v162, vcc
	v_lshl_add_u64 v[244:245], v[166:167], 0, v[154:155]
	s_add_i32 m0, s16, 0xc000
	ds_read_b128 v[208:211], v175
	ds_read_b128 v[212:215], v175 offset:1024
	ds_read_b128 v[216:219], v175 offset:2048
	ds_read_b128 v[220:223], v175 offset:3072
	ds_read_b128 v[224:227], v175 offset:4096
	ds_read_b128 v[228:231], v175 offset:5120
	ds_read_b128 v[232:235], v175 offset:6144
	ds_read_b128 v[236:239], v175 offset:7168
	global_load_lds_dwordx4 v[244:245], off
	v_lshl_add_u64 v[244:245], v[166:167], 0, v[152:153]
	s_add_i32 m0, s16, 0xe000
	s_nop 0
	global_load_lds_dwordx4 v[244:245], off
	s_setprio 0
	s_waitcnt vmcnt(8) lgkmcnt(0)
	s_barrier
	v_mfma_f32_16x16x32_bf16 v[124:127], v[176:179], v[208:211], v[124:127]
	v_mfma_f32_16x16x32_bf16 v[120:123], v[184:187], v[208:211], v[120:123]
	v_mfma_f32_16x16x32_bf16 v[116:119], v[176:179], v[216:219], v[116:119]
	v_mfma_f32_16x16x32_bf16 v[108:111], v[184:187], v[216:219], v[108:111]
	v_mfma_f32_16x16x32_bf16 v[100:103], v[176:179], v[224:227], v[100:103]
	v_mfma_f32_16x16x32_bf16 v[92:95], v[184:187], v[224:227], v[92:95]
	v_mfma_f32_16x16x32_bf16 v[84:87], v[176:179], v[232:235], v[84:87]
	v_mfma_f32_16x16x32_bf16 v[76:79], v[184:187], v[232:235], v[76:79]
	v_mfma_f32_16x16x32_bf16 v[124:127], v[180:183], v[212:215], v[124:127]
	v_mfma_f32_16x16x32_bf16 v[120:123], v[188:191], v[212:215], v[120:123]
	v_mfma_f32_16x16x32_bf16 v[116:119], v[180:183], v[220:223], v[116:119]
	v_mfma_f32_16x16x32_bf16 v[108:111], v[188:191], v[220:223], v[108:111]
	v_mfma_f32_16x16x32_bf16 v[100:103], v[180:183], v[228:231], v[100:103]
	v_mfma_f32_16x16x32_bf16 v[92:95], v[188:191], v[228:231], v[92:95]
	v_mfma_f32_16x16x32_bf16 v[84:87], v[180:183], v[236:239], v[84:87]
	v_mfma_f32_16x16x32_bf16 v[76:79], v[188:191], v[236:239], v[76:79]
	v_mfma_f32_16x16x32_bf16 v[112:115], v[192:195], v[208:211], v[112:115]
	v_mfma_f32_16x16x32_bf16 v[104:107], v[200:203], v[208:211], v[104:107]
	v_mfma_f32_16x16x32_bf16 v[96:99], v[192:195], v[216:219], v[96:99]
	v_mfma_f32_16x16x32_bf16 v[88:91], v[200:203], v[216:219], v[88:91]
	v_mfma_f32_16x16x32_bf16 v[80:83], v[192:195], v[224:227], v[80:83]
	v_mfma_f32_16x16x32_bf16 v[72:75], v[200:203], v[224:227], v[72:75]
	v_mfma_f32_16x16x32_bf16 v[68:71], v[192:195], v[232:235], v[68:71]
	v_mfma_f32_16x16x32_bf16 v[64:67], v[200:203], v[232:235], v[64:67]
	v_mfma_f32_16x16x32_bf16 v[112:115], v[196:199], v[212:215], v[112:115]
	v_mfma_f32_16x16x32_bf16 v[104:107], v[204:207], v[212:215], v[104:107]
	v_mfma_f32_16x16x32_bf16 v[96:99], v[196:199], v[220:223], v[96:99]
	v_mfma_f32_16x16x32_bf16 v[88:91], v[204:207], v[220:223], v[88:91]
	v_mfma_f32_16x16x32_bf16 v[80:83], v[196:199], v[228:231], v[80:83]
	v_mfma_f32_16x16x32_bf16 v[72:75], v[204:207], v[228:231], v[72:75]
	v_mfma_f32_16x16x32_bf16 v[68:71], v[196:199], v[236:239], v[68:71]
	v_mfma_f32_16x16x32_bf16 v[64:67], v[204:207], v[236:239], v[64:67]
	s_barrier
	s_setprio 1
	s_add_i32 s3, s3, s1
	v_lshl_add_u64 v[244:245], v[242:243], 0, v[128:129]
	s_mov_b32 m0, s3
	ds_read_b128 v[208:211], v175 offset:16384
	ds_read_b128 v[212:215], v175 offset:17408
	ds_read_b128 v[216:219], v175 offset:18432
	ds_read_b128 v[220:223], v175 offset:19456
	ds_read_b128 v[224:227], v175 offset:20480
	ds_read_b128 v[228:231], v175 offset:21504
	ds_read_b128 v[232:235], v175 offset:22528
	ds_read_b128 v[236:239], v175 offset:23552
	global_load_lds_dwordx4 v[244:245], off
	v_lshl_add_u64 v[246:247], v[242:243], 0, v[144:145]
	s_add_i32 m0, s3, 0x2000
	v_lshl_add_u64 v[248:249], v[242:243], 0, s[98:99]
	s_add_i32 s3, s13, s1
	global_load_lds_dwordx4 v[246:247], off
	v_lshl_add_u64 v[250:251], v[248:249], 0, v[128:129]
	s_mov_b32 m0, s3
	v_lshl_add_u64 v[248:249], v[248:249], 0, v[144:145]
	global_load_lds_dwordx4 v[250:251], off
	s_add_i32 m0, s3, 0x2000
	v_lshl_add_u64 v[250:251], v[240:241], 0, v[146:147]
	global_load_lds_dwordx4 v[248:249], off
	v_lshl_add_u64 v[248:249], v[240:241], 0, v[148:149]
	s_mov_b32 m0, s16
	s_nop 0
	global_load_lds_dwordx4 v[248:249], off
	s_mov_b32 m0, s17
	s_nop 0
	global_load_lds_dwordx4 v[250:251], off
	s_setprio 0
	s_waitcnt vmcnt(8) lgkmcnt(0)
	s_barrier
; #define PG8_STAGE(bufoff, gbase, voff) do { _Pragma("unroll") for (int _i = 0; _i < 2; ++_i) \
;         __builtin_amdgcn_global_load_lds((const unsigned*)((const char*)(gbase) + (voff)[_i]), (PG8_LAS unsigned*)(lds + (bufoff) + ldsw + _i * 8192), 16, 0, 0); } while (0)
; #define PG8_LDA(dst, b, h) do { _Pragma("unroll") for (int m = 0; m < 4; ++m) _Pragma("unroll") for (int k = 0; k < 2; ++k) dst[m][k] = *(const PG8_LAS bf16x8*)(lds + PG8_SA(b, h) + aoff + m * 2048 + k * 1024); } while (0)
; #define PG8_LDB(dst, b, h) do { _Pragma("unroll") for (int n = 0; n < 2; ++n) _Pragma("unroll") for (int k = 0; k < 2; ++k) dst[n][k] = *(const PG8_LAS bf16x8*)(lds + PG8_SB(b, h) + boff + n * 2048 + k * 1024); } while (0)
; #define PG8_MMA(ai, bj, At, Bt) do { __builtin_amdgcn_s_setprio(1); _Pragma("unroll") for (int m = 0; m < 4; ++m) _Pragma("unroll") for (int n = 0; n < 2; ++n) _Pragma("unroll") for (int k = 0; k < 2; ++k) \
;         acc[ai][bj][m][n] = __builtin_amdgcn_mfma_f32_16x16x32_bf16(Bt[n][k], At[m][k], acc[ai][bj][m][n], 0, 0, 0); __builtin_amdgcn_s_setprio(0); } while (0)
; #define PG8_WAIT_V(n) asm volatile("s_waitcnt vmcnt(" #n ")" ::: "memory")
; #define PG8_WAIT_L(n) asm volatile("s_waitcnt lgkmcnt(" #n ")" ::: "memory")
; #define PG8_BAR __builtin_amdgcn_s_barrier()
; #define PG8_SCHED __builtin_amdgcn_sched_barrier(0)
; template <class Epi, class Sched, bool ALIGN_EPI = false, bool SP2 = false>
; __device__ __forceinline__ void gemm_phase(PG8_LAS unsigned char* lds, const Gemm g, const Sched& S, const Epi& E, int tid_in) {
;     ...
;             PG8_WAIT_V(8); PG8_WAIT_L(0); PG8_BAR; PG8_MMA(1, 0, At, B0); PG8_MMA(1, 1, At, B1); PG8_BAR; PG8_SCHED;
;             PG8_LDB(B0, 1, 0); PG8_LDB(B1, 1, 1); PG8_SCHED; PG8_LDA(At, 1, 0); PG8_STAGE(PG8_SA(0, 1), a2 + hstep, voffA);
;             PG8_WAIT_V(8); PG8_WAIT_L(0); PG8_BAR; PG8_MMA(0, 0, At, B0); PG8_MMA(0, 1, At, B1); PG8_BAR; PG8_SCHED;
;             PG8_LDA(At, 1, 1); PG8_STAGE(PG8_SB(1, 0), b3, voffB); PG8_STAGE(PG8_SB(1, 1), b3 + hstep, voffB); PG8_STAGE(PG8_SA(1, 0), a3, voffA);
	v_mfma_f32_16x16x32_bf16 v[60:63], v[176:179], v[208:211], v[60:63]
	v_mfma_f32_16x16x32_bf16 v[56:59], v[184:187], v[208:211], v[56:59]
	v_mfma_f32_16x16x32_bf16 v[52:55], v[176:179], v[216:219], v[52:55]
	v_mfma_f32_16x16x32_bf16 v[44:47], v[184:187], v[216:219], v[44:47]
	v_mfma_f32_16x16x32_bf16 v[36:39], v[176:179], v[224:227], v[36:39]
	v_mfma_f32_16x16x32_bf16 v[28:31], v[184:187], v[224:227], v[28:31]
	v_mfma_f32_16x16x32_bf16 v[20:23], v[176:179], v[232:235], v[20:23]
	v_mfma_f32_16x16x32_bf16 v[12:15], v[184:187], v[232:235], v[12:15]
	v_mfma_f32_16x16x32_bf16 v[60:63], v[180:183], v[212:215], v[60:63]
	v_mfma_f32_16x16x32_bf16 v[56:59], v[188:191], v[212:215], v[56:59]
	v_mfma_f32_16x16x32_bf16 v[52:55], v[180:183], v[220:223], v[52:55]
	v_mfma_f32_16x16x32_bf16 v[44:47], v[188:191], v[220:223], v[44:47]
	v_mfma_f32_16x16x32_bf16 v[36:39], v[180:183], v[228:231], v[36:39]
	v_mfma_f32_16x16x32_bf16 v[28:31], v[188:191], v[228:231], v[28:31]
	v_mfma_f32_16x16x32_bf16 v[20:23], v[180:183], v[236:239], v[20:23]
	v_mfma_f32_16x16x32_bf16 v[12:15], v[188:191], v[236:239], v[12:15]
	v_mfma_f32_16x16x32_bf16 v[48:51], v[192:195], v[208:211], v[48:51]
	v_mfma_f32_16x16x32_bf16 v[40:43], v[200:203], v[208:211], v[40:43]
	v_mfma_f32_16x16x32_bf16 v[32:35], v[192:195], v[216:219], v[32:35]
	v_mfma_f32_16x16x32_bf16 v[24:27], v[200:203], v[216:219], v[24:27]
	v_mfma_f32_16x16x32_bf16 v[16:19], v[192:195], v[224:227], v[16:19]
	v_mfma_f32_16x16x32_bf16 v[8:11], v[200:203], v[224:227], v[8:11]
	v_mfma_f32_16x16x32_bf16 v[4:7], v[192:195], v[232:235], v[4:7]
	v_mfma_f32_16x16x32_bf16 v[0:3], v[200:203], v[232:235], v[0:3]
	v_mfma_f32_16x16x32_bf16 v[48:51], v[196:199], v[212:215], v[48:51]
	v_mfma_f32_16x16x32_bf16 v[40:43], v[204:207], v[212:215], v[40:43]
	v_mfma_f32_16x16x32_bf16 v[32:35], v[196:199], v[220:223], v[32:35]
	v_mfma_f32_16x16x32_bf16 v[24:27], v[204:207], v[220:223], v[24:27]
	v_mfma_f32_16x16x32_bf16 v[16:19], v[196:199], v[228:231], v[16:19]
	v_mfma_f32_16x16x32_bf16 v[8:11], v[204:207], v[228:231], v[8:11]
	v_mfma_f32_16x16x32_bf16 v[4:7], v[196:199], v[236:239], v[4:7]
	v_mfma_f32_16x16x32_bf16 v[0:3], v[204:207], v[236:239], v[0:3]
	s_barrier
	s_setprio 1
	s_add_i32 s3, 0, 0x18000
	s_add_i32 s13, 0, 0x1c000
	ds_read_b128 v[176:179], v173 offset:32768
	ds_read_b128 v[180:183], v173 offset:33792
	ds_read_b128 v[184:187], v173 offset:34816
	ds_read_b128 v[188:191], v173 offset:35840
	ds_read_b128 v[192:195], v173 offset:49152
	ds_read_b128 v[196:199], v173 offset:50176
	ds_read_b128 v[200:203], v173 offset:51200
	ds_read_b128 v[204:207], v173 offset:52224
	v_lshl_add_u64 v[240:241], v[240:241], 0, s[98:99]
	s_mov_b32 m0, s18
	v_lshl_add_u64 v[252:253], v[240:241], 0, v[148:149]
	ds_read_b128 v[208:211], v175 offset:32768
	ds_read_b128 v[212:215], v175 offset:33792
	ds_read_b128 v[216:219], v175 offset:34816
	ds_read_b128 v[220:223], v175 offset:35840
	ds_read_b128 v[224:227], v175 offset:36864
	ds_read_b128 v[228:231], v175 offset:37888
	ds_read_b128 v[232:235], v175 offset:38912
	ds_read_b128 v[236:239], v175 offset:39936
	global_load_lds_dwordx4 v[252:253], off
	v_lshl_add_u64 v[240:241], v[240:241], 0, v[146:147]
	s_mov_b32 m0, s19
	s_nop 0
	global_load_lds_dwordx4 v[240:241], off
	s_setprio 0
	s_waitcnt vmcnt(8) lgkmcnt(0)
	s_barrier
	v_mfma_f32_16x16x32_bf16 v[124:127], v[176:179], v[208:211], v[124:127]
	v_mfma_f32_16x16x32_bf16 v[120:123], v[184:187], v[208:211], v[120:123]
	v_mfma_f32_16x16x32_bf16 v[116:119], v[176:179], v[216:219], v[116:119]
	v_mfma_f32_16x16x32_bf16 v[108:111], v[184:187], v[216:219], v[108:111]
	v_mfma_f32_16x16x32_bf16 v[100:103], v[176:179], v[224:227], v[100:103]
	v_mfma_f32_16x16x32_bf16 v[92:95], v[184:187], v[224:227], v[92:95]
	v_mfma_f32_16x16x32_bf16 v[84:87], v[176:179], v[232:235], v[84:87]
	v_mfma_f32_16x16x32_bf16 v[76:79], v[184:187], v[232:235], v[76:79]
	v_mfma_f32_16x16x32_bf16 v[124:127], v[180:183], v[212:215], v[124:127]
	v_mfma_f32_16x16x32_bf16 v[120:123], v[188:191], v[212:215], v[120:123]
	v_mfma_f32_16x16x32_bf16 v[116:119], v[180:183], v[220:223], v[116:119]
	v_mfma_f32_16x16x32_bf16 v[108:111], v[188:191], v[220:223], v[108:111]
	v_mfma_f32_16x16x32_bf16 v[100:103], v[180:183], v[228:231], v[100:103]
	v_mfma_f32_16x16x32_bf16 v[92:95], v[188:191], v[228:231], v[92:95]
	v_mfma_f32_16x16x32_bf16 v[84:87], v[180:183], v[236:239], v[84:87]
	v_mfma_f32_16x16x32_bf16 v[76:79], v[188:191], v[236:239], v[76:79]
	v_mfma_f32_16x16x32_bf16 v[112:115], v[192:195], v[208:211], v[112:115]
	v_mfma_f32_16x16x32_bf16 v[104:107], v[200:203], v[208:211], v[104:107]
	v_mfma_f32_16x16x32_bf16 v[96:99], v[192:195], v[216:219], v[96:99]
	v_mfma_f32_16x16x32_bf16 v[88:91], v[200:203], v[216:219], v[88:91]
	v_mfma_f32_16x16x32_bf16 v[80:83], v[192:195], v[224:227], v[80:83]
	v_mfma_f32_16x16x32_bf16 v[72:75], v[200:203], v[224:227], v[72:75]
	v_mfma_f32_16x16x32_bf16 v[68:71], v[192:195], v[232:235], v[68:71]
	v_mfma_f32_16x16x32_bf16 v[64:67], v[200:203], v[232:235], v[64:67]
	v_mfma_f32_16x16x32_bf16 v[112:115], v[196:199], v[212:215], v[112:115]
	v_mfma_f32_16x16x32_bf16 v[104:107], v[204:207], v[212:215], v[104:107]
	v_mfma_f32_16x16x32_bf16 v[96:99], v[196:199], v[220:223], v[96:99]
	v_mfma_f32_16x16x32_bf16 v[88:91], v[204:207], v[220:223], v[88:91]
	v_mfma_f32_16x16x32_bf16 v[80:83], v[196:199], v[228:231], v[80:83]
	v_mfma_f32_16x16x32_bf16 v[72:75], v[204:207], v[228:231], v[72:75]
	v_mfma_f32_16x16x32_bf16 v[68:71], v[196:199], v[236:239], v[68:71]
	v_mfma_f32_16x16x32_bf16 v[64:67], v[204:207], v[236:239], v[64:67]
	s_barrier
; #define PG8_STAGE(bufoff, gbase, voff) do { _Pragma("unroll") for (int _i = 0; _i < 2; ++_i) \
;         __builtin_amdgcn_global_load_lds((const unsigned*)((const char*)(gbase) + (voff)[_i]), (PG8_LAS unsigned*)(lds + (bufoff) + ldsw + _i * 8192), 16, 0, 0); } while (0)
; #define PG8_LDA(dst, b, h) do { _Pragma("unroll") for (int m = 0; m < 4; ++m) _Pragma("unroll") for (int k = 0; k < 2; ++k) dst[m][k] = *(const PG8_LAS bf16x8*)(lds + PG8_SA(b, h) + aoff + m * 2048 + k * 1024); } while (0)
; #define PG8_MMA(ai, bj, At, Bt) do { __builtin_amdgcn_s_setprio(1); _Pragma("unroll") for (int m = 0; m < 4; ++m) _Pragma("unroll") for (int n = 0; n < 2; ++n) _Pragma("unroll") for (int k = 0; k < 2; ++k) \
;         acc[ai][bj][m][n] = __builtin_amdgcn_mfma_f32_16x16x32_bf16(Bt[n][k], At[m][k], acc[ai][bj][m][n], 0, 0, 0); __builtin_amdgcn_s_setprio(0); } while (0)
; #define PG8_WAIT_V(n) asm volatile("s_waitcnt vmcnt(" #n ")" ::: "memory")
; #define PG8_WAIT_L(n) asm volatile("s_waitcnt lgkmcnt(" #n ")" ::: "memory")
; #define PG8_BAR __builtin_amdgcn_s_barrier()
; #define PG8_SCHED __builtin_amdgcn_sched_barrier(0)
; template <class Epi, class Sched, bool ALIGN_EPI = false, bool SP2 = false>
; __device__ __forceinline__ void gemm_phase(PG8_LAS unsigned char* lds, const Gemm g, const Sched& S, const Epi& E, int tid_in) {
;     ...
;         for (int t = 0; t < nt; t += 2) {
;     ...
;             PG8_LDA(At, 1, 1); PG8_STAGE(PG8_SB(1, 0), b3, voffB); PG8_STAGE(PG8_SB(1, 1), b3 + hstep, voffB); PG8_STAGE(PG8_SA(1, 0), a3, voffA);
;             PG8_WAIT_V(8); PG8_WAIT_L(0); PG8_BAR; PG8_MMA(1, 0, At, B0); PG8_MMA(1, 1, At, B1); PG8_BAR; PG8_SCHED;
	s_setprio 1
	s_add_i32 s3, s3, s1
	v_lshl_add_u64 v[240:241], v[244:245], 0, s[70:71]
	s_mov_b32 m0, s3
	ds_read_b128 v[208:211], v175 offset:49152
	ds_read_b128 v[212:215], v175 offset:50176
	ds_read_b128 v[216:219], v175 offset:51200
	ds_read_b128 v[220:223], v175 offset:52224
	ds_read_b128 v[224:227], v175 offset:53248
	ds_read_b128 v[228:231], v175 offset:54272
	ds_read_b128 v[232:235], v175 offset:55296
	ds_read_b128 v[236:239], v175 offset:56320
	global_load_lds_dwordx4 v[240:241], off
	v_lshl_add_u64 v[240:241], v[246:247], 0, s[70:71]
	s_add_i32 m0, s3, 0x2000
	s_add_i32 s3, s13, s1
	global_load_lds_dwordx4 v[240:241], off
	v_lshl_add_u64 v[240:241], v[242:243], 0, s[86:87]
	v_lshl_add_u64 v[242:243], v[240:241], 0, v[128:129]
	s_mov_b32 m0, s3
	v_lshl_add_u64 v[240:241], v[240:241], 0, v[144:145]
	global_load_lds_dwordx4 v[242:243], off
	s_add_i32 m0, s3, 0x2000
	s_nop 0
	global_load_lds_dwordx4 v[240:241], off
	v_lshl_add_u64 v[240:241], v[248:249], 0, s[70:71]
	s_mov_b32 m0, s20
	s_nop 0
	global_load_lds_dwordx4 v[240:241], off
	v_lshl_add_u64 v[240:241], v[250:251], 0, s[70:71]
	s_mov_b32 m0, s21
	s_nop 0
	global_load_lds_dwordx4 v[240:241], off
	s_setprio 0
	s_waitcnt vmcnt(8) lgkmcnt(0)
	s_barrier
	v_mfma_f32_16x16x32_bf16 v[60:63], v[176:179], v[208:211], v[60:63]
	v_mfma_f32_16x16x32_bf16 v[56:59], v[184:187], v[208:211], v[56:59]
	v_mfma_f32_16x16x32_bf16 v[52:55], v[176:179], v[216:219], v[52:55]
	v_mfma_f32_16x16x32_bf16 v[44:47], v[184:187], v[216:219], v[44:47]
	v_mfma_f32_16x16x32_bf16 v[36:39], v[176:179], v[224:227], v[36:39]
	v_mfma_f32_16x16x32_bf16 v[28:31], v[184:187], v[224:227], v[28:31]
	v_mfma_f32_16x16x32_bf16 v[20:23], v[176:179], v[232:235], v[20:23]
	v_mfma_f32_16x16x32_bf16 v[12:15], v[184:187], v[232:235], v[12:15]
	v_mfma_f32_16x16x32_bf16 v[60:63], v[180:183], v[212:215], v[60:63]
	v_mfma_f32_16x16x32_bf16 v[56:59], v[188:191], v[212:215], v[56:59]
	v_mfma_f32_16x16x32_bf16 v[52:55], v[180:183], v[220:223], v[52:55]
	v_mfma_f32_16x16x32_bf16 v[44:47], v[188:191], v[220:223], v[44:47]
	v_mfma_f32_16x16x32_bf16 v[36:39], v[180:183], v[228:231], v[36:39]
	v_mfma_f32_16x16x32_bf16 v[28:31], v[188:191], v[228:231], v[28:31]
	v_mfma_f32_16x16x32_bf16 v[20:23], v[180:183], v[236:239], v[20:23]
	v_mfma_f32_16x16x32_bf16 v[12:15], v[188:191], v[236:239], v[12:15]
	v_mfma_f32_16x16x32_bf16 v[48:51], v[192:195], v[208:211], v[48:51]
	v_mfma_f32_16x16x32_bf16 v[40:43], v[200:203], v[208:211], v[40:43]
	v_mfma_f32_16x16x32_bf16 v[32:35], v[192:195], v[216:219], v[32:35]
	v_mfma_f32_16x16x32_bf16 v[24:27], v[200:203], v[216:219], v[24:27]
	v_mfma_f32_16x16x32_bf16 v[16:19], v[192:195], v[224:227], v[16:19]
	v_mfma_f32_16x16x32_bf16 v[8:11], v[200:203], v[224:227], v[8:11]
	v_mfma_f32_16x16x32_bf16 v[4:7], v[192:195], v[232:235], v[4:7]
	v_mfma_f32_16x16x32_bf16 v[0:3], v[200:203], v[232:235], v[0:3]
	v_mfma_f32_16x16x32_bf16 v[48:51], v[196:199], v[212:215], v[48:51]
	v_mfma_f32_16x16x32_bf16 v[40:43], v[204:207], v[212:215], v[40:43]
	v_mfma_f32_16x16x32_bf16 v[32:35], v[196:199], v[220:223], v[32:35]
	v_mfma_f32_16x16x32_bf16 v[24:27], v[204:207], v[220:223], v[24:27]
	v_mfma_f32_16x16x32_bf16 v[16:19], v[196:199], v[228:231], v[16:19]
	v_mfma_f32_16x16x32_bf16 v[8:11], v[204:207], v[228:231], v[8:11]
	v_mfma_f32_16x16x32_bf16 v[4:7], v[196:199], v[236:239], v[4:7]
	v_mfma_f32_16x16x32_bf16 v[0:3], v[204:207], v[236:239], v[0:3]
	s_barrier
	s_setprio 1
	s_add_i32 s2, s2, 2
	v_lshl_add_u64 v[164:165], v[164:165], 0, s[82:83]
	s_cmp_gt_u32 s2, 29
	v_lshl_add_u64 v[166:167], v[166:167], 0, s[82:83]
	s_cbranch_scc0 .LBB0_405
	s_setprio 0
	s_and_b64 vcc, exec, s[10:11]
	s_cbranch_vccz .LBB0_408
	s_barrier

; __device__ __forceinline__ float dot4(f32x4 a) { return (a.x * a.x + a.y * a.y) + (a.z * a.z + a.w * a.w); }
; __device__ __forceinline__ f32x4 bf4lo(u32x4 w) { return (f32x4){bflo(w.x), bfhi(w.x), bflo(w.y), bfhi(w.y)}; }
; __device__ __forceinline__ f32x4 bf4hi(u32x4 w) { return (f32x4){bflo(w.z), bfhi(w.z), bflo(w.w), bfhi(w.w)}; }
; __device__ __forceinline__ f32x4 rcp4(f32x4 g) { return (f32x4){__builtin_amdgcn_rcpf(g.x), __builtin_amdgcn_rcpf(g.y), __builtin_amdgcn_rcpf(g.z), __builtin_amdgcn_rcpf(g.w)}; }
; __device__ __forceinline__ void normres_phase(const bf16_t* hf, const float* xsrc, const float* gprev, bf16_t* HI, bf16_t* LO, float* RS, float* xdst, const float* gpost, float w, const float* gpre, ...
;     ...
;             u32x4 hiw[2][4]; float rsp[2];
; #pragma unroll
;             for (int q = 0; q < 2; ++q) { const int rr = q ? rowb : row;
;                 const u32x4* hr = (const u32x4*)(hf + (size_t)rr * D) + lane; const u32x4* ar = (const u32x4*)(HI + (size_t)rr * D) + lane;
;                 rsp[q] = RS[rr];
; #pragma unroll
;                 for (int c = 0; c < 4; ++c) { hw[q][c] = hr[64 * c]; hiw[q][c] = ar[64 * c]; } }
;             const f32x4* gv4 = (const f32x4*)gprev + 2 * lane;
; #pragma unroll
;             for (int c = 0; c < 4; ++c) { const f32x4 ig0 = rcp4(gv4[128 * c]), ig1 = rcp4(gv4[128 * c + 1]);
; #pragma unroll
;                 for (int q = 0; q < 2; ++q) { const float inv = __builtin_amdgcn_rcpf(rsp[q]);
;                     xv[q][2 * c] = bf4lo(hiw[q][c]) * ig0 * inv; xv[q][2 * c + 1] = bf4hi(hiw[q][c]) * ig1 * inv; } }
;         }
; #pragma unroll
;         for (int q = 0; q < 2; ++q) { if (q == 1 && !two) break; const int rr = q ? rowb : row;
;             float ss = 0.f;
; #pragma unroll
;             for (int c = 0; c < 4; ++c) ss += dot4(bf4lo(hw[q][c])) + dot4(bf4hi(hw[q][c]));
.LBB0_502:
	s_waitcnt vmcnt(0) lgkmcnt(0)
	flat_load_dwordx4 v[0:3], v[40:41]
	flat_load_dwordx4 v[4:7], v[40:41] offset:16
	flat_load_dwordx4 v[8:11], v[40:41] offset:2048
	flat_load_dwordx4 v[12:15], v[40:41] offset:2064
	flat_load_dwordx4 v[16:19], v[46:47]
	flat_load_dwordx4 v[20:23], v[48:49]
	flat_load_dwordx4 v[24:27], v[50:51]
	v_ashrrev_i32_e32 v73, 31, v72
	v_lshlrev_b64 v[78:79], 12, v[72:73]
	v_lshl_add_u64 v[110:111], v[72:73], 2, v[32:33]
	v_lshl_add_u64 v[112:113], v[38:39], 0, v[78:79]
	flat_load_dword v71, v[110:111]
	flat_load_dwordx4 v[28:31], v[112:113]
	flat_load_dwordx4 v[74:77], v[112:113] offset:1024
	flat_load_dwordx4 v[104:107], v[112:113] offset:2048
	flat_load_dwordx4 v[114:117], v[52:53]
	flat_load_dwordx4 v[118:121], v[112:113] offset:3072
	v_lshl_add_u64 v[78:79], v[36:37], 0, v[78:79]
	flat_load_dwordx4 v[122:125], v[78:79] offset:3072
	flat_load_dwordx4 v[140:143], v[78:79] offset:2048
	flat_load_dwordx4 v[144:147], v[78:79] offset:1024
	flat_load_dwordx4 v[148:151], v[78:79]
	s_waitcnt vmcnt(0) lgkmcnt(0)
	v_rcp_f32_e32 v100, v0
	v_rcp_f32_e32 v101, v1
	v_rcp_f32_e32 v92, v8
	v_rcp_f32_e32 v88, v12
	v_rcp_f32_e32 v89, v13
	v_rcp_f32_e32 v80, v20
	v_rcp_f32_e32 v78, v24
	v_rcp_f32_e32 v79, v25
	v_lshlrev_b32_e32 v0, 16, v28
	v_and_b32_e32 v1, 0xffff0000, v28
	v_pk_mul_f32 v[24:25], v[100:101], v[0:1]
	v_lshlrev_b32_e32 v0, 16, v118
	v_and_b32_e32 v1, 0xffff0000, v118
	v_rcp_f32_e32 v81, v21
	v_rcp_f32_e32 v82, v22
	v_rcp_f32_e32 v83, v23
	v_lshlrev_b32_e32 v20, 16, v106
	v_and_b32_e32 v21, 0xffff0000, v106
	v_lshlrev_b32_e32 v22, 16, v107
	v_and_b32_e32 v23, 0xffff0000, v107
	v_rcp_f32_e32 v106, v116
	v_rcp_f32_e32 v107, v117
	v_pk_mul_f32 v[116:117], v[78:79], v[0:1]
	v_and_b32_e32 v0, 64, v171
	v_rcp_f32_e32 v128, v71
	v_add_u32_e32 v71, 64, v0
	v_xor_b32_e32 v0, 1, v171
	v_cmp_lt_i32_e32 vcc, v0, v71
	v_rcp_f32_e32 v108, v26
	v_rcp_f32_e32 v109, v27
	v_cndmask_b32_e32 v0, v171, v0, vcc
	v_and_b32_e32 v27, 0xffff0000, v149
	v_and_b32_e32 v26, 0xffff0000, v148
	v_rcp_f32_e32 v90, v14
	v_rcp_f32_e32 v91, v15
	v_pk_mul_f32 v[176:177], v[82:83], v[22:23]
	v_lshlrev_b32_e32 v73, 2, v0
	v_lshlrev_b32_e32 v23, 16, v149
	v_lshlrev_b32_e32 v22, 16, v148
	v_pk_mul_f32 v[0:1], v[26:27], v[26:27]
	v_lshlrev_b32_e32 v12, 16, v76
	v_and_b32_e32 v13, 0xffff0000, v76
	v_pk_mul_f32 v[168:169], v[80:81], v[20:21]
	v_lshlrev_b32_e32 v20, 16, v119
	v_and_b32_e32 v21, 0xffff0000, v119
	v_pk_fma_f32 v[0:1], v[22:23], v[22:23], v[0:1]
	v_and_b32_e32 v119, 0xffff0000, v151
	v_and_b32_e32 v118, 0xffff0000, v150
	v_rcp_f32_e32 v84, v16
	v_rcp_f32_e32 v85, v17
	v_rcp_f32_e32 v86, v18
	v_rcp_f32_e32 v87, v19
	v_lshlrev_b32_e32 v16, 16, v104
	v_and_b32_e32 v17, 0xffff0000, v104
	v_lshlrev_b32_e32 v18, 16, v105
	v_and_b32_e32 v19, 0xffff0000, v105
	v_pk_mul_f32 v[162:163], v[88:89], v[12:13]
	v_rcp_f32_e32 v104, v114
	v_rcp_f32_e32 v105, v115
	v_pk_add_f32 v[12:13], v[0:1], v[0:1] op_sel_hi:[0,1]
	v_lshlrev_b32_e32 v115, 16, v151
	v_lshlrev_b32_e32 v114, 16, v150
	v_pk_mul_f32 v[0:1], v[118:119], v[118:119]
	v_lshlrev_b32_e32 v14, 16, v77
	v_and_b32_e32 v15, 0xffff0000, v77
	v_pk_fma_f32 v[0:1], v[114:115], v[114:115], v[0:1]
	v_and_b32_e32 v181, 0xffff0000, v145
	v_and_b32_e32 v180, 0xffff0000, v144
	v_pk_mul_f32 v[160:161], v[90:91], v[14:15]
	v_pk_add_f32 v[14:15], v[0:1], v[0:1] op_sel_hi:[0,1]
	v_lshlrev_b32_e32 v179, 16, v145
	v_lshlrev_b32_e32 v178, 16, v144
	v_pk_mul_f32 v[0:1], v[180:181], v[180:181]
	v_rcp_f32_e32 v93, v9
	v_pk_fma_f32 v[0:1], v[178:179], v[178:179], v[0:1]
	v_and_b32_e32 v185, 0xffff0000, v147
	v_and_b32_e32 v184, 0xffff0000, v146
	v_rcp_f32_e32 v94, v10
	v_rcp_f32_e32 v95, v11
	v_pk_mul_f32 v[164:165], v[84:85], v[16:17]
	v_pk_add_f32 v[16:17], v[0:1], v[0:1] op_sel_hi:[0,1]
	v_lshlrev_b32_e32 v183, 16, v147
	v_lshlrev_b32_e32 v182, 16, v146
	v_pk_mul_f32 v[0:1], v[184:185], v[184:185]
	v_lshlrev_b32_e32 v186, 16, v140
	v_pk_fma_f32 v[0:1], v[182:183], v[182:183], v[0:1]
	v_lshlrev_b32_e32 v8, 16, v74
	v_and_b32_e32 v9, 0xffff0000, v74
	v_pk_mul_f32 v[166:167], v[86:87], v[18:19]
	v_pk_add_f32 v[18:19], v[0:1], v[0:1] op_sel_hi:[0,1]
	v_and_b32_e32 v187, 0xffff0000, v140
	v_mul_f32_e32 v0, v186, v186
	v_lshlrev_b32_e32 v188, 16, v141
	v_lshlrev_b32_e32 v10, 16, v75
	v_and_b32_e32 v11, 0xffff0000, v75
	v_pk_mul_f32 v[158:159], v[92:93], v[8:9]
	v_pk_fma_f32 v[8:9], v[186:187], v[186:187], v[0:1] op_sel_hi:[1,1,0]
	v_and_b32_e32 v189, 0xffff0000, v141
	v_mul_f32_e32 v0, v188, v188
	v_lshlrev_b32_e32 v190, 16, v142
	v_pk_mul_f32 v[156:157], v[94:95], v[10:11]
	v_pk_fma_f32 v[10:11], v[188:189], v[188:189], v[0:1] op_sel_hi:[1,1,0]
	v_and_b32_e32 v191, 0xffff0000, v142
	v_mul_f32_e32 v0, v190, v190
	v_lshlrev_b32_e32 v192, 16, v143
	v_rcp_f32_e32 v102, v2
	v_rcp_f32_e32 v103, v3
	v_lshlrev_b32_e32 v2, 16, v29
	v_and_b32_e32 v3, 0xffff0000, v29
	v_pk_fma_f32 v[28:29], v[190:191], v[190:191], v[0:1] op_sel_hi:[1,1,0]
	v_and_b32_e32 v193, 0xffff0000, v143
	v_mul_f32_e32 v0, v192, v192
	v_rcp_f32_e32 v96, v4
	v_rcp_f32_e32 v97, v5
	v_rcp_f32_e32 v98, v6
	v_rcp_f32_e32 v99, v7
	v_lshlrev_b32_e32 v4, 16, v30
	v_and_b32_e32 v5, 0xffff0000, v30
	v_lshlrev_b32_e32 v6, 16, v31
	v_and_b32_e32 v7, 0xffff0000, v31
	v_pk_fma_f32 v[30:31], v[192:193], v[192:193], v[0:1] op_sel_hi:[1,1,0]
	v_lshlrev_b32_e32 v194, 16, v122
	v_and_b32_e32 v195, 0xffff0000, v122
	v_lshlrev_b32_e32 v196, 16, v123
	v_and_b32_e32 v197, 0xffff0000, v123
	v_lshlrev_b32_e32 v198, 16, v124
	v_and_b32_e32 v199, 0xffff0000, v124
	v_lshlrev_b32_e32 v200, 16, v125
	v_and_b32_e32 v201, 0xffff0000, v125
	v_mul_f32_e32 v8, v194, v194
	v_mul_f32_e32 v10, v195, v195
	v_mul_f32_e32 v28, v196, v196
	v_mul_f32_e32 v30, v197, v197
	v_mul_f32_e32 v16, v198, v198
	v_mul_f32_e32 v18, v199, v199
	v_mul_f32_e32 v12, v200, v200
	v_mul_f32_e32 v14, v201, v201
	v_pk_add_f32 v[74:75], v[8:9], v[10:11]
	v_pk_add_f32 v[28:29], v[28:29], v[30:31]
	v_pk_add_f32 v[16:17], v[16:17], v[18:19]
	v_pk_add_f32 v[12:13], v[12:13], v[14:15]
	v_pk_add_f32 v[28:29], v[74:75], v[28:29]
	v_pk_add_f32 v[12:13], v[16:17], v[12:13]
	v_pk_mul_f32 v[126:127], v[102:103], v[2:3]
	flat_load_dwordx4 v[0:3], v[42:43]
	v_pk_add_f32 v[12:13], v[28:29], v[12:13]
	v_pk_mul_f32 v[152:153], v[98:99], v[6:7]
	v_add_f32_e32 v16, v12, v13
	ds_bpermute_b32 v17, v73, v16
	v_pk_mul_f32 v[154:155], v[96:97], v[4:5]
	flat_load_dwordx4 v[4:7], v[42:43] offset:16
	v_xor_b32_e32 v76, 2, v171
	v_cmp_lt_i32_e32 vcc, v76, v71
	flat_load_dwordx4 v[8:11], v[42:43] offset:2048
	flat_load_dwordx4 v[12:15], v[42:43] offset:2064
	v_cndmask_b32_e32 v18, v171, v76, vcc
	v_lshlrev_b32_e32 v142, 2, v18
	s_waitcnt lgkmcnt(0)
; __device__ __forceinline__ float dot4(f32x4 a) { return (a.x * a.x + a.y * a.y) + (a.z * a.z + a.w * a.w); }
; __device__ __forceinline__ f32x4 bf4lo(u32x4 w) { return (f32x4){bflo(w.x), bfhi(w.x), bflo(w.y), bfhi(w.y)}; }
; __device__ __forceinline__ f32x4 bf4hi(u32x4 w) { return (f32x4){bflo(w.z), bfhi(w.z), bflo(w.w), bfhi(w.w)}; }
; __device__ __forceinline__ void normres_phase(const bf16_t* hf, const float* xsrc, const float* gprev, bf16_t* HI, bf16_t* LO, float* RS, float* xdst, const float* gpost, float w, const float* gpre, ...
;     ...
;         for (int q = 0; q < 2; ++q) { if (q == 1 && !two) break; const int rr = q ? rowb : row;
;             float ss = 0.f;
; #pragma unroll
;             for (int c = 0; c < 4; ++c) ss += dot4(bf4lo(hw[q][c])) + dot4(bf4hi(hw[q][c]));
;             const float rs = rsqrtf(wave_sum(ss) * (1.f / D) + EPS) * w; float ss2 = 0.f;
;             const f32x4* gp4 = (const f32x4*)gpost + 2 * lane;
; #pragma unroll
;             for (int c = 0; c < 4; ++c) { xv[q][2 * c] = xv[q][2 * c] + bf4lo(hw[q][c]) * rs * gp4[128 * c]; xv[q][2 * c + 1] = xv[q][2 * c + 1] + bf4hi(hw[q][c]) * rs * gp4[128 * c + 1];
;                 ss2 += dot4(xv[q][2 * c]) + dot4(xv[q][2 * c + 1]); }
	v_add_f32_e32 v29, v16, v17
	ds_bpermute_b32 v30, v142, v29
	v_xor_b32_e32 v28, 4, v171
	flat_load_dwordx4 v[16:19], v[54:55]
	v_cmp_lt_i32_e32 vcc, v28, v71
	v_xor_b32_e32 v74, 8, v171
	s_waitcnt lgkmcnt(0)
	v_add_f32_e32 v122, v29, v30
	v_cndmask_b32_e32 v28, v171, v28, vcc
	v_lshlrev_b32_e32 v143, 2, v28
	flat_load_dwordx4 v[28:31], v[56:57]
	v_cmp_lt_i32_e32 vcc, v74, v71
	flat_load_dwordx4 v[148:151], v[60:61]
	ds_bpermute_b32 v123, v143, v122
	v_cndmask_b32_e32 v74, v171, v74, vcc
	v_lshlrev_b32_e32 v144, 2, v74
	flat_load_dwordx4 v[74:77], v[58:59]
	v_xor_b32_e32 v124, 16, v171
	s_waitcnt lgkmcnt(0)
	v_add_f32_e32 v122, v122, v123
	ds_bpermute_b32 v123, v144, v122
	v_cmp_lt_i32_e32 vcc, v124, v71
	v_pk_mul_f32 v[202:203], v[108:109], v[20:21]
	v_lshlrev_b32_e32 v20, 16, v120
	v_cndmask_b32_e32 v124, v171, v124, vcc
	v_lshlrev_b32_e32 v145, 2, v124
	s_waitcnt lgkmcnt(0)
	v_add_f32_e32 v122, v122, v123
	ds_bpermute_b32 v123, v145, v122
	v_xor_b32_e32 v124, 32, v171
	v_cmp_lt_i32_e32 vcc, v124, v71
	v_and_b32_e32 v21, 0xffff0000, v120
	v_pk_mul_f32 v[204:205], v[104:105], v[20:21]
	v_cndmask_b32_e32 v71, v171, v124, vcc
	v_lshlrev_b32_e32 v146, 2, v71
	s_waitcnt lgkmcnt(0)
	v_add_f32_e32 v71, v122, v123
	ds_bpermute_b32 v122, v146, v71
	v_mov_b32_e32 v21, v26
	v_mov_b32_e32 v26, v23
	v_lshlrev_b32_e32 v120, 16, v121
	v_and_b32_e32 v121, 0xffff0000, v121
	s_waitcnt lgkmcnt(0)
	v_add_f32_e32 v71, v71, v122
	v_mov_b32_e32 v130, 0x358637bd
	v_fmamk_f32 v71, v71, 0x3a000000, v130
	v_mul_f32_e32 v122, 0x4b800000, v71
	v_cmp_gt_f32_e32 vcc, s92, v71
	v_pk_mul_f32 v[120:121], v[106:107], v[120:121]
	s_nop 0
	v_cndmask_b32_e32 v71, v71, v122, vcc
	v_rsq_f32_e32 v71, v71
	s_nop 0
	v_mul_f32_e32 v20, 0x45800000, v71
	v_cndmask_b32_e32 v206, v71, v20, vcc
	v_mov_b32_e32 v20, v22
	v_pk_mul_f32 v[20:21], v[206:207], v[20:21] op_sel_hi:[0,1]
	v_pk_mul_f32 v[22:23], v[206:207], v[26:27] op_sel_hi:[0,1]
	v_ashrrev_i32_e32 v71, 31, v70
	s_waitcnt vmcnt(0)
	v_pk_mul_f32 v[0:1], v[0:1], v[20:21]
	s_nop 0
	v_pk_fma_f32 v[24:25], v[128:129], v[24:25], v[0:1] op_sel_hi:[0,1,1]
	v_mov_b32_e32 v0, v114
	v_mov_b32_e32 v1, v118
	v_pk_mul_f32 v[0:1], v[206:207], v[0:1] op_sel_hi:[0,1]
	v_pk_mul_f32 v[2:3], v[2:3], v[22:23]
	v_mov_b32_e32 v118, v115
	v_pk_mul_f32 v[0:1], v[4:5], v[0:1]
	v_pk_fma_f32 v[26:27], v[128:129], v[126:127], v[2:3] op_sel_hi:[0,1,1]
	v_pk_mul_f32 v[2:3], v[206:207], v[118:119] op_sel_hi:[0,1]
	v_pk_fma_f32 v[126:127], v[128:129], v[154:155], v[0:1] op_sel_hi:[0,1,1]
	v_mov_b32_e32 v0, v178
	v_mov_b32_e32 v1, v180
	v_pk_mul_f32 v[2:3], v[6:7], v[2:3]
	v_pk_mul_f32 v[0:1], v[206:207], v[0:1] op_sel_hi:[0,1]
	v_mov_b32_e32 v180, v179
	v_pk_fma_f32 v[140:141], v[128:129], v[152:153], v[2:3] op_sel_hi:[0,1,1]
	v_pk_mul_f32 v[2:3], v[206:207], v[180:181] op_sel_hi:[0,1]
	v_pk_mul_f32 v[0:1], v[8:9], v[0:1]
	v_pk_mul_f32 v[2:3], v[10:11], v[2:3]
	v_pk_fma_f32 v[20:21], v[128:129], v[158:159], v[0:1] op_sel_hi:[0,1,1]
	v_mov_b32_e32 v0, v182
	v_mov_b32_e32 v1, v184
	v_mov_b32_e32 v184, v183
	v_pk_fma_f32 v[22:23], v[128:129], v[156:157], v[2:3] op_sel_hi:[0,1,1]
	v_pk_mul_f32 v[0:1], v[206:207], v[0:1] op_sel_hi:[0,1]
	v_pk_mul_f32 v[2:3], v[206:207], v[184:185] op_sel_hi:[0,1]
	v_pk_mul_f32 v[2:3], v[14:15], v[2:3]
	v_pk_mul_f32 v[0:1], v[12:13], v[0:1]
	v_pk_fma_f32 v[124:125], v[128:129], v[160:161], v[2:3] op_sel_hi:[0,1,1]
	v_pk_fma_f32 v[122:123], v[128:129], v[162:163], v[0:1] op_sel_hi:[0,1,1]
	v_pk_mul_f32 v[0:1], v[206:207], v[188:189] op_sel_hi:[0,1]
	v_pk_mul_f32 v[2:3], v[206:207], v[186:187] op_sel_hi:[0,1]
	v_pk_mul_f32 v[2:3], v[16:17], v[2:3]
	v_pk_mul_f32 v[0:1], v[18:19], v[0:1]
	v_pk_fma_f32 v[18:19], v[128:129], v[164:165], v[2:3] op_sel_hi:[0,1,1]
	v_pk_fma_f32 v[16:17], v[128:129], v[166:167], v[0:1] op_sel_hi:[0,1,1]
	v_pk_mul_f32 v[0:1], v[206:207], v[192:193] op_sel_hi:[0,1]
	v_pk_mul_f32 v[2:3], v[206:207], v[190:191] op_sel_hi:[0,1]
	v_pk_mul_f32 v[2:3], v[28:29], v[2:3]
	v_pk_mul_f32 v[0:1], v[30:31], v[0:1]
	v_pk_fma_f32 v[30:31], v[128:129], v[168:169], v[2:3] op_sel_hi:[0,1,1]
	v_pk_fma_f32 v[28:29], v[128:129], v[176:177], v[0:1] op_sel_hi:[0,1,1]
	v_pk_mul_f32 v[0:1], v[206:207], v[196:197] op_sel_hi:[0,1]
	v_pk_mul_f32 v[2:3], v[206:207], v[194:195] op_sel_hi:[0,1]
	v_pk_mul_f32 v[2:3], v[74:75], v[2:3]
	v_pk_mul_f32 v[0:1], v[76:77], v[0:1]
	v_pk_fma_f32 v[116:117], v[128:129], v[116:117], v[2:3] op_sel_hi:[0,1,1]
	v_pk_fma_f32 v[114:115], v[128:129], v[202:203], v[0:1] op_sel_hi:[0,1,1]
	v_pk_mul_f32 v[0:1], v[206:207], v[200:201] op_sel_hi:[0,1]
	v_pk_mul_f32 v[2:3], v[206:207], v[198:199] op_sel_hi:[0,1]
	v_pk_mul_f32 v[2:3], v[148:149], v[2:3]
	v_pk_mul_f32 v[0:1], v[150:151], v[0:1]
	v_pk_mul_f32 v[14:15], v[124:125], v[124:125]
	v_pk_fma_f32 v[118:119], v[128:129], v[120:121], v[0:1] op_sel_hi:[0,1,1]
	v_pk_fma_f32 v[120:121], v[128:129], v[204:205], v[2:3] op_sel_hi:[0,1,1]
	v_pk_mul_f32 v[0:1], v[26:27], v[26:27]
	v_pk_mul_f32 v[2:3], v[24:25], v[24:25]
	v_pk_mul_f32 v[74:75], v[122:123], v[122:123]
	v_pk_mov_b32 v[4:5], v[2:3], v[0:1] op_sel:[1,0]
	v_mov_b32_e32 v3, v1
	v_pk_add_f32 v[0:1], v[4:5], v[2:3]
	v_pk_mul_f32 v[2:3], v[126:127], v[126:127]
	v_pk_add_f32 v[8:9], v[0:1], v[0:1] op_sel_hi:[0,1]
	v_pk_mul_f32 v[0:1], v[140:141], v[140:141]
	v_pk_mov_b32 v[76:77], v[74:75], v[14:15] op_sel:[1,0]
	v_pk_mov_b32 v[4:5], v[2:3], v[0:1] op_sel:[1,0]
	v_mov_b32_e32 v3, v1
	v_pk_add_f32 v[0:1], v[4:5], v[2:3]
	v_pk_mul_f32 v[2:3], v[20:21], v[20:21]
	v_pk_add_f32 v[10:11], v[0:1], v[0:1] op_sel_hi:[0,1]
	v_pk_mul_f32 v[0:1], v[22:23], v[22:23]
	v_mov_b32_e32 v75, v15
	v_pk_mov_b32 v[4:5], v[2:3], v[0:1] op_sel:[1,0]
; __device__ __forceinline__ float dot4(f32x4 a) { return (a.x * a.x + a.y * a.y) + (a.z * a.z + a.w * a.w); }
; __device__ __forceinline__ f32x4 bf4lo(u32x4 w) { return (f32x4){bflo(w.x), bfhi(w.x), bflo(w.y), bfhi(w.y)}; }
; __device__ __forceinline__ f32x4 bf4hi(u32x4 w) { return (f32x4){bflo(w.z), bfhi(w.z), bflo(w.w), bfhi(w.w)}; }
; __device__ __forceinline__ void normres_phase(const bf16_t* hf, const float* xsrc, const float* gprev, bf16_t* HI, bf16_t* LO, float* RS, float* xdst, const float* gpost, float w, const float* gpre, ...
;     ...
;             for (int c = 0; c < 4; ++c) { xv[q][2 * c] = xv[q][2 * c] + bf4lo(hw[q][c]) * rs * gp4[128 * c]; xv[q][2 * c + 1] = xv[q][2 * c + 1] + bf4hi(hw[q][c]) * rs * gp4[128 * c + 1];
;                 ss2 += dot4(xv[q][2 * c]) + dot4(xv[q][2 * c + 1]); }
;             if (xdst) {
;                 f32x4* xo = (f32x4*)(xdst + (size_t)rr * D) + 2 * lane;
; #pragma unroll
;                 for (int c = 0; c < 4; ++c) { xo[128 * c] = xv[q][2 * c]; xo[128 * c + 1] = xv[q][2 * c + 1]; }
;             } else {
;                 const float rs2 = rsqrtf(wave_sum(ss2) * (1.f / D) + EPS);
;                 const f32x4* gn4 = (const f32x4*)gpre + 2 * lane; u32x4* oh = (u32x4*)(HI + (size_t)rr * D) + lane;
; #pragma unroll
;                 for (int c = 0; c < 4; ++c) { const f32x4 y0 = xv[q][2 * c] * rs2 * gn4[128 * c], y1 = xv[q][2 * c + 1] * rs2 * gn4[128 * c + 1];
;                     oh[64 * c] = (u32x4){pk2(y0.x, y0.y), pk2(y0.z, y0.w), pk2(y1.x, y1.y), pk2(y1.z, y1.w)}; }
;                 if (lane == 0) RS[rr] = rs2;
	v_mov_b32_e32 v3, v1
	v_pk_add_f32 v[0:1], v[4:5], v[2:3]
	flat_load_dwordx4 v[4:7], v[44:45]
	v_pk_add_f32 v[12:13], v[0:1], v[0:1] op_sel_hi:[0,1]
	flat_load_dwordx4 v[0:3], v[44:45] offset:16
	v_mul_f32_e32 v8, v18, v18
	v_pk_add_f32 v[14:15], v[76:77], v[74:75]
	v_pk_fma_f32 v[74:75], v[18:19], v[18:19], v[8:9] op_sel_hi:[1,1,0]
	v_mul_f32_e32 v8, v16, v16
	v_pk_fma_f32 v[76:77], v[16:17], v[16:17], v[8:9] op_sel_hi:[1,1,0]
	v_mul_f32_e32 v8, v30, v30
	v_pk_fma_f32 v[148:149], v[30:31], v[30:31], v[8:9] op_sel_hi:[1,1,0]
	v_mul_f32_e32 v8, v28, v28
	v_pk_add_f32 v[14:15], v[14:15], v[14:15] op_sel_hi:[0,1]
	v_pk_fma_f32 v[150:151], v[28:29], v[28:29], v[8:9] op_sel_hi:[1,1,0]
	v_mul_f32_e32 v74, v116, v116
	v_mul_f32_e32 v76, v117, v117
	v_mul_f32_e32 v148, v114, v114
	v_mul_f32_e32 v150, v115, v115
	v_mul_f32_e32 v8, v120, v120
	v_mul_f32_e32 v10, v121, v121
	v_mul_f32_e32 v12, v118, v118
	v_mul_f32_e32 v14, v119, v119
	v_pk_add_f32 v[74:75], v[74:75], v[76:77]
	v_pk_add_f32 v[76:77], v[148:149], v[150:151]
	v_pk_add_f32 v[8:9], v[8:9], v[10:11]
	v_pk_add_f32 v[10:11], v[12:13], v[14:15]
	v_pk_add_f32 v[74:75], v[74:75], v[76:77]
	v_pk_add_f32 v[8:9], v[8:9], v[10:11]
	v_lshlrev_b64 v[12:13], 12, v[70:71]
	v_pk_add_f32 v[8:9], v[74:75], v[8:9]
	v_lshl_add_u64 v[74:75], v[38:39], 0, v[12:13]
	v_add_f32_e32 v8, v8, v9
	ds_bpermute_b32 v9, v73, v8
	v_lshl_add_u64 v[76:77], v[70:71], 2, v[32:33]
	v_lshl_add_u64 v[152:153], v[36:37], 0, v[12:13]
	flat_load_dword v71, v[76:77]
	s_waitcnt lgkmcnt(0)
	v_add_f32_e32 v8, v8, v9
	ds_bpermute_b32 v9, v142, v8
	s_waitcnt lgkmcnt(0)
	v_add_f32_e32 v8, v8, v9
	ds_bpermute_b32 v9, v143, v8
	s_waitcnt lgkmcnt(0)
	v_add_f32_e32 v8, v8, v9
	ds_bpermute_b32 v9, v144, v8
	s_waitcnt lgkmcnt(0)
	v_add_f32_e32 v8, v8, v9
	ds_bpermute_b32 v9, v145, v8
	s_waitcnt lgkmcnt(0)
	v_add_f32_e32 v14, v8, v9
	ds_bpermute_b32 v15, v146, v14
	flat_load_dwordx4 v[8:11], v[74:75]
	s_waitcnt lgkmcnt(0)
	v_add_f32_e32 v14, v14, v15
	v_mov_b32_e32 v130, 0x358637bd
	v_fmamk_f32 v14, v14, 0x3a000000, v130
	v_mul_f32_e32 v15, 0x4b800000, v14
	v_cmp_gt_f32_e32 vcc, s92, v14
	s_nop 1
	v_cndmask_b32_e32 v14, v14, v15, vcc
	v_rsq_f32_e32 v128, v14
	flat_load_dwordx4 v[12:15], v[152:153]
	v_mul_f32_e32 v147, 0x45800000, v128
	v_cndmask_b32_e32 v128, v128, v147, vcc
	v_pk_mul_f32 v[24:25], v[24:25], v[128:129] op_sel_hi:[1,0]
	v_pk_mul_f32 v[26:27], v[26:27], v[128:129] op_sel_hi:[1,0]
	s_waitcnt vmcnt(0)
	v_pk_mul_f32 v[4:5], v[4:5], v[24:25]
	v_pk_mul_f32 v[6:7], v[6:7], v[26:27]
	v_pk_mul_f32 v[24:25], v[126:127], v[128:129] op_sel_hi:[1,0]
	v_pk_mul_f32 v[26:27], v[140:141], v[128:129] op_sel_hi:[1,0]
	v_pk_mul_f32 v[20:21], v[20:21], v[128:129] op_sel_hi:[1,0]
	v_pk_mul_f32 v[26:27], v[2:3], v[26:27]
	v_pk_mul_f32 v[2:3], v[0:1], v[24:25]
	v_cvt_pk_bf16_f32 v0, v4, v5
	v_cvt_pk_bf16_f32 v1, v6, v7
	v_cvt_pk_bf16_f32 v2, v2, v3
	v_cvt_pk_bf16_f32 v3, v26, v27
	flat_store_dwordx4 v[112:113], v[0:3]
	flat_load_dwordx4 v[0:3], v[44:45] offset:2048
	s_nop 0
	flat_load_dwordx4 v[148:151], v[44:45] offset:2064
	flat_load_dwordx4 v[4:7], v[152:153] offset:1024
	flat_load_dwordx4 v[24:27], v[74:75] offset:1024
	v_pk_mul_f32 v[22:23], v[22:23], v[128:129] op_sel_hi:[1,0]
	v_pk_mul_f32 v[18:19], v[18:19], v[128:129] op_sel_hi:[1,0]
	v_pk_mul_f32 v[16:17], v[16:17], v[128:129] op_sel_hi:[1,0]
	v_pk_mul_f32 v[28:29], v[28:29], v[128:129] op_sel_hi:[1,0]
	v_pk_mul_f32 v[116:117], v[116:117], v[128:129] op_sel_hi:[1,0]
	v_pk_mul_f32 v[114:115], v[114:115], v[128:129] op_sel_hi:[1,0]
	v_pk_mul_f32 v[120:121], v[120:121], v[128:129] op_sel_hi:[1,0]
	v_pk_mul_f32 v[118:119], v[118:119], v[128:129] op_sel_hi:[1,0]
	s_waitcnt vmcnt(0) lgkmcnt(0)
	v_pk_mul_f32 v[2:3], v[2:3], v[22:23]
	v_pk_mul_f32 v[0:1], v[0:1], v[20:21]
	v_pk_mul_f32 v[20:21], v[122:123], v[128:129] op_sel_hi:[1,0]
	v_pk_mul_f32 v[22:23], v[124:125], v[128:129] op_sel_hi:[1,0]
	v_pk_mul_f32 v[20:21], v[148:149], v[20:21]
	v_pk_mul_f32 v[22:23], v[150:151], v[22:23]
	v_cvt_pk_bf16_f32 v0, v0, v1
	v_cvt_pk_bf16_f32 v1, v2, v3
	v_cvt_pk_bf16_f32 v2, v20, v21
	v_cvt_pk_bf16_f32 v3, v22, v23
	flat_store_dwordx4 v[112:113], v[0:3] offset:1024
	flat_load_dwordx4 v[122:125], v[62:63]
	flat_load_dwordx4 v[148:151], v[64:65]
	flat_load_dwordx4 v[20:23], v[74:75] offset:2048
	s_nop 0
	flat_load_dwordx4 v[0:3], v[152:153] offset:2048
	s_waitcnt vmcnt(0) lgkmcnt(0)
	v_pk_mul_f32 v[124:125], v[124:125], v[16:17]
	v_pk_mul_f32 v[16:17], v[122:123], v[18:19]
	v_pk_mul_f32 v[18:19], v[30:31], v[128:129] op_sel_hi:[1,0]
	v_pk_mul_f32 v[28:29], v[150:151], v[28:29]
	v_pk_mul_f32 v[18:19], v[148:149], v[18:19]
	v_cvt_pk_bf16_f32 v16, v16, v17
	v_cvt_pk_bf16_f32 v17, v124, v125
	v_cvt_pk_bf16_f32 v18, v18, v19
	v_cvt_pk_bf16_f32 v19, v28, v29
	flat_store_dwordx4 v[112:113], v[16:19] offset:2048
	flat_load_dwordx4 v[122:125], v[66:67]
	flat_load_dwordx4 v[148:151], v[68:69]
	flat_load_dwordx4 v[28:31], v[74:75] offset:3072
	s_nop 0
	flat_load_dwordx4 v[16:19], v[152:153] offset:3072
	s_waitcnt vmcnt(0) lgkmcnt(0)
	v_pk_mul_f32 v[124:125], v[124:125], v[114:115]
	v_pk_mul_f32 v[114:115], v[122:123], v[116:117]
	v_pk_mul_f32 v[118:119], v[150:151], v[118:119]
	v_pk_mul_f32 v[116:117], v[148:149], v[120:121]
	v_cvt_pk_bf16_f32 v114, v114, v115
	v_cvt_pk_bf16_f32 v115, v124, v125
	v_cvt_pk_bf16_f32 v116, v116, v117
	v_cvt_pk_bf16_f32 v117, v118, v119
	flat_store_dwordx4 v[112:113], v[114:117] offset:3072
	s_and_saveexec_b64 s[2:3], s[8:9]
	s_cbranch_execz .LBB0_504
	flat_store_dword v[110:111], v128
; __device__ __forceinline__ float dot4(f32x4 a) { return (a.x * a.x + a.y * a.y) + (a.z * a.z + a.w * a.w); }
; __device__ __forceinline__ f32x4 bf4lo(u32x4 w) { return (f32x4){bflo(w.x), bfhi(w.x), bflo(w.y), bfhi(w.y)}; }
; __device__ __forceinline__ f32x4 bf4hi(u32x4 w) { return (f32x4){bflo(w.z), bfhi(w.z), bflo(w.w), bfhi(w.w)}; }
; __device__ __forceinline__ f32x4 rcp4(f32x4 g) { return (f32x4){__builtin_amdgcn_rcpf(g.x), __builtin_amdgcn_rcpf(g.y), __builtin_amdgcn_rcpf(g.z), __builtin_amdgcn_rcpf(g.w)}; }
; __device__ __forceinline__ void normres_phase(const bf16_t* hf, const float* xsrc, const float* gprev, bf16_t* HI, bf16_t* LO, float* RS, float* xdst, const float* gpost, float w, const float* gpre, ...
;     ...
;             for (int c = 0; c < 4; ++c) { const f32x4 ig0 = rcp4(gv4[128 * c]), ig1 = rcp4(gv4[128 * c + 1]);
; #pragma unroll
;                 for (int q = 0; q < 2; ++q) { const float inv = __builtin_amdgcn_rcpf(rsp[q]);
;                     xv[q][2 * c] = bf4lo(hiw[q][c]) * ig0 * inv; xv[q][2 * c + 1] = bf4hi(hiw[q][c]) * ig1 * inv; } }
;         }
; #pragma unroll
;         for (int q = 0; q < 2; ++q) { if (q == 1 && !two) break; const int rr = q ? rowb : row;
;             float ss = 0.f;
; #pragma unroll
;             for (int c = 0; c < 4; ++c) ss += dot4(bf4lo(hw[q][c])) + dot4(bf4hi(hw[q][c]));
;             const float rs = rsqrtf(wave_sum(ss) * (1.f / D) + EPS) * w; float ss2 = 0.f;
;             const f32x4* gp4 = (const f32x4*)gpost + 2 * lane;
; #pragma unroll
;             for (int c = 0; c < 4; ++c) { xv[q][2 * c] = xv[q][2 * c] + bf4lo(hw[q][c]) * rs * gp4[128 * c]; xv[q][2 * c + 1] = xv[q][2 * c + 1] + bf4hi(hw[q][c]) * rs * gp4[128 * c + 1];
.LBB0_504:
	s_or_b64 exec, exec, s[2:3]
	s_mov_b64 s[2:3], 0
	s_and_saveexec_b64 s[16:17], s[12:13]
	s_cbranch_execz .LBB0_485
	v_lshlrev_b32_e32 v114, 16, v8
	v_and_b32_e32 v115, 0xffff0000, v8
	v_lshlrev_b32_e32 v8, 16, v9
	v_and_b32_e32 v9, 0xffff0000, v9
	v_pk_mul_f32 v[112:113], v[102:103], v[8:9]
	v_lshlrev_b32_e32 v8, 16, v10
	v_and_b32_e32 v9, 0xffff0000, v10
	v_lshlrev_b32_e32 v10, 16, v11
	v_and_b32_e32 v11, 0xffff0000, v11
	v_pk_mul_f32 v[102:103], v[96:97], v[8:9]
	v_lshlrev_b32_e32 v8, 16, v24
	v_and_b32_e32 v9, 0xffff0000, v24
	v_pk_mul_f32 v[114:115], v[100:101], v[114:115]
	v_pk_mul_f32 v[100:101], v[98:99], v[10:11]
	v_lshlrev_b32_e32 v10, 16, v25
	v_and_b32_e32 v11, 0xffff0000, v25
	v_pk_mul_f32 v[92:93], v[92:93], v[8:9]
	v_lshlrev_b32_e32 v8, 16, v26
	v_and_b32_e32 v9, 0xffff0000, v26
	v_pk_mul_f32 v[94:95], v[94:95], v[10:11]
	v_lshlrev_b32_e32 v10, 16, v27
	v_and_b32_e32 v11, 0xffff0000, v27
	v_pk_mul_f32 v[88:89], v[88:89], v[8:9]
	v_lshlrev_b32_e32 v8, 16, v20
	v_and_b32_e32 v9, 0xffff0000, v20
	v_pk_mul_f32 v[90:91], v[90:91], v[10:11]
	v_lshlrev_b32_e32 v10, 16, v21
	v_and_b32_e32 v11, 0xffff0000, v21
	v_pk_mul_f32 v[84:85], v[84:85], v[8:9]
	v_lshlrev_b32_e32 v8, 16, v22
	v_and_b32_e32 v9, 0xffff0000, v22
	v_pk_mul_f32 v[86:87], v[86:87], v[10:11]
	v_lshlrev_b32_e32 v10, 16, v23
	v_and_b32_e32 v11, 0xffff0000, v23
	v_pk_mul_f32 v[26:27], v[80:81], v[8:9]
	v_lshlrev_b32_e32 v8, 16, v28
	v_and_b32_e32 v9, 0xffff0000, v28
	v_and_b32_e32 v81, 0xffff0000, v13
	v_and_b32_e32 v80, 0xffff0000, v12
	v_pk_mul_f32 v[22:23], v[82:83], v[10:11]
	v_lshlrev_b32_e32 v10, 16, v29
	v_and_b32_e32 v11, 0xffff0000, v29
	v_pk_mul_f32 v[24:25], v[78:79], v[8:9]
	v_lshlrev_b32_e32 v79, 16, v13
	v_lshlrev_b32_e32 v78, 16, v12
	v_pk_mul_f32 v[12:13], v[80:81], v[80:81]
	v_pk_mul_f32 v[20:21], v[108:109], v[10:11]
	v_lshlrev_b32_e32 v8, 16, v30
	v_and_b32_e32 v9, 0xffff0000, v30
	v_lshlrev_b32_e32 v10, 16, v31
	v_and_b32_e32 v11, 0xffff0000, v31
	v_pk_fma_f32 v[12:13], v[78:79], v[78:79], v[12:13]
	v_and_b32_e32 v31, 0xffff0000, v15
	v_and_b32_e32 v30, 0xffff0000, v14
	v_pk_add_f32 v[82:83], v[12:13], v[12:13] op_sel_hi:[0,1]
	v_lshlrev_b32_e32 v29, 16, v15
	v_lshlrev_b32_e32 v28, 16, v14
	v_pk_mul_f32 v[12:13], v[30:31], v[30:31]
	v_lshlrev_b32_e32 v119, 16, v5
	v_pk_fma_f32 v[12:13], v[28:29], v[28:29], v[12:13]
	v_lshlrev_b32_e32 v118, 16, v4
	v_and_b32_e32 v5, 0xffff0000, v5
	v_and_b32_e32 v4, 0xffff0000, v4
	v_pk_add_f32 v[120:121], v[12:13], v[12:13] op_sel_hi:[0,1]
	v_pk_mul_f32 v[12:13], v[4:5], v[4:5]
	v_lshlrev_b32_e32 v14, 16, v1
	v_pk_fma_f32 v[12:13], v[118:119], v[118:119], v[12:13]
	v_pk_mul_f32 v[8:9], v[104:105], v[8:9]
	v_pk_add_f32 v[122:123], v[12:13], v[12:13] op_sel_hi:[0,1]
	v_lshlrev_b32_e32 v12, 16, v0
	v_and_b32_e32 v13, 0xffff0000, v0
	v_mul_f32_e32 v0, v12, v12
	v_pk_fma_f32 v[124:125], v[12:13], v[12:13], v[0:1] op_sel_hi:[1,1,0]
	v_and_b32_e32 v15, 0xffff0000, v1
	v_mul_f32_e32 v0, v14, v14
	v_lshlrev_b32_e32 v104, 16, v2
	v_pk_mul_f32 v[10:11], v[106:107], v[10:11]
	v_and_b32_e32 v117, 0xffff0000, v7
	v_and_b32_e32 v116, 0xffff0000, v6
	v_pk_fma_f32 v[126:127], v[14:15], v[14:15], v[0:1] op_sel_hi:[1,1,0]
	v_and_b32_e32 v105, 0xffff0000, v2
	v_mul_f32_e32 v0, v104, v104
	v_lshlrev_b32_e32 v106, 16, v3
	v_lshlrev_b32_e32 v109, 16, v7
	v_lshlrev_b32_e32 v108, 16, v6
	v_pk_mul_f32 v[6:7], v[116:117], v[116:117]
	v_pk_fma_f32 v[140:141], v[104:105], v[104:105], v[0:1] op_sel_hi:[1,1,0]
	v_and_b32_e32 v107, 0xffff0000, v3
	v_mul_f32_e32 v0, v106, v106
	v_pk_fma_f32 v[6:7], v[108:109], v[108:109], v[6:7]
	v_pk_fma_f32 v[148:149], v[106:107], v[106:107], v[0:1] op_sel_hi:[1,1,0]
	v_lshlrev_b32_e32 v96, 16, v16
	v_and_b32_e32 v97, 0xffff0000, v16
	v_lshlrev_b32_e32 v98, 16, v17
	v_and_b32_e32 v99, 0xffff0000, v17
	v_pk_add_f32 v[6:7], v[6:7], v[6:7] op_sel_hi:[0,1]
	v_mul_f32_e32 v124, v96, v96
	v_mul_f32_e32 v126, v97, v97
	v_mul_f32_e32 v140, v98, v98
	v_mul_f32_e32 v148, v99, v99
	v_lshlrev_b32_e32 v0, 16, v18
	v_and_b32_e32 v1, 0xffff0000, v18
	v_lshlrev_b32_e32 v2, 16, v19
	v_and_b32_e32 v3, 0xffff0000, v19
	v_mul_f32_e32 v122, v0, v0
	v_mul_f32_e32 v6, v1, v1
	v_mul_f32_e32 v82, v2, v2
	v_mul_f32_e32 v120, v3, v3
	v_pk_add_f32 v[16:17], v[124:125], v[126:127]
	v_pk_add_f32 v[18:19], v[140:141], v[148:149]
	v_pk_add_f32 v[6:7], v[122:123], v[6:7]
	v_pk_add_f32 v[16:17], v[16:17], v[18:19]
	v_pk_add_f32 v[18:19], v[82:83], v[120:121]
	v_rcp_f32_e32 v110, v71
	v_pk_add_f32 v[6:7], v[6:7], v[18:19]
	s_nop 0
	v_pk_add_f32 v[6:7], v[16:17], v[6:7]
	flat_load_dwordx4 v[16:19], v[42:43]
	v_add_f32_e32 v6, v6, v7
	ds_bpermute_b32 v7, v73, v6
	s_waitcnt lgkmcnt(0)
	v_add_f32_e32 v6, v6, v7
	ds_bpermute_b32 v7, v142, v6
	s_waitcnt lgkmcnt(0)
	v_add_f32_e32 v6, v6, v7
	ds_bpermute_b32 v7, v143, v6
	s_waitcnt lgkmcnt(0)
	v_add_f32_e32 v6, v6, v7
	ds_bpermute_b32 v7, v144, v6
	s_waitcnt lgkmcnt(0)
	v_add_f32_e32 v6, v6, v7
	ds_bpermute_b32 v7, v145, v6
	s_waitcnt lgkmcnt(0)
	v_add_f32_e32 v6, v6, v7
	ds_bpermute_b32 v7, v146, v6
	s_waitcnt lgkmcnt(0)
	v_add_f32_e32 v6, v6, v7
	v_mov_b32_e32 v130, 0x358637bd
	v_fmamk_f32 v6, v6, 0x3a000000, v130
	v_cmp_gt_f32_e32 vcc, s92, v6
	v_mul_f32_e32 v7, 0x4b800000, v6
	s_nop 0
	v_cndmask_b32_e32 v6, v6, v7, vcc
	v_rsq_f32_e32 v6, v6
	s_nop 0
	v_mul_f32_e32 v7, 0x45800000, v6
	v_cndmask_b32_e32 v82, v6, v7, vcc
	v_mov_b32_e32 v7, v80
	v_mov_b32_e32 v80, v79
	v_mov_b32_e32 v6, v78
	v_pk_mul_f32 v[78:79], v[82:83], v[80:81] op_sel_hi:[0,1]
	v_pk_mul_f32 v[6:7], v[82:83], v[6:7] op_sel_hi:[0,1]
	s_waitcnt vmcnt(0)
; __device__ __forceinline__ float dot4(f32x4 a) { return (a.x * a.x + a.y * a.y) + (a.z * a.z + a.w * a.w); }
; __device__ __forceinline__ f32x4 bf4lo(u32x4 w) { return (f32x4){bflo(w.x), bfhi(w.x), bflo(w.y), bfhi(w.y)}; }
; __device__ __forceinline__ f32x4 bf4hi(u32x4 w) { return (f32x4){bflo(w.z), bfhi(w.z), bflo(w.w), bfhi(w.w)}; }
; __device__ __forceinline__ void normres_phase(const bf16_t* hf, const float* xsrc, const float* gprev, bf16_t* HI, bf16_t* LO, float* RS, float* xdst, const float* gpost, float w, const float* gpre, ...
;     ...
;             const f32x4* gp4 = (const f32x4*)gpost + 2 * lane;
; #pragma unroll
;             for (int c = 0; c < 4; ++c) { xv[q][2 * c] = xv[q][2 * c] + bf4lo(hw[q][c]) * rs * gp4[128 * c]; xv[q][2 * c + 1] = xv[q][2 * c + 1] + bf4hi(hw[q][c]) * rs * gp4[128 * c + 1];
;                 ss2 += dot4(xv[q][2 * c]) + dot4(xv[q][2 * c + 1]); }
;             if (xdst) {
;                 f32x4* xo = (f32x4*)(xdst + (size_t)rr * D) + 2 * lane;
; #pragma unroll
;                 for (int c = 0; c < 4; ++c) { xo[128 * c] = xv[q][2 * c]; xo[128 * c + 1] = xv[q][2 * c + 1]; }
;             } else {
;                 const float rs2 = rsqrtf(wave_sum(ss2) * (1.f / D) + EPS);
	v_pk_mul_f32 v[18:19], v[18:19], v[78:79]
	v_pk_mul_f32 v[6:7], v[16:17], v[6:7]
	v_pk_fma_f32 v[80:81], v[110:111], v[112:113], v[18:19] op_sel_hi:[0,1,1]
	flat_load_dwordx4 v[16:19], v[42:43] offset:16
	v_pk_fma_f32 v[78:79], v[110:111], v[114:115], v[6:7] op_sel_hi:[0,1,1]
	v_mov_b32_e32 v6, v28
	v_mov_b32_e32 v7, v30
	v_pk_mul_f32 v[6:7], v[82:83], v[6:7] op_sel_hi:[0,1]
	v_mov_b32_e32 v30, v29
	v_pk_mul_f32 v[28:29], v[82:83], v[30:31] op_sel_hi:[0,1]
	s_waitcnt vmcnt(0) lgkmcnt(0)
	v_pk_mul_f32 v[6:7], v[16:17], v[6:7]
	v_pk_mul_f32 v[18:19], v[18:19], v[28:29]
	v_pk_fma_f32 v[28:29], v[110:111], v[102:103], v[6:7] op_sel_hi:[0,1,1]
	v_mov_b32_e32 v6, v118
	v_mov_b32_e32 v7, v4
	v_mov_b32_e32 v4, v119
	v_pk_fma_f32 v[30:31], v[110:111], v[100:101], v[18:19] op_sel_hi:[0,1,1]
	v_pk_mul_f32 v[16:17], v[82:83], v[6:7] op_sel_hi:[0,1]
	v_pk_mul_f32 v[18:19], v[82:83], v[4:5] op_sel_hi:[0,1]
	flat_load_dwordx4 v[4:7], v[42:43] offset:2048
	s_waitcnt vmcnt(0) lgkmcnt(0)
	v_pk_mul_f32 v[4:5], v[4:5], v[16:17]
	v_mov_b32_e32 v16, v108
	v_mov_b32_e32 v17, v116
	v_pk_mul_f32 v[6:7], v[6:7], v[18:19]
	v_pk_fma_f32 v[4:5], v[110:111], v[92:93], v[4:5] op_sel_hi:[0,1,1]
	v_pk_mul_f32 v[92:93], v[82:83], v[16:17] op_sel_hi:[0,1]
	flat_load_dwordx4 v[16:19], v[42:43] offset:2064
	v_mov_b32_e32 v116, v109
	v_pk_fma_f32 v[6:7], v[110:111], v[94:95], v[6:7] op_sel_hi:[0,1,1]
	v_pk_mul_f32 v[94:95], v[82:83], v[116:117] op_sel_hi:[0,1]
	s_waitcnt vmcnt(0) lgkmcnt(0)
	v_pk_mul_f32 v[18:19], v[18:19], v[94:95]
	v_pk_mul_f32 v[16:17], v[16:17], v[92:93]
	v_pk_fma_f32 v[18:19], v[110:111], v[90:91], v[18:19] op_sel_hi:[0,1,1]
	v_pk_fma_f32 v[16:17], v[110:111], v[88:89], v[16:17] op_sel_hi:[0,1,1]
	v_pk_mul_f32 v[88:89], v[82:83], v[14:15] op_sel_hi:[0,1]
	v_pk_mul_f32 v[90:91], v[82:83], v[12:13] op_sel_hi:[0,1]
	flat_load_dwordx4 v[12:15], v[54:55]
	s_waitcnt vmcnt(0) lgkmcnt(0)
	v_pk_mul_f32 v[90:91], v[12:13], v[90:91]
	v_pk_mul_f32 v[12:13], v[14:15], v[88:89]
	v_pk_fma_f32 v[14:15], v[110:111], v[84:85], v[90:91] op_sel_hi:[0,1,1]
	v_pk_fma_f32 v[12:13], v[110:111], v[86:87], v[12:13] op_sel_hi:[0,1,1]
	flat_load_dwordx4 v[84:87], v[56:57]
	v_pk_mul_f32 v[88:89], v[82:83], v[106:107] op_sel_hi:[0,1]
	v_pk_mul_f32 v[90:91], v[82:83], v[104:105] op_sel_hi:[0,1]
	s_waitcnt vmcnt(0) lgkmcnt(0)
	v_pk_mul_f32 v[84:85], v[84:85], v[90:91]
	v_pk_mul_f32 v[86:87], v[86:87], v[88:89]
	v_pk_fma_f32 v[26:27], v[110:111], v[26:27], v[84:85] op_sel_hi:[0,1,1]
	v_pk_fma_f32 v[22:23], v[110:111], v[22:23], v[86:87] op_sel_hi:[0,1,1]
	flat_load_dwordx4 v[84:87], v[58:59]
	v_pk_mul_f32 v[90:91], v[82:83], v[96:97] op_sel_hi:[0,1]
	v_pk_mul_f32 v[88:89], v[82:83], v[98:99] op_sel_hi:[0,1]
	s_waitcnt vmcnt(0) lgkmcnt(0)
	v_pk_mul_f32 v[84:85], v[84:85], v[90:91]
	s_nop 0
	v_pk_fma_f32 v[24:25], v[110:111], v[24:25], v[84:85] op_sel_hi:[0,1,1]
	v_pk_mul_f32 v[84:85], v[82:83], v[2:3] op_sel_hi:[0,1]
	v_pk_mul_f32 v[82:83], v[82:83], v[0:1] op_sel_hi:[0,1]
	flat_load_dwordx4 v[0:3], v[60:61]
	v_pk_mul_f32 v[86:87], v[86:87], v[88:89]
	s_waitcnt vmcnt(0) lgkmcnt(0)
	v_pk_mul_f32 v[82:83], v[0:1], v[82:83]
	v_pk_mul_f32 v[0:1], v[2:3], v[84:85]
	v_pk_fma_f32 v[2:3], v[110:111], v[8:9], v[82:83] op_sel_hi:[0,1,1]
	v_pk_fma_f32 v[0:1], v[110:111], v[10:11], v[0:1] op_sel_hi:[0,1,1]
	v_pk_mul_f32 v[8:9], v[80:81], v[80:81]
	v_pk_mul_f32 v[10:11], v[78:79], v[78:79]
	v_pk_fma_f32 v[20:21], v[110:111], v[20:21], v[86:87] op_sel_hi:[0,1,1]
	v_pk_mov_b32 v[82:83], v[10:11], v[8:9] op_sel:[1,0]
	v_mov_b32_e32 v11, v9
	v_pk_add_f32 v[8:9], v[82:83], v[10:11]
	v_pk_mul_f32 v[10:11], v[30:31], v[30:31]
	v_pk_mul_f32 v[82:83], v[28:29], v[28:29]
	v_pk_add_f32 v[8:9], v[8:9], v[8:9] op_sel_hi:[0,1]
	v_pk_mov_b32 v[84:85], v[82:83], v[10:11] op_sel:[1,0]
	v_mov_b32_e32 v83, v11
	v_pk_add_f32 v[10:11], v[84:85], v[82:83]
	v_pk_mul_f32 v[82:83], v[6:7], v[6:7]
	v_pk_mul_f32 v[84:85], v[4:5], v[4:5]
	v_mul_f32_e32 v8, v14, v14
	v_pk_mov_b32 v[86:87], v[84:85], v[82:83] op_sel:[1,0]
	v_mov_b32_e32 v85, v83
	v_pk_add_f32 v[82:83], v[86:87], v[84:85]
	v_pk_mul_f32 v[84:85], v[18:19], v[18:19]
	v_pk_mul_f32 v[86:87], v[16:17], v[16:17]
	v_pk_add_f32 v[10:11], v[10:11], v[10:11] op_sel_hi:[0,1]
	v_pk_mov_b32 v[88:89], v[86:87], v[84:85] op_sel:[1,0]
	v_mov_b32_e32 v87, v85
	v_pk_add_f32 v[84:85], v[88:89], v[86:87]
	v_pk_fma_f32 v[86:87], v[14:15], v[14:15], v[8:9] op_sel_hi:[1,1,0]
	v_mul_f32_e32 v8, v12, v12
	v_pk_fma_f32 v[88:89], v[12:13], v[12:13], v[8:9] op_sel_hi:[1,1,0]
	v_mul_f32_e32 v8, v26, v26
	v_pk_fma_f32 v[90:91], v[26:27], v[26:27], v[8:9] op_sel_hi:[1,1,0]
	v_mul_f32_e32 v8, v22, v22
	v_pk_add_f32 v[82:83], v[82:83], v[82:83] op_sel_hi:[0,1]
	v_pk_add_f32 v[84:85], v[84:85], v[84:85] op_sel_hi:[0,1]
	v_pk_fma_f32 v[92:93], v[22:23], v[22:23], v[8:9] op_sel_hi:[1,1,0]
	v_mul_f32_e32 v86, v24, v24
	v_mul_f32_e32 v88, v25, v25
	v_mul_f32_e32 v90, v20, v20
	v_mul_f32_e32 v92, v21, v21
	v_mul_f32_e32 v8, v2, v2
	v_mul_f32_e32 v10, v3, v3
	v_mul_f32_e32 v82, v0, v0
	v_mul_f32_e32 v84, v1, v1
	v_pk_add_f32 v[86:87], v[86:87], v[88:89]
	v_pk_add_f32 v[88:89], v[90:91], v[92:93]
	v_pk_add_f32 v[8:9], v[8:9], v[10:11]
	v_pk_add_f32 v[10:11], v[82:83], v[84:85]
	v_pk_add_f32 v[86:87], v[86:87], v[88:89]
	v_pk_add_f32 v[8:9], v[8:9], v[10:11]
	s_nop 0
	v_pk_add_f32 v[8:9], v[86:87], v[8:9]
	s_nop 0
	v_add_f32_e32 v8, v8, v9
	ds_bpermute_b32 v9, v73, v8
	s_waitcnt lgkmcnt(0)
; __device__ __forceinline__ void normres_phase(const bf16_t* hf, const float* xsrc, const float* gprev, bf16_t* HI, bf16_t* LO, float* RS, float* xdst, const float* gpost, float w, const float* gpre, ...
;     ...
;                 const float rs2 = rsqrtf(wave_sum(ss2) * (1.f / D) + EPS);
;                 const f32x4* gn4 = (const f32x4*)gpre + 2 * lane; u32x4* oh = (u32x4*)(HI + (size_t)rr * D) + lane;
; #pragma unroll
;                 for (int c = 0; c < 4; ++c) { const f32x4 y0 = xv[q][2 * c] * rs2 * gn4[128 * c], y1 = xv[q][2 * c + 1] * rs2 * gn4[128 * c + 1];
;                     oh[64 * c] = (u32x4){pk2(y0.x, y0.y), pk2(y0.z, y0.w), pk2(y1.x, y1.y), pk2(y1.z, y1.w)}; }
;                 if (lane == 0) RS[rr] = rs2;
	v_add_f32_e32 v8, v8, v9
	ds_bpermute_b32 v9, v142, v8
	s_waitcnt lgkmcnt(0)
	v_add_f32_e32 v8, v8, v9
	ds_bpermute_b32 v9, v143, v8
	s_waitcnt lgkmcnt(0)
	v_add_f32_e32 v8, v8, v9
	ds_bpermute_b32 v9, v144, v8
	s_waitcnt lgkmcnt(0)
	v_add_f32_e32 v8, v8, v9
	ds_bpermute_b32 v9, v145, v8
	s_waitcnt lgkmcnt(0)
	v_add_f32_e32 v8, v8, v9
	ds_bpermute_b32 v9, v146, v8
	s_waitcnt lgkmcnt(0)
	v_add_f32_e32 v8, v8, v9
	v_mov_b32_e32 v130, 0x358637bd
	v_fmamk_f32 v8, v8, 0x3a000000, v130
	v_cmp_gt_f32_e32 vcc, s92, v8
	v_mul_f32_e32 v9, 0x4b800000, v8
	s_nop 0
	v_cndmask_b32_e32 v8, v8, v9, vcc
	v_rsq_f32_e32 v8, v8
	s_nop 0
	v_mul_f32_e32 v9, 0x45800000, v8
	v_cndmask_b32_e32 v8, v8, v9, vcc
	v_pk_mul_f32 v[10:11], v[78:79], v[8:9] op_sel_hi:[1,0]
	v_pk_mul_f32 v[82:83], v[80:81], v[8:9] op_sel_hi:[1,0]
	flat_load_dwordx4 v[78:81], v[44:45]
	v_pk_mul_f32 v[16:17], v[16:17], v[8:9] op_sel_hi:[1,0]
	v_pk_mul_f32 v[18:19], v[18:19], v[8:9] op_sel_hi:[1,0]
	v_pk_mul_f32 v[12:13], v[12:13], v[8:9] op_sel_hi:[1,0]
	s_waitcnt vmcnt(0) lgkmcnt(0)
	v_pk_mul_f32 v[80:81], v[80:81], v[82:83]
	v_pk_mul_f32 v[10:11], v[78:79], v[10:11]
	v_pk_mul_f32 v[78:79], v[28:29], v[8:9] op_sel_hi:[1,0]
	v_pk_mul_f32 v[82:83], v[30:31], v[8:9] op_sel_hi:[1,0]
	flat_load_dwordx4 v[28:31], v[44:45] offset:16
	s_waitcnt vmcnt(0) lgkmcnt(0)
	v_pk_mul_f32 v[82:83], v[30:31], v[82:83]
	v_pk_mul_f32 v[30:31], v[28:29], v[78:79]
	v_cvt_pk_bf16_f32 v28, v10, v11
	v_cvt_pk_bf16_f32 v29, v80, v81
	v_cvt_pk_bf16_f32 v30, v30, v31
	v_cvt_pk_bf16_f32 v31, v82, v83
	flat_store_dwordx4 v[74:75], v[28:31]
	v_pk_mul_f32 v[10:11], v[4:5], v[8:9] op_sel_hi:[1,0]
	s_nop 0
	v_pk_mul_f32 v[28:29], v[6:7], v[8:9] op_sel_hi:[1,0]
	flat_load_dwordx4 v[4:7], v[44:45] offset:2048
	s_waitcnt vmcnt(0) lgkmcnt(0)
	v_pk_mul_f32 v[28:29], v[6:7], v[28:29]
	v_pk_mul_f32 v[10:11], v[4:5], v[10:11]
	flat_load_dwordx4 v[4:7], v[44:45] offset:2064
	s_waitcnt vmcnt(0) lgkmcnt(0)
	v_pk_mul_f32 v[18:19], v[6:7], v[18:19]
	v_pk_mul_f32 v[6:7], v[4:5], v[16:17]
	v_cvt_pk_bf16_f32 v4, v10, v11
	v_cvt_pk_bf16_f32 v5, v28, v29
	v_cvt_pk_bf16_f32 v6, v6, v7
	v_cvt_pk_bf16_f32 v7, v18, v19
	flat_store_dwordx4 v[74:75], v[4:7] offset:1024
	flat_load_dwordx4 v[4:7], v[62:63]
	v_pk_mul_f32 v[10:11], v[14:15], v[8:9] op_sel_hi:[1,0]
	v_pk_mul_f32 v[14:15], v[26:27], v[8:9] op_sel_hi:[1,0]
	v_pk_mul_f32 v[16:17], v[22:23], v[8:9] op_sel_hi:[1,0]
	s_waitcnt vmcnt(0) lgkmcnt(0)
	v_pk_mul_f32 v[12:13], v[6:7], v[12:13]
	v_pk_mul_f32 v[10:11], v[4:5], v[10:11]
	flat_load_dwordx4 v[4:7], v[64:65]
	s_waitcnt vmcnt(0) lgkmcnt(0)
	v_pk_mul_f32 v[16:17], v[6:7], v[16:17]
	v_pk_mul_f32 v[6:7], v[4:5], v[14:15]
	v_cvt_pk_bf16_f32 v4, v10, v11
	v_cvt_pk_bf16_f32 v5, v12, v13
	v_cvt_pk_bf16_f32 v6, v6, v7
	v_cvt_pk_bf16_f32 v7, v16, v17
	flat_store_dwordx4 v[74:75], v[4:7] offset:2048
	flat_load_dwordx4 v[4:7], v[66:67]
	v_pk_mul_f32 v[10:11], v[24:25], v[8:9] op_sel_hi:[1,0]
	v_pk_mul_f32 v[12:13], v[20:21], v[8:9] op_sel_hi:[1,0]
	s_waitcnt vmcnt(0) lgkmcnt(0)
	v_pk_mul_f32 v[4:5], v[4:5], v[10:11]
	v_pk_mul_f32 v[6:7], v[6:7], v[12:13]
	v_pk_mul_f32 v[10:11], v[2:3], v[8:9] op_sel_hi:[1,0]
	v_pk_mul_f32 v[12:13], v[0:1], v[8:9] op_sel_hi:[1,0]
	flat_load_dwordx4 v[0:3], v[68:69]
	s_waitcnt vmcnt(0) lgkmcnt(0)
	v_pk_mul_f32 v[12:13], v[2:3], v[12:13]
	v_pk_mul_f32 v[2:3], v[0:1], v[10:11]
	v_cvt_pk_bf16_f32 v0, v4, v5
	v_cvt_pk_bf16_f32 v1, v6, v7
	v_cvt_pk_bf16_f32 v2, v2, v3
	v_cvt_pk_bf16_f32 v3, v12, v13
	flat_store_dwordx4 v[74:75], v[0:3] offset:3072
	s_and_saveexec_b64 s[2:3], s[8:9]
	s_cbranch_execz .LBB0_484
	flat_store_dword v[76:77], v8
	s_branch .LBB0_484

; #define PG8_STAGE(bufoff, gbase, voff) do { _Pragma("unroll") for (int _i = 0; _i < 2; ++_i) \
;         __builtin_amdgcn_global_load_lds((const unsigned*)((const char*)(gbase) + (voff)[_i]), (PG8_LAS unsigned*)(lds + (bufoff) + ldsw + _i * 8192), 16, 0, 0); } while (0)
; #define PG8_BAR __builtin_amdgcn_s_barrier()
; template <class Epi, class Sched, bool ALIGN_EPI = false, bool SP2 = false>
; __device__ __forceinline__ void gemm_phase(PG8_LAS unsigned char* lds, const Gemm g, const Sched& S, const Epi& E, int tid_in) {
;     ...
;     const int tid = tid_l, wid = __builtin_amdgcn_readfirstlane(tid >> 6), lane = tid & 63, wr = wid >> 2, wc = wid & 3, fr = lane & 15, fq = lane >> 4;
;     const int K = g.K, nt = K / BK;
;     unsigned voffA[2], voffB[2];
; #pragma unroll
;     for (int i = 0; i < 2; ++i) { int R, C; stage_rc(tid * 16 + i * 8192, R, C); const int Rb = Epi::PERM ? ((R & ~31) + perm32(R & 31)) : R;
;         voffA[i] = (unsigned)(R * K + C) * 2u; voffB[i] = (unsigned)(Rb * K + C) * 2u; }
;     ...
;         PG8_STAGE(PG8_SB(0, 0), cB, voffB); PG8_STAGE(PG8_SB(0, 1), cB + hstep, voffB); PG8_STAGE(PG8_SA(0, 0), cA, voffA); PG8_STAGE(PG8_SA(0, 1), cA + hstep, voffA);
;         if (wr == 1) PG8_BAR;
.LBB0_579:
	v_readlane_b32 s0, v255, 28
	v_readlane_b32 s1, v255, 29
	s_xor_b64 s[38:39], s[0:1], -1
	s_mov_b64 s[0:1], s[44:45]
	s_waitcnt vmcnt(0) lgkmcnt(0)
	v_mov_b64_e32 v[0:1], s[0:1]
	flat_load_dwordx2 v[4:5], v[0:1] offset:136
	v_readlane_b32 s0, v254, 23
	v_mbcnt_lo_u32_b32 v0, -1, 0
	v_mbcnt_hi_u32_b32 v0, -1, v0
	v_readlane_b32 s1, v254, 24
	v_add_u32_e32 v20, s43, v0
	s_andn2_b64 vcc, exec, s[0:1]
	v_readfirstlane_b32 s0, v20
	s_cbranch_vccnz .LBB0_595
	s_mov_b64 s[2:3], 0x13c00000
	s_waitcnt vmcnt(0) lgkmcnt(0)
	v_lshl_add_u64 v[140:141], v[4:5], 0, s[2:3]
	v_readlane_b32 s2, v255, 17
	v_readlane_b32 s3, v255, 18
	v_mov_b32_e32 v145, v129
	v_mov_b32_e32 v149, v129
	v_lshl_add_u64 v[0:1], v[4:5], 0, s[2:3]
	v_readlane_b32 s2, v255, 28
	v_readlane_b32 s3, v255, 29
	s_and_b64 s[2:3], s[2:3], exec
	s_cselect_b32 s48, 0, 0x5c00000
	v_lshl_add_u64 v[142:143], v[0:1], 0, s[48:49]
	v_lshlrev_b32_e32 v0, 4, v20
	v_add_u32_e32 v1, 0x2000, v0
	v_ashrrev_i32_e32 v2, 31, v1
	v_lshrrev_b32_e32 v2, 22, v2
	v_add_u32_e32 v2, v1, v2
	v_ashrrev_i32_e32 v14, 10, v2
	v_mul_i32_i24_e32 v2, 0x400, v14
	v_sub_u32_e32 v1, v1, v2
	v_lshrrev_b32_e32 v2, 4, v1
	v_bitop3_b32 v1, v2, v1, 32 bitop3:0x6c
	v_ashrrev_i32_e32 v2, 31, v1
	v_lshrrev_b32_e32 v2, 26, v2
	v_add_u32_e32 v2, v1, v2
	v_lshlrev_b32_e32 v3, 3, v14
	v_ashrrev_i32_e32 v15, 6, v2
	v_and_b32_e32 v3, -16, v3
	v_add_u32_e32 v3, v15, v3
	v_and_b32_e32 v6, 3, v15
	s_mov_b32 s2, 0xfffe0
	v_lshrrev_b32_e32 v7, 2, v3
	v_lshlrev_b32_e32 v8, 1, v3
	v_and_b32_e32 v2, 0xc0, v2
	v_and_or_b32 v6, v3, s2, v6
	v_and_b32_e32 v7, 4, v7
	v_and_b32_e32 v8, 24, v8
	v_sub_u32_e32 v1, v1, v2
	v_or3_b32 v6, v6, v7, v8
	v_lshlrev_b32_e32 v7, 5, v14
	v_ashrrev_i16_sdwa v1, v170, sext(v1) dst_sel:DWORD dst_unused:UNUSED_PAD src0_sel:DWORD src1_sel:BYTE_0
	v_and_b32_e32 v7, 32, v7
	v_bfe_i32 v16, v1, 0, 16
	v_add_lshl_u32 v1, v7, v16, 1
	v_lshl_add_u32 v144, v6, 12, v1
	v_lshl_add_u32 v146, v3, 12, v1
	v_bfe_i32 v1, v20, 27, 1
	v_lshrrev_b32_e32 v1, 22, v1
	v_add_u32_e32 v1, v0, v1
	v_and_b32_e32 v1, 0xfffffc00, v1
	v_sub_u32_e32 v0, v0, v1
	v_lshrrev_b32_e32 v1, 4, v0
	v_ashrrev_i32_e32 v2, 31, v20
	v_bitop3_b32 v0, v1, v0, 32 bitop3:0x6c
	v_lshrrev_b32_e32 v2, 26, v2
	v_ashrrev_i32_e32 v1, 31, v0
	v_add_u32_e32 v2, v20, v2
	v_lshrrev_b32_e32 v1, 26, v1
	v_ashrrev_i32_e32 v18, 6, v2
	v_add_u32_e32 v1, v0, v1
	v_lshlrev_b32_e32 v2, 3, v18
	v_ashrrev_i32_e32 v17, 6, v1
	v_and_b32_e32 v2, -16, v2
	v_add_u32_e32 v2, v17, v2
	v_and_b32_e32 v3, 3, v17
	v_lshrrev_b32_e32 v6, 2, v2
	v_lshlrev_b32_e32 v7, 1, v2
	v_and_b32_e32 v1, 0xc0, v1
	v_and_or_b32 v3, v2, s2, v3
	v_and_b32_e32 v6, 4, v6
	v_and_b32_e32 v7, 24, v7
	v_sub_u32_e32 v0, v0, v1
	v_or3_b32 v3, v3, v6, v7
	v_lshlrev_b32_e32 v6, 5, v18
	v_ashrrev_i16_sdwa v0, v170, sext(v0) dst_sel:DWORD dst_unused:UNUSED_PAD src0_sel:DWORD src1_sel:BYTE_0
	s_ashr_i32 s1, s0, 6
	v_and_b32_e32 v6, 32, v6
	v_bfe_i32 v19, v0, 0, 16
	v_readlane_b32 s2, v254, 42
	s_lshl_b32 s14, s1, 10
	s_mov_b32 s100, s1
	v_add_lshl_u32 v0, v6, v19, 1
	v_readlane_b32 s3, v254, 43
	v_lshrrev_b32_e32 v248, 3, v171
	v_lshrrev_b32_e32 v249, 4, v171
	v_lshlrev_b32_e32 v249, 1, v249
	v_and_b32_e32 v250, 7, v171
	v_xor_b32_e32 v249, v249, v250
	v_lshlrev_b32_e32 v249, 4, v249
	s_lshl_b32 s101, s1, 3
	v_add_u32_e32 v250, s101, v248
	v_lshl_add_u32 v148, v250, 12, v249
	v_add_u32_e32 v146, 0x40000, v148
	v_mov_b32_e32 v154, v148
	v_mov_b32_e32 v152, v146
	v_lshrrev_b32_e32 v250, 2, v248
	v_lshlrev_b32_e32 v250, 3, v250
	v_and_b32_e32 v251, 3, v248
	v_add_u32_e32 v250, v250, v251
	s_lshr_b32 s101, s1, 2
	s_lshl_b32 s101, s101, 5
	v_add_u32_e32 v250, s101, v250
	s_and_b32 s101, s1, 1
	s_lshl_b32 s101, s101, 4
	v_add_u32_e32 v250, s101, v250
	s_bfe_u32 s101, s1, 0x10001
	s_lshl_b32 s101, s101, 2
	v_add_u32_e32 v250, s101, v250
	v_lshl_add_u32 v128, v250, 12, v249
	v_add_u32_e32 v144, 0x40000, v128
	v_lshl_add_u64 v[0:1], v[142:143], 0, s[2:3]
	s_add_i32 s15, s14, 0
	s_add_i32 m0, s15, 0x10000
	v_lshl_add_u64 v[6:7], v[0:1], 0, v[128:129]
	global_load_lds_dwordx4 v[6:7], off
	v_lshl_add_u64 v[8:9], v[0:1], 0, v[144:145]
	s_add_i32 m0, s15, 0x12000
	v_lshl_add_u64 v[2:3], v[0:1], 0, s[98:99]
	global_load_lds_dwordx4 v[8:9], off
	s_add_i32 m0, s15, 0x14000
	v_lshl_add_u64 v[10:11], v[2:3], 0, v[128:129]
	v_readlane_b32 s2, v254, 40
	global_load_lds_dwordx4 v[10:11], off
	v_lshl_add_u64 v[2:3], v[2:3], 0, v[144:145]
	s_add_i32 m0, s15, 0x16000
	v_readlane_b32 s3, v254, 41
	global_load_lds_dwordx4 v[2:3], off
	s_nop 0
	v_lshl_add_u64 v[2:3], v[140:141], 0, s[2:3]
	v_lshl_add_u64 v[10:11], v[2:3], 0, v[148:149]
	s_mov_b32 m0, s15
	v_mov_b32_e32 v147, v129
	s_add_i32 s16, s15, 0x2000
	global_load_lds_dwordx4 v[10:11], off
	v_lshl_add_u64 v[12:13], v[2:3], 0, v[146:147]
	s_mov_b32 m0, s16
	v_lshl_add_u64 v[22:23], v[2:3], 0, s[98:99]
	s_add_i32 s17, s15, 0x4000
	global_load_lds_dwordx4 v[12:13], off
	v_lshl_add_u64 v[24:25], v[22:23], 0, v[148:149]
	s_mov_b32 m0, s17
	s_add_i32 s18, s15, 0x6000
	global_load_lds_dwordx4 v[24:25], off
	v_lshl_add_u64 v[22:23], v[22:23], 0, v[146:147]
	s_mov_b32 m0, s18
	s_ashr_i32 s2, s0, 8
	global_load_lds_dwordx4 v[22:23], off
	s_cmp_eq_u32 s2, 1
	s_cselect_b64 s[6:7], -1, 0
	s_cmp_lg_u32 s2, 1
	s_cbranch_scc1 .LBB0_582
	s_barrier
; #define PG8_STAGE(bufoff, gbase, voff) do { _Pragma("unroll") for (int _i = 0; _i < 2; ++_i) \
;         __builtin_amdgcn_global_load_lds((const unsigned*)((const char*)(gbase) + (voff)[_i]), (PG8_LAS unsigned*)(lds + (bufoff) + ldsw + _i * 8192), 16, 0, 0); } while (0)
; #define PG8_WAIT_V(n) asm volatile("s_waitcnt vmcnt(" #n ")" ::: "memory")
; #define PG8_BAR __builtin_amdgcn_s_barrier()
; template <class Epi, class Sched, bool ALIGN_EPI = false, bool SP2 = false>
; __device__ __forceinline__ void gemm_phase(PG8_LAS unsigned char* lds, const Gemm g, const Sched& S, const Epi& E, int tid_in) {
;     ...
;     const unsigned ldsw = (unsigned)wid * 1024u;
;     const int aoff = lds_byte(wr * 64 + fr, fq * 8), boff = lds_byte(wc * 32 + fr, fq * 8);
;     ...
;         PG8_WAIT_V(2); PG8_BAR;
;         PG8_STAGE(PG8_SB(1, 0), cB + kstep, voffB); PG8_STAGE(PG8_SA(1, 0), cA + kstep, voffA); PG8_STAGE(PG8_SB(1, 1), cB + hstep + kstep, voffB);
;         PG8_WAIT_V(6); PG8_BAR;
.LBB0_582:
	v_lshl_add_u64 v[150:151], v[4:5], 0, s[40:41]
	v_lshrrev_b32_e32 v5, 1, v20
	v_and_b32_e32 v21, 24, v5
	v_and_b32_e32 v4, 15, v20
	v_lshlrev_b32_e32 v5, 1, v21
	v_lshl_or_b32 v163, s2, 6, v4
	v_lshl_or_b32 v4, v4, 6, v5
	v_lshlrev_b32_e32 v5, 2, v20
	s_lshl_b32 s2, s2, 13
	v_and_b32_e32 v5, 32, v5
	s_lshl_b32 s1, s1, 5
	v_bitop3_b32 v20, v4, s2, v5 bitop3:0xde
	s_and_b32 s2, s1, 0x60
	s_lshl_b32 s1, s2, 7
	v_bitop3_b32 v168, v4, s1, v5 bitop3:0xde
	s_add_i32 m0, s15, 0x18000
	v_lshl_add_u64 v[4:5], v[6:7], 0, s[70:71]
	s_waitcnt vmcnt(2)
	s_barrier
	global_load_lds_dwordx4 v[4:5], off
	v_lshl_add_u64 v[4:5], v[8:9], 0, s[70:71]
	s_add_i32 m0, s15, 0x1a000
	s_add_i32 s19, s15, 0x8000
	global_load_lds_dwordx4 v[4:5], off
	v_lshl_add_u64 v[4:5], v[10:11], 0, s[70:71]
	s_mov_b32 m0, s19
	s_add_i32 s1, s15, 0xa000
	global_load_lds_dwordx4 v[4:5], off
	v_lshl_add_u64 v[4:5], v[12:13], 0, s[70:71]
	s_mov_b32 m0, s1
	v_or_b32_e32 v169, s2, v21
	global_load_lds_dwordx4 v[4:5], off
	v_lshl_add_u64 v[4:5], v[0:1], 0, s[86:87]
	s_add_i32 m0, s15, 0x1c000
	v_lshl_add_u64 v[6:7], v[4:5], 0, v[128:129]
	global_load_lds_dwordx4 v[6:7], off
	v_lshl_add_u64 v[4:5], v[4:5], 0, v[144:145]
	s_add_i32 m0, s15, 0x1e000
	s_cmpk_lt_u32 s0, 0x100
	global_load_lds_dwordx4 v[4:5], off
	v_lshlrev_b32_e32 v4, 15, v14
	v_and_b32_e32 v4, 0xffff0000, v4
	v_lshl_add_u32 v4, v15, 12, v4
	v_and_b32_e32 v5, 1, v14
	v_lshl_or_b32 v4, v5, 6, v4
	v_lshlrev_b32_e32 v4, 15, v18
	v_and_b32_e32 v4, 0xffff0000, v4
	s_waitcnt vmcnt(6)
	v_lshl_add_u32 v4, v17, 12, v4
	v_and_b32_e32 v5, 1, v18
	v_lshl_or_b32 v4, v5, 6, v4
	v_readlane_b32 s2, v254, 38
	s_cselect_b64 s[8:9], -1, 0
	v_mov_b32_e32 v153, v129
	v_mov_b32_e32 v155, v129
	s_mov_b32 s0, 0
	v_and_b32_e32 v248, 15, v171
	v_lshrrev_b32_e32 v249, 4, v171
	v_lshrrev_b32_e32 v250, 1, v248
	v_and_b32_e32 v250, 3, v250
	v_lshlrev_b32_e32 v250, 1, v250
	v_xor_b32_e32 v249, v249, v250
	v_lshlrev_b32_e32 v249, 4, v249
	v_lshl_add_u32 v249, v248, 7, v249
	s_lshr_b32 s101, s100, 2
	s_lshl_b32 s101, s101, 13
	v_add_u32_e32 v175, s101, v249
	v_xor_b32_e32 v168, 64, v175
	s_and_b32 s101, s100, 3
	s_lshl_b32 s101, s101, 12
	s_add_i32 s101, s101, 0x10000
	v_add_u32_e32 v173, s101, v249
	v_xor_b32_e32 v130, 64, v173
	v_readlane_b32 s20, v254, 37
	s_mov_b32 s21, s2
	s_barrier
	v_readlane_b32 s3, v254, 39
	s_branch .LBB0_585

; #define PG8_STAGE(bufoff, gbase, voff) do { _Pragma("unroll") for (int _i = 0; _i < 2; ++_i) \
;         __builtin_amdgcn_global_load_lds((const unsigned*)((const char*)(gbase) + (voff)[_i]), (PG8_LAS unsigned*)(lds + (bufoff) + ldsw + _i * 8192), 16, 0, 0); } while (0)
; #define PG8_LDA(dst, b, h) do { _Pragma("unroll") for (int m = 0; m < 4; ++m) _Pragma("unroll") for (int k = 0; k < 2; ++k) dst[m][k] = *(const PG8_LAS bf16x8*)(lds + PG8_SA(b, h) + aoff + m * 2048 + k * 1024); } while (0)
; #define PG8_LDB(dst, b, h) do { _Pragma("unroll") for (int n = 0; n < 2; ++n) _Pragma("unroll") for (int k = 0; k < 2; ++k) dst[n][k] = *(const PG8_LAS bf16x8*)(lds + PG8_SB(b, h) + boff + n * 2048 + k * 1024); } while (0)
; #define PG8_MMA(ai, bj, At, Bt) do { __builtin_amdgcn_s_setprio(1); _Pragma("unroll") for (int m = 0; m < 4; ++m) _Pragma("unroll") for (int n = 0; n < 2; ++n) _Pragma("unroll") for (int k = 0; k < 2; ++k) \
;         acc[ai][bj][m][n] = __builtin_amdgcn_mfma_f32_16x16x32_bf16(Bt[n][k], At[m][k], acc[ai][bj][m][n], 0, 0, 0); __builtin_amdgcn_s_setprio(0); } while (0)
; #define PG8_WAIT_V(n) asm volatile("s_waitcnt vmcnt(" #n ")" ::: "memory")
; #define PG8_WAIT_L(n) asm volatile("s_waitcnt lgkmcnt(" #n ")" ::: "memory")
; template <class Epi, class Sched, bool ALIGN_EPI = false, bool SP2 = false>
; __device__ __forceinline__ void gemm_phase(PG8_LAS unsigned char* lds, const Gemm g, const Sched& S, const Epi& E, int tid_in) {
;     ...
;             const bool last = (t == nt - 2);
;             const char* a1 = cA + (size_t)(t + 1) * kstep;
;             const char* a2 = last ? nA : cA + (size_t)(t + 2) * kstep; const char* b2 = last ? nB : cB + (size_t)(t + 2) * kstep;
;             const char* a3 = a2 + kstep; const char* b3 = b2 + kstep;
;             if (last && has_next) S.a_ready(nxt);
;             if constexpr (SP2) {
;             PG8_LDB(B0, 0, 0); PG8_LDB(B1, 0, 1); PG8_SCHED; PG8_LDA(At, 0, 0); PG8_STAGE(PG8_SA(1, 1), a1 + hstep, voffA);
;             PG8_WAIT_V(8); PG8_WAIT_L(0); PG8_BAR; PG8_MMA(0, 0, At, B0); PG8_MMA(0, 1, At, B1); PG8_BAR; PG8_SCHED;
;             PG8_LDA(At, 0, 1); PG8_STAGE(PG8_SB(0, 0), b2, voffB); PG8_STAGE(PG8_SB(0, 1), b2 + hstep, voffB); PG8_STAGE(PG8_SA(0, 0), a2, voffA);
;             PG8_WAIT_V(8); PG8_WAIT_L(0); PG8_BAR; PG8_MMA(1, 0, At, B0); PG8_MMA(1, 1, At, B1); PG8_BAR; PG8_SCHED;
.LBB0_588:
	s_cmp_eq_u32 s2, 28
	s_cselect_b64 vcc, -1, 0
	s_add_i32 s3, 0, 0x10000
	s_add_i32 s11, 0, 0x14000
	v_lshl_add_u64 v[176:177], v[166:167], 0, s[52:53]
	v_cndmask_b32_e32 v241, v177, v131, vcc
	v_cndmask_b32_e32 v240, v176, v160, vcc
	ds_read_b128 v[176:179], v173
	ds_read_b128 v[180:183], v130
	ds_read_b128 v[184:187], v173 offset:2048
	ds_read_b128 v[188:191], v130 offset:2048
	ds_read_b128 v[192:195], v173 offset:16384
	ds_read_b128 v[196:199], v130 offset:16384
	ds_read_b128 v[200:203], v173 offset:18432
	ds_read_b128 v[204:207], v130 offset:18432
	v_cndmask_b32_e32 v243, v165, v161, vcc
	v_cndmask_b32_e32 v242, v164, v162, vcc
	v_lshl_add_u64 v[244:245], v[166:167], 0, v[154:155]
	s_add_i32 m0, s15, 0xc000
	ds_read_b128 v[208:211], v175
	ds_read_b128 v[212:215], v168
	ds_read_b128 v[216:219], v175 offset:2048
	ds_read_b128 v[220:223], v168 offset:2048
	ds_read_b128 v[224:227], v175 offset:4096
	ds_read_b128 v[228:231], v168 offset:4096
	ds_read_b128 v[232:235], v175 offset:6144
	ds_read_b128 v[236:239], v168 offset:6144
	global_load_lds_dwordx4 v[244:245], off
	v_lshl_add_u64 v[244:245], v[166:167], 0, v[152:153]
	s_add_i32 m0, s15, 0xe000
	s_nop 0
	global_load_lds_dwordx4 v[244:245], off
	s_setprio 0
	s_waitcnt vmcnt(8) lgkmcnt(0)
	s_barrier
	v_mfma_f32_16x16x32_bf16 v[124:127], v[176:179], v[208:211], v[124:127]
	v_mfma_f32_16x16x32_bf16 v[116:119], v[184:187], v[208:211], v[116:119]
	v_mfma_f32_16x16x32_bf16 v[108:111], v[176:179], v[216:219], v[108:111]
	v_mfma_f32_16x16x32_bf16 v[100:103], v[184:187], v[216:219], v[100:103]
	v_mfma_f32_16x16x32_bf16 v[92:95], v[176:179], v[224:227], v[92:95]
	v_mfma_f32_16x16x32_bf16 v[84:87], v[184:187], v[224:227], v[84:87]
	v_mfma_f32_16x16x32_bf16 v[76:79], v[176:179], v[232:235], v[76:79]
	v_mfma_f32_16x16x32_bf16 v[68:71], v[184:187], v[232:235], v[68:71]
	v_mfma_f32_16x16x32_bf16 v[124:127], v[180:183], v[212:215], v[124:127]
	v_mfma_f32_16x16x32_bf16 v[116:119], v[188:191], v[212:215], v[116:119]
	v_mfma_f32_16x16x32_bf16 v[108:111], v[180:183], v[220:223], v[108:111]
	v_mfma_f32_16x16x32_bf16 v[100:103], v[188:191], v[220:223], v[100:103]
	v_mfma_f32_16x16x32_bf16 v[92:95], v[180:183], v[228:231], v[92:95]
	v_mfma_f32_16x16x32_bf16 v[84:87], v[188:191], v[228:231], v[84:87]
	v_mfma_f32_16x16x32_bf16 v[76:79], v[180:183], v[236:239], v[76:79]
	v_mfma_f32_16x16x32_bf16 v[68:71], v[188:191], v[236:239], v[68:71]
	v_mfma_f32_16x16x32_bf16 v[120:123], v[192:195], v[208:211], v[120:123]
	v_mfma_f32_16x16x32_bf16 v[112:115], v[200:203], v[208:211], v[112:115]
	v_mfma_f32_16x16x32_bf16 v[104:107], v[192:195], v[216:219], v[104:107]
	v_mfma_f32_16x16x32_bf16 v[96:99], v[200:203], v[216:219], v[96:99]
	v_mfma_f32_16x16x32_bf16 v[88:91], v[192:195], v[224:227], v[88:91]
	v_mfma_f32_16x16x32_bf16 v[80:83], v[200:203], v[224:227], v[80:83]
	v_mfma_f32_16x16x32_bf16 v[72:75], v[192:195], v[232:235], v[72:75]
	v_mfma_f32_16x16x32_bf16 v[64:67], v[200:203], v[232:235], v[64:67]
	v_mfma_f32_16x16x32_bf16 v[120:123], v[196:199], v[212:215], v[120:123]
	v_mfma_f32_16x16x32_bf16 v[112:115], v[204:207], v[212:215], v[112:115]
	v_mfma_f32_16x16x32_bf16 v[104:107], v[196:199], v[220:223], v[104:107]
	v_mfma_f32_16x16x32_bf16 v[96:99], v[204:207], v[220:223], v[96:99]
	v_mfma_f32_16x16x32_bf16 v[88:91], v[196:199], v[228:231], v[88:91]
	v_mfma_f32_16x16x32_bf16 v[80:83], v[204:207], v[228:231], v[80:83]
	v_mfma_f32_16x16x32_bf16 v[72:75], v[196:199], v[236:239], v[72:75]
	v_mfma_f32_16x16x32_bf16 v[64:67], v[204:207], v[236:239], v[64:67]
	s_barrier
	s_setprio 1
	s_add_i32 s3, s3, s14
	v_lshl_add_u64 v[244:245], v[242:243], 0, v[128:129]
	s_mov_b32 m0, s3
	ds_read_b128 v[208:211], v175 offset:16384
	ds_read_b128 v[212:215], v168 offset:16384
	ds_read_b128 v[216:219], v175 offset:18432
	ds_read_b128 v[220:223], v168 offset:18432
	ds_read_b128 v[224:227], v175 offset:20480
	ds_read_b128 v[228:231], v168 offset:20480
	ds_read_b128 v[232:235], v175 offset:22528
	ds_read_b128 v[236:239], v168 offset:22528
	global_load_lds_dwordx4 v[244:245], off
	v_lshl_add_u64 v[246:247], v[242:243], 0, v[144:145]
	s_add_i32 m0, s3, 0x2000
	v_lshl_add_u64 v[248:249], v[242:243], 0, s[98:99]
	s_add_i32 s3, s11, s14
	global_load_lds_dwordx4 v[246:247], off
	v_lshl_add_u64 v[250:251], v[248:249], 0, v[128:129]
	s_mov_b32 m0, s3
	v_lshl_add_u64 v[248:249], v[248:249], 0, v[144:145]
	global_load_lds_dwordx4 v[250:251], off
	s_add_i32 m0, s3, 0x2000
	v_lshl_add_u64 v[250:251], v[240:241], 0, v[146:147]
	global_load_lds_dwordx4 v[248:249], off
	v_lshl_add_u64 v[248:249], v[240:241], 0, v[148:149]
	s_mov_b32 m0, s15
	s_nop 0
	global_load_lds_dwordx4 v[248:249], off
	s_mov_b32 m0, s16
	s_nop 0
	global_load_lds_dwordx4 v[250:251], off
	s_setprio 0
	s_waitcnt vmcnt(8) lgkmcnt(0)
	s_barrier
; #define PG8_STAGE(bufoff, gbase, voff) do { _Pragma("unroll") for (int _i = 0; _i < 2; ++_i) \
;         __builtin_amdgcn_global_load_lds((const unsigned*)((const char*)(gbase) + (voff)[_i]), (PG8_LAS unsigned*)(lds + (bufoff) + ldsw + _i * 8192), 16, 0, 0); } while (0)
; #define PG8_LDA(dst, b, h) do { _Pragma("unroll") for (int m = 0; m < 4; ++m) _Pragma("unroll") for (int k = 0; k < 2; ++k) dst[m][k] = *(const PG8_LAS bf16x8*)(lds + PG8_SA(b, h) + aoff + m * 2048 + k * 1024); } while (0)
; #define PG8_LDB(dst, b, h) do { _Pragma("unroll") for (int n = 0; n < 2; ++n) _Pragma("unroll") for (int k = 0; k < 2; ++k) dst[n][k] = *(const PG8_LAS bf16x8*)(lds + PG8_SB(b, h) + boff + n * 2048 + k * 1024); } while (0)
; #define PG8_MMA(ai, bj, At, Bt) do { __builtin_amdgcn_s_setprio(1); _Pragma("unroll") for (int m = 0; m < 4; ++m) _Pragma("unroll") for (int n = 0; n < 2; ++n) _Pragma("unroll") for (int k = 0; k < 2; ++k) \
;         acc[ai][bj][m][n] = __builtin_amdgcn_mfma_f32_16x16x32_bf16(Bt[n][k], At[m][k], acc[ai][bj][m][n], 0, 0, 0); __builtin_amdgcn_s_setprio(0); } while (0)
; #define PG8_WAIT_V(n) asm volatile("s_waitcnt vmcnt(" #n ")" ::: "memory")
; #define PG8_WAIT_L(n) asm volatile("s_waitcnt lgkmcnt(" #n ")" ::: "memory")
; #define PG8_BAR __builtin_amdgcn_s_barrier()
; #define PG8_SCHED __builtin_amdgcn_sched_barrier(0)
; template <class Epi, class Sched, bool ALIGN_EPI = false, bool SP2 = false>
; __device__ __forceinline__ void gemm_phase(PG8_LAS unsigned char* lds, const Gemm g, const Sched& S, const Epi& E, int tid_in) {
;     ...
;             PG8_WAIT_V(8); PG8_WAIT_L(0); PG8_BAR; PG8_MMA(1, 0, At, B0); PG8_MMA(1, 1, At, B1); PG8_BAR; PG8_SCHED;
;             PG8_LDB(B0, 1, 0); PG8_LDB(B1, 1, 1); PG8_SCHED; PG8_LDA(At, 1, 0); PG8_STAGE(PG8_SA(0, 1), a2 + hstep, voffA);
;             PG8_WAIT_V(8); PG8_WAIT_L(0); PG8_BAR; PG8_MMA(0, 0, At, B0); PG8_MMA(0, 1, At, B1); PG8_BAR; PG8_SCHED;
;             PG8_LDA(At, 1, 1); PG8_STAGE(PG8_SB(1, 0), b3, voffB); PG8_STAGE(PG8_SB(1, 1), b3 + hstep, voffB); PG8_STAGE(PG8_SA(1, 0), a3, voffA);
	v_mfma_f32_16x16x32_bf16 v[60:63], v[176:179], v[208:211], v[60:63]
	v_mfma_f32_16x16x32_bf16 v[52:55], v[184:187], v[208:211], v[52:55]
	v_mfma_f32_16x16x32_bf16 v[44:47], v[176:179], v[216:219], v[44:47]
	v_mfma_f32_16x16x32_bf16 v[36:39], v[184:187], v[216:219], v[36:39]
	v_mfma_f32_16x16x32_bf16 v[28:31], v[176:179], v[224:227], v[28:31]
	v_mfma_f32_16x16x32_bf16 v[20:23], v[184:187], v[224:227], v[20:23]
	v_mfma_f32_16x16x32_bf16 v[12:15], v[176:179], v[232:235], v[12:15]
	v_mfma_f32_16x16x32_bf16 v[4:7], v[184:187], v[232:235], v[4:7]
	v_mfma_f32_16x16x32_bf16 v[60:63], v[180:183], v[212:215], v[60:63]
	v_mfma_f32_16x16x32_bf16 v[52:55], v[188:191], v[212:215], v[52:55]
	v_mfma_f32_16x16x32_bf16 v[44:47], v[180:183], v[220:223], v[44:47]
	v_mfma_f32_16x16x32_bf16 v[36:39], v[188:191], v[220:223], v[36:39]
	v_mfma_f32_16x16x32_bf16 v[28:31], v[180:183], v[228:231], v[28:31]
	v_mfma_f32_16x16x32_bf16 v[20:23], v[188:191], v[228:231], v[20:23]
	v_mfma_f32_16x16x32_bf16 v[12:15], v[180:183], v[236:239], v[12:15]
	v_mfma_f32_16x16x32_bf16 v[4:7], v[188:191], v[236:239], v[4:7]
	v_mfma_f32_16x16x32_bf16 v[56:59], v[192:195], v[208:211], v[56:59]
	v_mfma_f32_16x16x32_bf16 v[48:51], v[200:203], v[208:211], v[48:51]
	v_mfma_f32_16x16x32_bf16 v[40:43], v[192:195], v[216:219], v[40:43]
	v_mfma_f32_16x16x32_bf16 v[32:35], v[200:203], v[216:219], v[32:35]
	v_mfma_f32_16x16x32_bf16 v[24:27], v[192:195], v[224:227], v[24:27]
	v_mfma_f32_16x16x32_bf16 v[16:19], v[200:203], v[224:227], v[16:19]
	v_mfma_f32_16x16x32_bf16 v[8:11], v[192:195], v[232:235], v[8:11]
	v_mfma_f32_16x16x32_bf16 v[0:3], v[200:203], v[232:235], v[0:3]
	v_mfma_f32_16x16x32_bf16 v[56:59], v[196:199], v[212:215], v[56:59]
	v_mfma_f32_16x16x32_bf16 v[48:51], v[204:207], v[212:215], v[48:51]
	v_mfma_f32_16x16x32_bf16 v[40:43], v[196:199], v[220:223], v[40:43]
	v_mfma_f32_16x16x32_bf16 v[32:35], v[204:207], v[220:223], v[32:35]
	v_mfma_f32_16x16x32_bf16 v[24:27], v[196:199], v[228:231], v[24:27]
	v_mfma_f32_16x16x32_bf16 v[16:19], v[204:207], v[228:231], v[16:19]
	v_mfma_f32_16x16x32_bf16 v[8:11], v[196:199], v[236:239], v[8:11]
	v_mfma_f32_16x16x32_bf16 v[0:3], v[204:207], v[236:239], v[0:3]
	s_barrier
	s_setprio 1
	s_add_i32 s3, 0, 0x18000
	s_add_i32 s11, 0, 0x1c000
	ds_read_b128 v[176:179], v173 offset:32768
	ds_read_b128 v[180:183], v130 offset:32768
	ds_read_b128 v[184:187], v173 offset:34816
	ds_read_b128 v[188:191], v130 offset:34816
	ds_read_b128 v[192:195], v173 offset:49152
	ds_read_b128 v[196:199], v130 offset:49152
	ds_read_b128 v[200:203], v173 offset:51200
	ds_read_b128 v[204:207], v130 offset:51200
	v_lshl_add_u64 v[240:241], v[240:241], 0, s[98:99]
	s_mov_b32 m0, s17
	v_lshl_add_u64 v[252:253], v[240:241], 0, v[148:149]
	ds_read_b128 v[208:211], v175 offset:32768
	ds_read_b128 v[212:215], v168 offset:32768
	ds_read_b128 v[216:219], v175 offset:34816
	ds_read_b128 v[220:223], v168 offset:34816
	ds_read_b128 v[224:227], v175 offset:36864
	ds_read_b128 v[228:231], v168 offset:36864
	ds_read_b128 v[232:235], v175 offset:38912
	ds_read_b128 v[236:239], v168 offset:38912
	global_load_lds_dwordx4 v[252:253], off
	v_lshl_add_u64 v[240:241], v[240:241], 0, v[146:147]
	s_mov_b32 m0, s18
	s_nop 0
	global_load_lds_dwordx4 v[240:241], off
	s_setprio 0
	s_waitcnt vmcnt(8) lgkmcnt(0)
	s_barrier
	v_mfma_f32_16x16x32_bf16 v[124:127], v[176:179], v[208:211], v[124:127]
	v_mfma_f32_16x16x32_bf16 v[116:119], v[184:187], v[208:211], v[116:119]
	v_mfma_f32_16x16x32_bf16 v[108:111], v[176:179], v[216:219], v[108:111]
	v_mfma_f32_16x16x32_bf16 v[100:103], v[184:187], v[216:219], v[100:103]
	v_mfma_f32_16x16x32_bf16 v[92:95], v[176:179], v[224:227], v[92:95]
	v_mfma_f32_16x16x32_bf16 v[84:87], v[184:187], v[224:227], v[84:87]
	v_mfma_f32_16x16x32_bf16 v[76:79], v[176:179], v[232:235], v[76:79]
	v_mfma_f32_16x16x32_bf16 v[68:71], v[184:187], v[232:235], v[68:71]
	v_mfma_f32_16x16x32_bf16 v[124:127], v[180:183], v[212:215], v[124:127]
	v_mfma_f32_16x16x32_bf16 v[116:119], v[188:191], v[212:215], v[116:119]
	v_mfma_f32_16x16x32_bf16 v[108:111], v[180:183], v[220:223], v[108:111]
	v_mfma_f32_16x16x32_bf16 v[100:103], v[188:191], v[220:223], v[100:103]
	v_mfma_f32_16x16x32_bf16 v[92:95], v[180:183], v[228:231], v[92:95]
	v_mfma_f32_16x16x32_bf16 v[84:87], v[188:191], v[228:231], v[84:87]
	v_mfma_f32_16x16x32_bf16 v[76:79], v[180:183], v[236:239], v[76:79]
	v_mfma_f32_16x16x32_bf16 v[68:71], v[188:191], v[236:239], v[68:71]
	v_mfma_f32_16x16x32_bf16 v[120:123], v[192:195], v[208:211], v[120:123]
	v_mfma_f32_16x16x32_bf16 v[112:115], v[200:203], v[208:211], v[112:115]
	v_mfma_f32_16x16x32_bf16 v[104:107], v[192:195], v[216:219], v[104:107]
	v_mfma_f32_16x16x32_bf16 v[96:99], v[200:203], v[216:219], v[96:99]
	v_mfma_f32_16x16x32_bf16 v[88:91], v[192:195], v[224:227], v[88:91]
	v_mfma_f32_16x16x32_bf16 v[80:83], v[200:203], v[224:227], v[80:83]
	v_mfma_f32_16x16x32_bf16 v[72:75], v[192:195], v[232:235], v[72:75]
	v_mfma_f32_16x16x32_bf16 v[64:67], v[200:203], v[232:235], v[64:67]
	v_mfma_f32_16x16x32_bf16 v[120:123], v[196:199], v[212:215], v[120:123]
	v_mfma_f32_16x16x32_bf16 v[112:115], v[204:207], v[212:215], v[112:115]
	v_mfma_f32_16x16x32_bf16 v[104:107], v[196:199], v[220:223], v[104:107]
	v_mfma_f32_16x16x32_bf16 v[96:99], v[204:207], v[220:223], v[96:99]
	v_mfma_f32_16x16x32_bf16 v[88:91], v[196:199], v[228:231], v[88:91]
	v_mfma_f32_16x16x32_bf16 v[80:83], v[204:207], v[228:231], v[80:83]
	v_mfma_f32_16x16x32_bf16 v[72:75], v[196:199], v[236:239], v[72:75]
	v_mfma_f32_16x16x32_bf16 v[64:67], v[204:207], v[236:239], v[64:67]
	s_barrier
; #define PG8_STAGE(bufoff, gbase, voff) do { _Pragma("unroll") for (int _i = 0; _i < 2; ++_i) \
;         __builtin_amdgcn_global_load_lds((const unsigned*)((const char*)(gbase) + (voff)[_i]), (PG8_LAS unsigned*)(lds + (bufoff) + ldsw + _i * 8192), 16, 0, 0); } while (0)
; #define PG8_LDA(dst, b, h) do { _Pragma("unroll") for (int m = 0; m < 4; ++m) _Pragma("unroll") for (int k = 0; k < 2; ++k) dst[m][k] = *(const PG8_LAS bf16x8*)(lds + PG8_SA(b, h) + aoff + m * 2048 + k * 1024); } while (0)
; #define PG8_MMA(ai, bj, At, Bt) do { __builtin_amdgcn_s_setprio(1); _Pragma("unroll") for (int m = 0; m < 4; ++m) _Pragma("unroll") for (int n = 0; n < 2; ++n) _Pragma("unroll") for (int k = 0; k < 2; ++k) \
;         acc[ai][bj][m][n] = __builtin_amdgcn_mfma_f32_16x16x32_bf16(Bt[n][k], At[m][k], acc[ai][bj][m][n], 0, 0, 0); __builtin_amdgcn_s_setprio(0); } while (0)
; #define PG8_WAIT_V(n) asm volatile("s_waitcnt vmcnt(" #n ")" ::: "memory")
; #define PG8_WAIT_L(n) asm volatile("s_waitcnt lgkmcnt(" #n ")" ::: "memory")
; #define PG8_BAR __builtin_amdgcn_s_barrier()
; #define PG8_SCHED __builtin_amdgcn_sched_barrier(0)
; template <class Epi, class Sched, bool ALIGN_EPI = false, bool SP2 = false>
; __device__ __forceinline__ void gemm_phase(PG8_LAS unsigned char* lds, const Gemm g, const Sched& S, const Epi& E, int tid_in) {
;     ...
;         for (int t = 0; t < nt; t += 2) {
;     ...
;             PG8_LDA(At, 1, 1); PG8_STAGE(PG8_SB(1, 0), b3, voffB); PG8_STAGE(PG8_SB(1, 1), b3 + hstep, voffB); PG8_STAGE(PG8_SA(1, 0), a3, voffA);
;             PG8_WAIT_V(8); PG8_WAIT_L(0); PG8_BAR; PG8_MMA(1, 0, At, B0); PG8_MMA(1, 1, At, B1); PG8_BAR; PG8_SCHED;
	s_setprio 1
	s_add_i32 s3, s3, s14
	v_lshl_add_u64 v[240:241], v[244:245], 0, s[70:71]
	s_mov_b32 m0, s3
	ds_read_b128 v[208:211], v175 offset:49152
	ds_read_b128 v[212:215], v168 offset:49152
	ds_read_b128 v[216:219], v175 offset:51200
	ds_read_b128 v[220:223], v168 offset:51200
	ds_read_b128 v[224:227], v175 offset:53248
	ds_read_b128 v[228:231], v168 offset:53248
	ds_read_b128 v[232:235], v175 offset:55296
	ds_read_b128 v[236:239], v168 offset:55296
	global_load_lds_dwordx4 v[240:241], off
	v_lshl_add_u64 v[240:241], v[246:247], 0, s[70:71]
	s_add_i32 m0, s3, 0x2000
	s_add_i32 s3, s11, s14
	global_load_lds_dwordx4 v[240:241], off
	v_lshl_add_u64 v[240:241], v[242:243], 0, s[86:87]
	v_lshl_add_u64 v[242:243], v[240:241], 0, v[128:129]
	s_mov_b32 m0, s3
	v_lshl_add_u64 v[240:241], v[240:241], 0, v[144:145]
	global_load_lds_dwordx4 v[242:243], off
	s_add_i32 m0, s3, 0x2000
	s_nop 0
	global_load_lds_dwordx4 v[240:241], off
	v_lshl_add_u64 v[240:241], v[248:249], 0, s[70:71]
	s_mov_b32 m0, s19
	s_nop 0
	global_load_lds_dwordx4 v[240:241], off
	v_lshl_add_u64 v[240:241], v[250:251], 0, s[70:71]
	s_mov_b32 m0, s1
	s_nop 0
	global_load_lds_dwordx4 v[240:241], off
	s_setprio 0
	s_waitcnt vmcnt(8) lgkmcnt(0)
	s_barrier
	v_mfma_f32_16x16x32_bf16 v[60:63], v[176:179], v[208:211], v[60:63]
	v_mfma_f32_16x16x32_bf16 v[52:55], v[184:187], v[208:211], v[52:55]
	v_mfma_f32_16x16x32_bf16 v[44:47], v[176:179], v[216:219], v[44:47]
	v_mfma_f32_16x16x32_bf16 v[36:39], v[184:187], v[216:219], v[36:39]
	v_mfma_f32_16x16x32_bf16 v[28:31], v[176:179], v[224:227], v[28:31]
	v_mfma_f32_16x16x32_bf16 v[20:23], v[184:187], v[224:227], v[20:23]
	v_mfma_f32_16x16x32_bf16 v[12:15], v[176:179], v[232:235], v[12:15]
	v_mfma_f32_16x16x32_bf16 v[4:7], v[184:187], v[232:235], v[4:7]
	v_mfma_f32_16x16x32_bf16 v[60:63], v[180:183], v[212:215], v[60:63]
	v_mfma_f32_16x16x32_bf16 v[52:55], v[188:191], v[212:215], v[52:55]
	v_mfma_f32_16x16x32_bf16 v[44:47], v[180:183], v[220:223], v[44:47]
	v_mfma_f32_16x16x32_bf16 v[36:39], v[188:191], v[220:223], v[36:39]
	v_mfma_f32_16x16x32_bf16 v[28:31], v[180:183], v[228:231], v[28:31]
	v_mfma_f32_16x16x32_bf16 v[20:23], v[188:191], v[228:231], v[20:23]
	v_mfma_f32_16x16x32_bf16 v[12:15], v[180:183], v[236:239], v[12:15]
	v_mfma_f32_16x16x32_bf16 v[4:7], v[188:191], v[236:239], v[4:7]
	v_mfma_f32_16x16x32_bf16 v[56:59], v[192:195], v[208:211], v[56:59]
	v_mfma_f32_16x16x32_bf16 v[48:51], v[200:203], v[208:211], v[48:51]
	v_mfma_f32_16x16x32_bf16 v[40:43], v[192:195], v[216:219], v[40:43]
	v_mfma_f32_16x16x32_bf16 v[32:35], v[200:203], v[216:219], v[32:35]
	v_mfma_f32_16x16x32_bf16 v[24:27], v[192:195], v[224:227], v[24:27]
	v_mfma_f32_16x16x32_bf16 v[16:19], v[200:203], v[224:227], v[16:19]
	v_mfma_f32_16x16x32_bf16 v[8:11], v[192:195], v[232:235], v[8:11]
	v_mfma_f32_16x16x32_bf16 v[0:3], v[200:203], v[232:235], v[0:3]
	v_mfma_f32_16x16x32_bf16 v[56:59], v[196:199], v[212:215], v[56:59]
	v_mfma_f32_16x16x32_bf16 v[48:51], v[204:207], v[212:215], v[48:51]
	v_mfma_f32_16x16x32_bf16 v[40:43], v[196:199], v[220:223], v[40:43]
	v_mfma_f32_16x16x32_bf16 v[32:35], v[204:207], v[220:223], v[32:35]
	v_mfma_f32_16x16x32_bf16 v[24:27], v[196:199], v[228:231], v[24:27]
	v_mfma_f32_16x16x32_bf16 v[16:19], v[204:207], v[228:231], v[16:19]
	v_mfma_f32_16x16x32_bf16 v[8:11], v[196:199], v[236:239], v[8:11]
	v_mfma_f32_16x16x32_bf16 v[0:3], v[204:207], v[236:239], v[0:3]
	s_barrier
	s_setprio 1
	s_add_i32 s2, s2, 2
	v_lshl_add_u64 v[164:165], v[164:165], 0, s[82:83]
	s_cmp_gt_u32 s2, 29
	v_lshl_add_u64 v[166:167], v[166:167], 0, s[82:83]
	s_cbranch_scc0 .LBB0_588
	s_setprio 0
	s_and_b64 vcc, exec, s[8:9]
	s_cbranch_vccz .LBB0_591
	s_barrier

; #define PG8_STAGE(bufoff, gbase, voff) do { _Pragma("unroll") for (int _i = 0; _i < 2; ++_i) \
;         __builtin_amdgcn_global_load_lds((const unsigned*)((const char*)(gbase) + (voff)[_i]), (PG8_LAS unsigned*)(lds + (bufoff) + ldsw + _i * 8192), 16, 0, 0); } while (0)
; #define PG8_WAIT_V(n) asm volatile("s_waitcnt vmcnt(" #n ")" ::: "memory")
; #define PG8_BAR __builtin_amdgcn_s_barrier()
; template <class Epi, class Sched, bool ALIGN_EPI = false, bool SP2 = false>
; __device__ __forceinline__ void gemm_phase(PG8_LAS unsigned char* lds, const Gemm g, const Sched& S, const Epi& E, int tid_in) {
;     ...
;     const unsigned ldsw = (unsigned)wid * 1024u;
;     const int aoff = lds_byte(wr * 64 + fr, fq * 8), boff = lds_byte(wc * 32 + fr, fq * 8);
;     ...
;         PG8_WAIT_V(2); PG8_BAR;
;         PG8_STAGE(PG8_SB(1, 0), cB + kstep, voffB); PG8_STAGE(PG8_SA(1, 0), cA + kstep, voffA); PG8_STAGE(PG8_SB(1, 1), cB + hstep + kstep, voffB);
;         PG8_WAIT_V(6); PG8_BAR;
.LBB0_669:
	s_mov_b64 s[8:9], 0x22c00000
	v_lshl_add_u64 v[150:151], v[2:3], 0, s[8:9]
	v_lshrrev_b32_e32 v3, 1, v20
	v_and_b32_e32 v21, 24, v3
	v_and_b32_e32 v2, 15, v20
	v_lshlrev_b32_e32 v3, 1, v21
	v_lshl_or_b32 v131, s6, 6, v2
	v_lshl_or_b32 v2, v2, 6, v3
	v_lshlrev_b32_e32 v3, 2, v20
	s_lshl_b32 s3, s3, 5
	s_lshl_b32 s6, s6, 13
	v_and_b32_e32 v3, 32, v3
	s_and_b32 s3, s3, 0x60
	v_bitop3_b32 v20, v2, s6, v3 bitop3:0xde
	s_lshl_b32 s6, s3, 7
	v_bitop3_b32 v166, v2, s6, v3 bitop3:0xde
	v_add_u32_e32 v173, 0x10000, v166
	s_add_i32 m0, s14, 0x18000
	v_lshl_add_u64 v[2:3], v[4:5], 0, s[70:71]
	s_waitcnt vmcnt(2)
	s_barrier
	global_load_lds_dwordx4 v[2:3], off
	v_lshl_add_u64 v[2:3], v[6:7], 0, s[70:71]
	s_add_i32 m0, s14, 0x1a000
	s_add_i32 s18, s14, 0x8000
	global_load_lds_dwordx4 v[2:3], off
	v_lshl_add_u64 v[2:3], v[8:9], 0, s[70:71]
	s_mov_b32 m0, s18
	s_add_i32 s19, s14, 0xa000
	global_load_lds_dwordx4 v[2:3], off
	v_lshl_add_u64 v[2:3], v[10:11], 0, s[70:71]
	s_mov_b32 m0, s19
	s_movk_i32 s7, 0x1600
	global_load_lds_dwordx4 v[2:3], off
	v_lshl_add_u64 v[2:3], v[0:1], 0, s[60:61]
	s_add_i32 m0, s14, 0x1c000
	v_lshl_add_u64 v[4:5], v[2:3], 0, v[128:129]
	global_load_lds_dwordx4 v[4:5], off
	v_lshl_add_u64 v[2:3], v[2:3], 0, v[144:145]
	s_add_i32 m0, s14, 0x1e000
	s_mov_b32 s6, 0x16000
	global_load_lds_dwordx4 v[2:3], off
	v_lshrrev_b32_e32 v3, 1, v12
	v_mul_lo_u32 v2, v13, s7
	s_cmpk_lt_u32 s2, 0x100
	v_or_b32_e32 v167, s3, v21
	v_mad_u64_u32 v[2:3], s[2:3], v3, s6, v[2:3]
	v_or_b32_e32 v2, v2, v14
	v_add_lshl_u32 v2, v2, v15, 1
	v_mov_b32_e32 v3, v129
	v_lshl_add_u64 v[152:153], v[2:3], 0, s[60:61]
	v_lshrrev_b32_e32 v3, 1, v17
	v_mul_lo_u32 v2, v16, s7
	v_mad_u64_u32 v[2:3], s[2:3], v3, s6, v[2:3]
	s_waitcnt vmcnt(6)
	v_or_b32_e32 v2, v2, v18
	v_add_lshl_u32 v2, v2, v19, 1
	v_mov_b32_e32 v3, v129
	v_readlane_b32 s2, v254, 44
	s_cselect_b64 s[12:13], -1, 0
	v_lshl_add_u64 v[154:155], v[2:3], 0, s[60:61]
	s_mov_b32 s20, 0
	v_add_u32_e32 v168, 0, v20
	v_readlane_b32 s23, v254, 48
	s_mov_b32 s24, s2
	s_barrier
	v_readlane_b32 s3, v254, 45
	s_branch .LBB0_672

; #define PG8_STAGE(bufoff, gbase, voff) do { _Pragma("unroll") for (int _i = 0; _i < 2; ++_i) \
;         __builtin_amdgcn_global_load_lds((const unsigned*)((const char*)(gbase) + (voff)[_i]), (PG8_LAS unsigned*)(lds + (bufoff) + ldsw + _i * 8192), 16, 0, 0); } while (0)
; #define PG8_LDA(dst, b, h) do { _Pragma("unroll") for (int m = 0; m < 4; ++m) _Pragma("unroll") for (int k = 0; k < 2; ++k) dst[m][k] = *(const PG8_LAS bf16x8*)(lds + PG8_SA(b, h) + aoff + m * 2048 + k * 1024); } while (0)
; #define PG8_LDB(dst, b, h) do { _Pragma("unroll") for (int n = 0; n < 2; ++n) _Pragma("unroll") for (int k = 0; k < 2; ++k) dst[n][k] = *(const PG8_LAS bf16x8*)(lds + PG8_SB(b, h) + boff + n * 2048 + k * 1024); } while (0)
; #define PG8_MMA(ai, bj, At, Bt) do { __builtin_amdgcn_s_setprio(1); _Pragma("unroll") for (int m = 0; m < 4; ++m) _Pragma("unroll") for (int n = 0; n < 2; ++n) _Pragma("unroll") for (int k = 0; k < 2; ++k) \
;         acc[ai][bj][m][n] = __builtin_amdgcn_mfma_f32_16x16x32_bf16(Bt[n][k], At[m][k], acc[ai][bj][m][n], 0, 0, 0); __builtin_amdgcn_s_setprio(0); } while (0)
; #define PG8_WAIT_V(n) asm volatile("s_waitcnt vmcnt(" #n ")" ::: "memory")
; #define PG8_WAIT_L(n) asm volatile("s_waitcnt lgkmcnt(" #n ")" ::: "memory")
; template <class Epi, class Sched, bool ALIGN_EPI = false, bool SP2 = false>
; __device__ __forceinline__ void gemm_phase(PG8_LAS unsigned char* lds, const Gemm g, const Sched& S, const Epi& E, int tid_in) {
;     ...
;             const bool last = (t == nt - 2);
;             const char* a1 = cA + (size_t)(t + 1) * kstep;
;             const char* a2 = last ? nA : cA + (size_t)(t + 2) * kstep; const char* b2 = last ? nB : cB + (size_t)(t + 2) * kstep;
;             const char* a3 = a2 + kstep; const char* b3 = b2 + kstep;
;             if (last && has_next) S.a_ready(nxt);
;             if constexpr (SP2) {
;             PG8_LDB(B0, 0, 0); PG8_LDB(B1, 0, 1); PG8_SCHED; PG8_LDA(At, 0, 0); PG8_STAGE(PG8_SA(1, 1), a1 + hstep, voffA);
;             PG8_WAIT_V(8); PG8_WAIT_L(0); PG8_BAR; PG8_MMA(0, 0, At, B0); PG8_MMA(0, 1, At, B1); PG8_BAR; PG8_SCHED;
;             PG8_LDA(At, 0, 1); PG8_STAGE(PG8_SB(0, 0), b2, voffB); PG8_STAGE(PG8_SB(0, 1), b2 + hstep, voffB); PG8_STAGE(PG8_SA(0, 0), a2, voffA);
;             PG8_WAIT_V(8); PG8_WAIT_L(0); PG8_BAR; PG8_MMA(1, 0, At, B0); PG8_MMA(1, 1, At, B1); PG8_BAR; PG8_SCHED;
.LBB0_683:
	s_cmpk_eq_i32 s2, 0x54
	s_cselect_b64 vcc, -1, 0
	s_add_i32 s3, 0, 0x10000
	s_add_i32 s8, 0, 0x14000
	ds_read_b128 v[176:179], v173
	ds_read_b128 v[180:183], v173 offset:1024
	ds_read_b128 v[184:187], v173 offset:2048
	ds_read_b128 v[188:191], v173 offset:3072
	ds_read_b128 v[192:195], v173 offset:16384
	ds_read_b128 v[196:199], v173 offset:17408
	ds_read_b128 v[200:203], v173 offset:18432
	ds_read_b128 v[204:207], v173 offset:19456
	v_lshl_add_u64 v[164:165], v[162:163], 0, s[82:83]
	v_cndmask_b32_e32 v241, v165, v157, vcc
	v_cndmask_b32_e32 v240, v164, v156, vcc
	v_cndmask_b32_e32 v243, v161, v159, vcc
	v_cndmask_b32_e32 v242, v160, v158, vcc
	v_lshl_add_u64 v[244:245], v[162:163], 0, v[154:155]
	s_add_i32 m0, s14, 0xc000
	ds_read_b128 v[208:211], v168
	ds_read_b128 v[212:215], v168 offset:1024
	ds_read_b128 v[216:219], v168 offset:2048
	ds_read_b128 v[220:223], v168 offset:3072
	ds_read_b128 v[224:227], v168 offset:4096
	ds_read_b128 v[228:231], v168 offset:5120
	ds_read_b128 v[232:235], v168 offset:6144
	ds_read_b128 v[236:239], v168 offset:7168
	global_load_lds_dwordx4 v[244:245], off
	v_lshl_add_u64 v[162:163], v[162:163], 0, v[152:153]
	s_add_i32 m0, s14, 0xe000
	s_nop 0
	global_load_lds_dwordx4 v[162:163], off
	s_setprio 0
	s_waitcnt vmcnt(8) lgkmcnt(0)
	s_barrier
	v_mfma_f32_16x16x32_bf16 v[124:127], v[176:179], v[208:211], v[124:127]
	v_mfma_f32_16x16x32_bf16 v[120:123], v[184:187], v[208:211], v[120:123]
	v_mfma_f32_16x16x32_bf16 v[116:119], v[176:179], v[216:219], v[116:119]
	v_mfma_f32_16x16x32_bf16 v[108:111], v[184:187], v[216:219], v[108:111]
	v_mfma_f32_16x16x32_bf16 v[100:103], v[176:179], v[224:227], v[100:103]
	v_mfma_f32_16x16x32_bf16 v[92:95], v[184:187], v[224:227], v[92:95]
	v_mfma_f32_16x16x32_bf16 v[84:87], v[176:179], v[232:235], v[84:87]
	v_mfma_f32_16x16x32_bf16 v[76:79], v[184:187], v[232:235], v[76:79]
	v_mfma_f32_16x16x32_bf16 v[124:127], v[180:183], v[212:215], v[124:127]
	v_mfma_f32_16x16x32_bf16 v[120:123], v[188:191], v[212:215], v[120:123]
	v_mfma_f32_16x16x32_bf16 v[116:119], v[180:183], v[220:223], v[116:119]
	v_mfma_f32_16x16x32_bf16 v[108:111], v[188:191], v[220:223], v[108:111]
	v_mfma_f32_16x16x32_bf16 v[100:103], v[180:183], v[228:231], v[100:103]
	v_mfma_f32_16x16x32_bf16 v[92:95], v[188:191], v[228:231], v[92:95]
	v_mfma_f32_16x16x32_bf16 v[84:87], v[180:183], v[236:239], v[84:87]
	v_mfma_f32_16x16x32_bf16 v[76:79], v[188:191], v[236:239], v[76:79]
	v_mfma_f32_16x16x32_bf16 v[112:115], v[192:195], v[208:211], v[112:115]
	v_mfma_f32_16x16x32_bf16 v[104:107], v[200:203], v[208:211], v[104:107]
	v_mfma_f32_16x16x32_bf16 v[96:99], v[192:195], v[216:219], v[96:99]
	v_mfma_f32_16x16x32_bf16 v[88:91], v[200:203], v[216:219], v[88:91]
	v_mfma_f32_16x16x32_bf16 v[80:83], v[192:195], v[224:227], v[80:83]
	v_mfma_f32_16x16x32_bf16 v[72:75], v[200:203], v[224:227], v[72:75]
	v_mfma_f32_16x16x32_bf16 v[68:71], v[192:195], v[232:235], v[68:71]
	v_mfma_f32_16x16x32_bf16 v[64:67], v[200:203], v[232:235], v[64:67]
	v_mfma_f32_16x16x32_bf16 v[112:115], v[196:199], v[212:215], v[112:115]
	v_mfma_f32_16x16x32_bf16 v[104:107], v[204:207], v[212:215], v[104:107]
	v_mfma_f32_16x16x32_bf16 v[96:99], v[196:199], v[220:223], v[96:99]
	v_mfma_f32_16x16x32_bf16 v[88:91], v[204:207], v[220:223], v[88:91]
	v_mfma_f32_16x16x32_bf16 v[80:83], v[196:199], v[228:231], v[80:83]
	v_mfma_f32_16x16x32_bf16 v[72:75], v[204:207], v[228:231], v[72:75]
	v_mfma_f32_16x16x32_bf16 v[68:71], v[196:199], v[236:239], v[68:71]
	v_mfma_f32_16x16x32_bf16 v[64:67], v[204:207], v[236:239], v[64:67]
	s_barrier
	s_setprio 1
	s_add_i32 s3, s3, s1
	v_lshl_add_u64 v[162:163], v[242:243], 0, v[128:129]
	s_mov_b32 m0, s3
	ds_read_b128 v[208:211], v168 offset:16384
	ds_read_b128 v[212:215], v168 offset:17408
	ds_read_b128 v[216:219], v168 offset:18432
	ds_read_b128 v[220:223], v168 offset:19456
	ds_read_b128 v[224:227], v168 offset:20480
	ds_read_b128 v[228:231], v168 offset:21504
	ds_read_b128 v[232:235], v168 offset:22528
	ds_read_b128 v[236:239], v168 offset:23552
	global_load_lds_dwordx4 v[162:163], off
	v_lshl_add_u64 v[244:245], v[242:243], 0, v[144:145]
	s_add_i32 m0, s3, 0x2000
	v_lshl_add_u64 v[246:247], v[242:243], 0, s[74:75]
	s_add_i32 s3, s8, s1
	global_load_lds_dwordx4 v[244:245], off
	v_lshl_add_u64 v[248:249], v[246:247], 0, v[128:129]
	s_mov_b32 m0, s3
	v_lshl_add_u64 v[246:247], v[246:247], 0, v[144:145]
	global_load_lds_dwordx4 v[248:249], off
	s_add_i32 m0, s3, 0x2000
	v_lshl_add_u64 v[248:249], v[240:241], 0, v[146:147]
	global_load_lds_dwordx4 v[246:247], off
	v_lshl_add_u64 v[246:247], v[240:241], 0, v[148:149]
	s_mov_b32 m0, s14
	s_nop 0
	global_load_lds_dwordx4 v[246:247], off
	s_mov_b32 m0, s15
	s_nop 0
	global_load_lds_dwordx4 v[248:249], off
	s_setprio 0
	s_waitcnt vmcnt(8) lgkmcnt(0)
	s_barrier
; #define PG8_STAGE(bufoff, gbase, voff) do { _Pragma("unroll") for (int _i = 0; _i < 2; ++_i) \
;         __builtin_amdgcn_global_load_lds((const unsigned*)((const char*)(gbase) + (voff)[_i]), (PG8_LAS unsigned*)(lds + (bufoff) + ldsw + _i * 8192), 16, 0, 0); } while (0)
; #define PG8_LDA(dst, b, h) do { _Pragma("unroll") for (int m = 0; m < 4; ++m) _Pragma("unroll") for (int k = 0; k < 2; ++k) dst[m][k] = *(const PG8_LAS bf16x8*)(lds + PG8_SA(b, h) + aoff + m * 2048 + k * 1024); } while (0)
; #define PG8_LDB(dst, b, h) do { _Pragma("unroll") for (int n = 0; n < 2; ++n) _Pragma("unroll") for (int k = 0; k < 2; ++k) dst[n][k] = *(const PG8_LAS bf16x8*)(lds + PG8_SB(b, h) + boff + n * 2048 + k * 1024); } while (0)
; #define PG8_MMA(ai, bj, At, Bt) do { __builtin_amdgcn_s_setprio(1); _Pragma("unroll") for (int m = 0; m < 4; ++m) _Pragma("unroll") for (int n = 0; n < 2; ++n) _Pragma("unroll") for (int k = 0; k < 2; ++k) \
;         acc[ai][bj][m][n] = __builtin_amdgcn_mfma_f32_16x16x32_bf16(Bt[n][k], At[m][k], acc[ai][bj][m][n], 0, 0, 0); __builtin_amdgcn_s_setprio(0); } while (0)
; #define PG8_WAIT_V(n) asm volatile("s_waitcnt vmcnt(" #n ")" ::: "memory")
; #define PG8_WAIT_L(n) asm volatile("s_waitcnt lgkmcnt(" #n ")" ::: "memory")
; #define PG8_BAR __builtin_amdgcn_s_barrier()
; #define PG8_SCHED __builtin_amdgcn_sched_barrier(0)
; template <class Epi, class Sched, bool ALIGN_EPI = false, bool SP2 = false>
; __device__ __forceinline__ void gemm_phase(PG8_LAS unsigned char* lds, const Gemm g, const Sched& S, const Epi& E, int tid_in) {
;     ...
;             PG8_WAIT_V(8); PG8_WAIT_L(0); PG8_BAR; PG8_MMA(1, 0, At, B0); PG8_MMA(1, 1, At, B1); PG8_BAR; PG8_SCHED;
;             PG8_LDB(B0, 1, 0); PG8_LDB(B1, 1, 1); PG8_SCHED; PG8_LDA(At, 1, 0); PG8_STAGE(PG8_SA(0, 1), a2 + hstep, voffA);
;             PG8_WAIT_V(8); PG8_WAIT_L(0); PG8_BAR; PG8_MMA(0, 0, At, B0); PG8_MMA(0, 1, At, B1); PG8_BAR; PG8_SCHED;
;             PG8_LDA(At, 1, 1); PG8_STAGE(PG8_SB(1, 0), b3, voffB); PG8_STAGE(PG8_SB(1, 1), b3 + hstep, voffB); PG8_STAGE(PG8_SA(1, 0), a3, voffA);
	v_mfma_f32_16x16x32_bf16 v[60:63], v[176:179], v[208:211], v[60:63]
	v_mfma_f32_16x16x32_bf16 v[56:59], v[184:187], v[208:211], v[56:59]
	v_mfma_f32_16x16x32_bf16 v[52:55], v[176:179], v[216:219], v[52:55]
	v_mfma_f32_16x16x32_bf16 v[44:47], v[184:187], v[216:219], v[44:47]
	v_mfma_f32_16x16x32_bf16 v[36:39], v[176:179], v[224:227], v[36:39]
	v_mfma_f32_16x16x32_bf16 v[28:31], v[184:187], v[224:227], v[28:31]
	v_mfma_f32_16x16x32_bf16 v[20:23], v[176:179], v[232:235], v[20:23]
	v_mfma_f32_16x16x32_bf16 v[12:15], v[184:187], v[232:235], v[12:15]
	v_mfma_f32_16x16x32_bf16 v[60:63], v[180:183], v[212:215], v[60:63]
	v_mfma_f32_16x16x32_bf16 v[56:59], v[188:191], v[212:215], v[56:59]
	v_mfma_f32_16x16x32_bf16 v[52:55], v[180:183], v[220:223], v[52:55]
	v_mfma_f32_16x16x32_bf16 v[44:47], v[188:191], v[220:223], v[44:47]
	v_mfma_f32_16x16x32_bf16 v[36:39], v[180:183], v[228:231], v[36:39]
	v_mfma_f32_16x16x32_bf16 v[28:31], v[188:191], v[228:231], v[28:31]
	v_mfma_f32_16x16x32_bf16 v[20:23], v[180:183], v[236:239], v[20:23]
	v_mfma_f32_16x16x32_bf16 v[12:15], v[188:191], v[236:239], v[12:15]
	v_mfma_f32_16x16x32_bf16 v[48:51], v[192:195], v[208:211], v[48:51]
	v_mfma_f32_16x16x32_bf16 v[40:43], v[200:203], v[208:211], v[40:43]
	v_mfma_f32_16x16x32_bf16 v[32:35], v[192:195], v[216:219], v[32:35]
	v_mfma_f32_16x16x32_bf16 v[24:27], v[200:203], v[216:219], v[24:27]
	v_mfma_f32_16x16x32_bf16 v[16:19], v[192:195], v[224:227], v[16:19]
	v_mfma_f32_16x16x32_bf16 v[8:11], v[200:203], v[224:227], v[8:11]
	v_mfma_f32_16x16x32_bf16 v[4:7], v[192:195], v[232:235], v[4:7]
	v_mfma_f32_16x16x32_bf16 v[0:3], v[200:203], v[232:235], v[0:3]
	v_mfma_f32_16x16x32_bf16 v[48:51], v[196:199], v[212:215], v[48:51]
	v_mfma_f32_16x16x32_bf16 v[40:43], v[204:207], v[212:215], v[40:43]
	v_mfma_f32_16x16x32_bf16 v[32:35], v[196:199], v[220:223], v[32:35]
	v_mfma_f32_16x16x32_bf16 v[24:27], v[204:207], v[220:223], v[24:27]
	v_mfma_f32_16x16x32_bf16 v[16:19], v[196:199], v[228:231], v[16:19]
	v_mfma_f32_16x16x32_bf16 v[8:11], v[204:207], v[228:231], v[8:11]
	v_mfma_f32_16x16x32_bf16 v[4:7], v[196:199], v[236:239], v[4:7]
	v_mfma_f32_16x16x32_bf16 v[0:3], v[204:207], v[236:239], v[0:3]
	s_barrier
	s_setprio 1
	s_add_i32 s3, 0, 0x18000
	s_add_i32 s8, 0, 0x1c000
	ds_read_b128 v[176:179], v173 offset:32768
	ds_read_b128 v[180:183], v173 offset:33792
	ds_read_b128 v[184:187], v173 offset:34816
	ds_read_b128 v[188:191], v173 offset:35840
	ds_read_b128 v[192:195], v173 offset:49152
	ds_read_b128 v[196:199], v173 offset:50176
	ds_read_b128 v[200:203], v173 offset:51200
	ds_read_b128 v[204:207], v173 offset:52224
	v_lshl_add_u64 v[240:241], v[240:241], 0, s[74:75]
	s_mov_b32 m0, s16
	v_lshl_add_u64 v[250:251], v[240:241], 0, v[148:149]
	ds_read_b128 v[208:211], v168 offset:32768
	ds_read_b128 v[212:215], v168 offset:33792
	ds_read_b128 v[216:219], v168 offset:34816
	ds_read_b128 v[220:223], v168 offset:35840
	ds_read_b128 v[224:227], v168 offset:36864
	ds_read_b128 v[228:231], v168 offset:37888
	ds_read_b128 v[232:235], v168 offset:38912
	ds_read_b128 v[236:239], v168 offset:39936
	global_load_lds_dwordx4 v[250:251], off
	v_lshl_add_u64 v[240:241], v[240:241], 0, v[146:147]
	s_mov_b32 m0, s17
	s_nop 0
	global_load_lds_dwordx4 v[240:241], off
	s_setprio 0
	s_waitcnt vmcnt(8) lgkmcnt(0)
	s_barrier
	v_mfma_f32_16x16x32_bf16 v[124:127], v[176:179], v[208:211], v[124:127]
	v_mfma_f32_16x16x32_bf16 v[120:123], v[184:187], v[208:211], v[120:123]
	v_mfma_f32_16x16x32_bf16 v[116:119], v[176:179], v[216:219], v[116:119]
	v_mfma_f32_16x16x32_bf16 v[108:111], v[184:187], v[216:219], v[108:111]
	v_mfma_f32_16x16x32_bf16 v[100:103], v[176:179], v[224:227], v[100:103]
	v_mfma_f32_16x16x32_bf16 v[92:95], v[184:187], v[224:227], v[92:95]
	v_mfma_f32_16x16x32_bf16 v[84:87], v[176:179], v[232:235], v[84:87]
	v_mfma_f32_16x16x32_bf16 v[76:79], v[184:187], v[232:235], v[76:79]
	v_mfma_f32_16x16x32_bf16 v[124:127], v[180:183], v[212:215], v[124:127]
	v_mfma_f32_16x16x32_bf16 v[120:123], v[188:191], v[212:215], v[120:123]
	v_mfma_f32_16x16x32_bf16 v[116:119], v[180:183], v[220:223], v[116:119]
	v_mfma_f32_16x16x32_bf16 v[108:111], v[188:191], v[220:223], v[108:111]
	v_mfma_f32_16x16x32_bf16 v[100:103], v[180:183], v[228:231], v[100:103]
	v_mfma_f32_16x16x32_bf16 v[92:95], v[188:191], v[228:231], v[92:95]
	v_mfma_f32_16x16x32_bf16 v[84:87], v[180:183], v[236:239], v[84:87]
	v_mfma_f32_16x16x32_bf16 v[76:79], v[188:191], v[236:239], v[76:79]
	v_mfma_f32_16x16x32_bf16 v[112:115], v[192:195], v[208:211], v[112:115]
	v_mfma_f32_16x16x32_bf16 v[104:107], v[200:203], v[208:211], v[104:107]
	v_mfma_f32_16x16x32_bf16 v[96:99], v[192:195], v[216:219], v[96:99]
	v_mfma_f32_16x16x32_bf16 v[88:91], v[200:203], v[216:219], v[88:91]
	v_mfma_f32_16x16x32_bf16 v[80:83], v[192:195], v[224:227], v[80:83]
	v_mfma_f32_16x16x32_bf16 v[72:75], v[200:203], v[224:227], v[72:75]
	v_mfma_f32_16x16x32_bf16 v[68:71], v[192:195], v[232:235], v[68:71]
	v_mfma_f32_16x16x32_bf16 v[64:67], v[200:203], v[232:235], v[64:67]
	v_mfma_f32_16x16x32_bf16 v[112:115], v[196:199], v[212:215], v[112:115]
	v_mfma_f32_16x16x32_bf16 v[104:107], v[204:207], v[212:215], v[104:107]
	v_mfma_f32_16x16x32_bf16 v[96:99], v[196:199], v[220:223], v[96:99]
	v_mfma_f32_16x16x32_bf16 v[88:91], v[204:207], v[220:223], v[88:91]
	v_mfma_f32_16x16x32_bf16 v[80:83], v[196:199], v[228:231], v[80:83]
	v_mfma_f32_16x16x32_bf16 v[72:75], v[204:207], v[228:231], v[72:75]
	v_mfma_f32_16x16x32_bf16 v[68:71], v[196:199], v[236:239], v[68:71]
	v_mfma_f32_16x16x32_bf16 v[64:67], v[204:207], v[236:239], v[64:67]
	s_barrier
; #define PG8_STAGE(bufoff, gbase, voff) do { _Pragma("unroll") for (int _i = 0; _i < 2; ++_i) \
;         __builtin_amdgcn_global_load_lds((const unsigned*)((const char*)(gbase) + (voff)[_i]), (PG8_LAS unsigned*)(lds + (bufoff) + ldsw + _i * 8192), 16, 0, 0); } while (0)
; #define PG8_LDA(dst, b, h) do { _Pragma("unroll") for (int m = 0; m < 4; ++m) _Pragma("unroll") for (int k = 0; k < 2; ++k) dst[m][k] = *(const PG8_LAS bf16x8*)(lds + PG8_SA(b, h) + aoff + m * 2048 + k * 1024); } while (0)
; #define PG8_MMA(ai, bj, At, Bt) do { __builtin_amdgcn_s_setprio(1); _Pragma("unroll") for (int m = 0; m < 4; ++m) _Pragma("unroll") for (int n = 0; n < 2; ++n) _Pragma("unroll") for (int k = 0; k < 2; ++k) \
;         acc[ai][bj][m][n] = __builtin_amdgcn_mfma_f32_16x16x32_bf16(Bt[n][k], At[m][k], acc[ai][bj][m][n], 0, 0, 0); __builtin_amdgcn_s_setprio(0); } while (0)
; #define PG8_WAIT_V(n) asm volatile("s_waitcnt vmcnt(" #n ")" ::: "memory")
; #define PG8_WAIT_L(n) asm volatile("s_waitcnt lgkmcnt(" #n ")" ::: "memory")
; #define PG8_BAR __builtin_amdgcn_s_barrier()
; #define PG8_SCHED __builtin_amdgcn_sched_barrier(0)
; template <class Epi, class Sched, bool ALIGN_EPI = false, bool SP2 = false>
; __device__ __forceinline__ void gemm_phase(PG8_LAS unsigned char* lds, const Gemm g, const Sched& S, const Epi& E, int tid_in) {
;     ...
;         for (int t = 0; t < nt; t += 2) {
;     ...
;             PG8_LDA(At, 1, 1); PG8_STAGE(PG8_SB(1, 0), b3, voffB); PG8_STAGE(PG8_SB(1, 1), b3 + hstep, voffB); PG8_STAGE(PG8_SA(1, 0), a3, voffA);
;             PG8_WAIT_V(8); PG8_WAIT_L(0); PG8_BAR; PG8_MMA(1, 0, At, B0); PG8_MMA(1, 1, At, B1); PG8_BAR; PG8_SCHED;
	s_setprio 1
	s_add_i32 s3, s3, s1
	v_lshl_add_u64 v[162:163], v[162:163], 0, s[70:71]
	s_mov_b32 m0, s3
	ds_read_b128 v[208:211], v168 offset:49152
	ds_read_b128 v[212:215], v168 offset:50176
	ds_read_b128 v[216:219], v168 offset:51200
	ds_read_b128 v[220:223], v168 offset:52224
	ds_read_b128 v[224:227], v168 offset:53248
	ds_read_b128 v[228:231], v168 offset:54272
	ds_read_b128 v[232:235], v168 offset:55296
	ds_read_b128 v[236:239], v168 offset:56320
	global_load_lds_dwordx4 v[162:163], off
	v_lshl_add_u64 v[162:163], v[244:245], 0, s[70:71]
	s_add_i32 m0, s3, 0x2000
	s_add_i32 s3, s8, s1
	global_load_lds_dwordx4 v[162:163], off
	v_lshl_add_u64 v[162:163], v[242:243], 0, s[60:61]
	v_lshl_add_u64 v[240:241], v[162:163], 0, v[128:129]
	s_mov_b32 m0, s3
	v_lshl_add_u64 v[162:163], v[162:163], 0, v[144:145]
	global_load_lds_dwordx4 v[240:241], off
	s_add_i32 m0, s3, 0x2000
	s_nop 0
	global_load_lds_dwordx4 v[162:163], off
	v_lshl_add_u64 v[162:163], v[246:247], 0, s[70:71]
	s_mov_b32 m0, s18
	s_nop 0
	global_load_lds_dwordx4 v[162:163], off
	v_lshl_add_u64 v[162:163], v[248:249], 0, s[70:71]
	s_mov_b32 m0, s19
	s_nop 0
	global_load_lds_dwordx4 v[162:163], off
	s_setprio 0
	s_waitcnt vmcnt(8) lgkmcnt(0)
	s_barrier
	v_mfma_f32_16x16x32_bf16 v[60:63], v[176:179], v[208:211], v[60:63]
	v_mfma_f32_16x16x32_bf16 v[56:59], v[184:187], v[208:211], v[56:59]
	v_mfma_f32_16x16x32_bf16 v[52:55], v[176:179], v[216:219], v[52:55]
	v_mfma_f32_16x16x32_bf16 v[44:47], v[184:187], v[216:219], v[44:47]
	v_mfma_f32_16x16x32_bf16 v[36:39], v[176:179], v[224:227], v[36:39]
	v_mfma_f32_16x16x32_bf16 v[28:31], v[184:187], v[224:227], v[28:31]
	v_mfma_f32_16x16x32_bf16 v[20:23], v[176:179], v[232:235], v[20:23]
	v_mfma_f32_16x16x32_bf16 v[12:15], v[184:187], v[232:235], v[12:15]
	v_mfma_f32_16x16x32_bf16 v[60:63], v[180:183], v[212:215], v[60:63]
	v_mfma_f32_16x16x32_bf16 v[56:59], v[188:191], v[212:215], v[56:59]
	v_mfma_f32_16x16x32_bf16 v[52:55], v[180:183], v[220:223], v[52:55]
	v_mfma_f32_16x16x32_bf16 v[44:47], v[188:191], v[220:223], v[44:47]
	v_mfma_f32_16x16x32_bf16 v[36:39], v[180:183], v[228:231], v[36:39]
	v_mfma_f32_16x16x32_bf16 v[28:31], v[188:191], v[228:231], v[28:31]
	v_mfma_f32_16x16x32_bf16 v[20:23], v[180:183], v[236:239], v[20:23]
	v_mfma_f32_16x16x32_bf16 v[12:15], v[188:191], v[236:239], v[12:15]
	v_mfma_f32_16x16x32_bf16 v[48:51], v[192:195], v[208:211], v[48:51]
	v_mfma_f32_16x16x32_bf16 v[40:43], v[200:203], v[208:211], v[40:43]
	v_mfma_f32_16x16x32_bf16 v[32:35], v[192:195], v[216:219], v[32:35]
	v_mfma_f32_16x16x32_bf16 v[24:27], v[200:203], v[216:219], v[24:27]
	v_mfma_f32_16x16x32_bf16 v[16:19], v[192:195], v[224:227], v[16:19]
	v_mfma_f32_16x16x32_bf16 v[8:11], v[200:203], v[224:227], v[8:11]
	v_mfma_f32_16x16x32_bf16 v[4:7], v[192:195], v[232:235], v[4:7]
	v_mfma_f32_16x16x32_bf16 v[0:3], v[200:203], v[232:235], v[0:3]
	v_mfma_f32_16x16x32_bf16 v[48:51], v[196:199], v[212:215], v[48:51]
	v_mfma_f32_16x16x32_bf16 v[40:43], v[204:207], v[212:215], v[40:43]
	v_mfma_f32_16x16x32_bf16 v[32:35], v[196:199], v[220:223], v[32:35]
	v_mfma_f32_16x16x32_bf16 v[24:27], v[204:207], v[220:223], v[24:27]
	v_mfma_f32_16x16x32_bf16 v[16:19], v[196:199], v[228:231], v[16:19]
	v_mfma_f32_16x16x32_bf16 v[8:11], v[204:207], v[228:231], v[8:11]
	v_mfma_f32_16x16x32_bf16 v[4:7], v[196:199], v[236:239], v[4:7]
	v_mfma_f32_16x16x32_bf16 v[0:3], v[204:207], v[236:239], v[0:3]
	s_barrier
	s_setprio 1
	s_add_i32 s2, s2, 2
	v_lshl_add_u64 v[160:161], v[160:161], 0, s[82:83]
	s_cmpk_gt_u32 s2, 0x55
	v_mov_b64_e32 v[162:163], v[164:165]
	s_cbranch_scc0 .LBB0_683
	s_setprio 0
	s_and_b64 vcc, exec, s[12:13]
	s_cbranch_vccz .LBB0_686
	s_barrier

; __device__ __forceinline__ float dot4(f32x4 a) { return (a.x * a.x + a.y * a.y) + (a.z * a.z + a.w * a.w); }
; __device__ __forceinline__ f32x4 bf4lo(u32x4 w) { return (f32x4){bflo(w.x), bfhi(w.x), bflo(w.y), bfhi(w.y)}; }
; __device__ __forceinline__ f32x4 bf4hi(u32x4 w) { return (f32x4){bflo(w.z), bfhi(w.z), bflo(w.w), bfhi(w.w)}; }
; __device__ __forceinline__ void normres_phase(const bf16_t* hf, const float* xsrc, const float* gprev, bf16_t* HI, bf16_t* LO, float* RS, float* xdst, const float* gpost, float w, const float* gpre, ...
;     ...
;         for (int q = 0; q < 2; ++q) { if (q == 1 && !two) break; const int rr = q ? rowb : row;
;             float ss = 0.f;
; #pragma unroll
;             for (int c = 0; c < 4; ++c) ss += dot4(bf4lo(hw[q][c])) + dot4(bf4hi(hw[q][c]));
;             const float rs = rsqrtf(wave_sum(ss) * (1.f / D) + EPS) * w; float ss2 = 0.f;
.LBB0_795:
	s_or_b64 exec, exec, s[22:23]
	v_lshl_add_u64 v[44:45], v[36:37], 1, v[92:93]
	v_lshl_add_u64 v[80:81], v[80:81], 1, v[92:93]
	flat_load_dwordx4 v[32:35], v[44:45] offset:3072
	flat_load_dwordx4 v[36:39], v[44:45] offset:2048
	flat_load_dwordx4 v[40:43], v[44:45] offset:1024
	s_nop 0
	flat_load_dwordx4 v[44:47], v[44:45]
	s_nop 0
	flat_load_dwordx4 v[84:87], v[80:81] offset:3072
	flat_load_dwordx4 v[146:149], v[80:81] offset:2048
	flat_load_dwordx4 v[150:153], v[80:81] offset:1024
	s_nop 0
	flat_load_dwordx4 v[80:83], v[80:81]
	v_and_b32_e32 v128, 64, v171
	v_add_u32_e32 v128, 64, v128
	v_xor_b32_e32 v154, 1, v171
	v_cmp_lt_i32_e32 vcc, v154, v128
	s_waitcnt vmcnt(0) lgkmcnt(0)
	v_lshlrev_b32_e32 v158, 16, v146
	v_cndmask_b32_e32 v154, v171, v154, vcc
	v_lshlrev_b32_e32 v175, 2, v154
	v_xor_b32_e32 v154, 2, v171
	v_cmp_lt_i32_e32 vcc, v154, v128
	v_and_b32_e32 v185, 0xffff0000, v81
	v_and_b32_e32 v184, 0xffff0000, v80
	v_cndmask_b32_e32 v154, v171, v154, vcc
	v_lshlrev_b32_e32 v176, 2, v154
	v_xor_b32_e32 v154, 4, v171
	v_cmp_lt_i32_e32 vcc, v154, v128
	v_lshlrev_b32_e32 v183, 16, v81
	v_lshlrev_b32_e32 v182, 16, v80
	v_cndmask_b32_e32 v154, v171, v154, vcc
	v_lshlrev_b32_e32 v177, 2, v154
	v_xor_b32_e32 v154, 8, v171
	v_cmp_lt_i32_e32 vcc, v154, v128
	v_pk_mul_f32 v[80:81], v[184:185], v[184:185]
	v_and_b32_e32 v169, 0xffff0000, v151
	v_cndmask_b32_e32 v154, v171, v154, vcc
	v_lshlrev_b32_e32 v178, 2, v154
	v_xor_b32_e32 v154, 16, v171
	v_cmp_lt_i32_e32 vcc, v154, v128
	v_pk_fma_f32 v[80:81], v[182:183], v[182:183], v[80:81]
	v_and_b32_e32 v168, 0xffff0000, v150
	v_cndmask_b32_e32 v154, v171, v154, vcc
	v_lshlrev_b32_e32 v179, 2, v154
	v_xor_b32_e32 v154, 32, v171
	v_cmp_lt_i32_e32 vcc, v154, v128
	v_pk_add_f32 v[186:187], v[80:81], v[80:81] op_sel_hi:[0,1]
	v_lshlrev_b32_e32 v81, 16, v83
	v_lshlrev_b32_e32 v80, 16, v82
	v_and_b32_e32 v83, 0xffff0000, v83
	v_and_b32_e32 v82, 0xffff0000, v82
	v_cndmask_b32_e32 v128, v171, v154, vcc
	v_pk_mul_f32 v[154:155], v[82:83], v[82:83]
	v_lshlrev_b32_e32 v180, 2, v128
	v_pk_fma_f32 v[154:155], v[80:81], v[80:81], v[154:155]
	v_lshlrev_b32_e32 v167, 16, v151
	v_lshlrev_b32_e32 v166, 16, v150
	v_pk_mul_f32 v[150:151], v[168:169], v[168:169]
	v_and_b32_e32 v159, 0xffff0000, v146
	v_mul_f32_e32 v128, v158, v158
	v_lshlrev_b32_e32 v160, 16, v147
	v_pk_add_f32 v[188:189], v[154:155], v[154:155] op_sel_hi:[0,1]
	v_pk_fma_f32 v[150:151], v[166:167], v[166:167], v[150:151]
	v_and_b32_e32 v165, 0xffff0000, v153
	v_and_b32_e32 v164, 0xffff0000, v152
	v_pk_fma_f32 v[194:195], v[158:159], v[158:159], v[128:129] op_sel_hi:[1,1,0]
	v_and_b32_e32 v161, 0xffff0000, v147
	v_mul_f32_e32 v128, v160, v160
	v_lshlrev_b32_e32 v154, 16, v148
	v_pk_add_f32 v[190:191], v[150:151], v[150:151] op_sel_hi:[0,1]
	v_lshlrev_b32_e32 v163, 16, v153
	v_lshlrev_b32_e32 v162, 16, v152
	v_pk_mul_f32 v[150:151], v[164:165], v[164:165]
	v_pk_fma_f32 v[196:197], v[160:161], v[160:161], v[128:129] op_sel_hi:[1,1,0]
	v_and_b32_e32 v155, 0xffff0000, v148
	v_mul_f32_e32 v128, v154, v154
	v_lshlrev_b32_e32 v156, 16, v149
	v_pk_fma_f32 v[150:151], v[162:163], v[162:163], v[150:151]
	v_pk_fma_f32 v[198:199], v[154:155], v[154:155], v[128:129] op_sel_hi:[1,1,0]
	v_and_b32_e32 v157, 0xffff0000, v149
	v_mul_f32_e32 v128, v156, v156
	v_pk_add_f32 v[192:193], v[150:151], v[150:151] op_sel_hi:[0,1]
	v_pk_fma_f32 v[200:201], v[156:157], v[156:157], v[128:129] op_sel_hi:[1,1,0]
	v_lshlrev_b32_e32 v150, 16, v84
	v_and_b32_e32 v151, 0xffff0000, v84
	v_lshlrev_b32_e32 v152, 16, v85
	v_and_b32_e32 v153, 0xffff0000, v85
	v_mul_f32_e32 v194, v150, v150
	v_mul_f32_e32 v196, v151, v151
	v_mul_f32_e32 v198, v152, v152
	v_mul_f32_e32 v200, v153, v153
	v_lshlrev_b32_e32 v146, 16, v86
	v_and_b32_e32 v147, 0xffff0000, v86
	v_lshlrev_b32_e32 v148, 16, v87
	v_and_b32_e32 v149, 0xffff0000, v87
	v_mul_f32_e32 v190, v146, v146
	v_mul_f32_e32 v192, v147, v147
	v_mul_f32_e32 v186, v148, v148
	v_mul_f32_e32 v188, v149, v149
	v_pk_add_f32 v[84:85], v[194:195], v[196:197]
	v_pk_add_f32 v[86:87], v[198:199], v[200:201]
	v_pk_add_f32 v[186:187], v[186:187], v[188:189]
	v_pk_add_f32 v[84:85], v[84:85], v[86:87]
	v_pk_add_f32 v[86:87], v[190:191], v[192:193]
	s_nop 0
	v_pk_add_f32 v[86:87], v[86:87], v[186:187]
	s_nop 0
	v_pk_add_f32 v[84:85], v[84:85], v[86:87]
	s_nop 0
	v_add_f32_e32 v84, v84, v85
	ds_bpermute_b32 v85, v175, v84
	s_waitcnt lgkmcnt(0)
; __device__ __forceinline__ float dot4(f32x4 a) { return (a.x * a.x + a.y * a.y) + (a.z * a.z + a.w * a.w); }
; __device__ __forceinline__ f32x4 bf4lo(u32x4 w) { return (f32x4){bflo(w.x), bfhi(w.x), bflo(w.y), bfhi(w.y)}; }
; __device__ __forceinline__ f32x4 bf4hi(u32x4 w) { return (f32x4){bflo(w.z), bfhi(w.z), bflo(w.w), bfhi(w.w)}; }
; __device__ __forceinline__ void normres_phase(const bf16_t* hf, const float* xsrc, const float* gprev, bf16_t* HI, bf16_t* LO, float* RS, float* xdst, const float* gpost, float w, const float* gpre, ...
;     ...
;             const float rs = rsqrtf(wave_sum(ss) * (1.f / D) + EPS) * w; float ss2 = 0.f;
;             const f32x4* gp4 = (const f32x4*)gpost + 2 * lane;
; #pragma unroll
;             for (int c = 0; c < 4; ++c) { xv[q][2 * c] = xv[q][2 * c] + bf4lo(hw[q][c]) * rs * gp4[128 * c]; xv[q][2 * c + 1] = xv[q][2 * c + 1] + bf4hi(hw[q][c]) * rs * gp4[128 * c + 1];
;                 ss2 += dot4(xv[q][2 * c]) + dot4(xv[q][2 * c + 1]); }
;             if (xdst) {
;                 f32x4* xo = (f32x4*)(xdst + (size_t)rr * D) + 2 * lane;
; #pragma unroll
;                 for (int c = 0; c < 4; ++c) { xo[128 * c] = xv[q][2 * c]; xo[128 * c + 1] = xv[q][2 * c + 1]; }
	v_add_f32_e32 v84, v84, v85
	ds_bpermute_b32 v85, v176, v84
	s_waitcnt lgkmcnt(0)
	v_add_f32_e32 v84, v84, v85
	ds_bpermute_b32 v85, v177, v84
	s_waitcnt lgkmcnt(0)
	v_add_f32_e32 v84, v84, v85
	ds_bpermute_b32 v85, v178, v84
	s_waitcnt lgkmcnt(0)
	v_add_f32_e32 v84, v84, v85
	ds_bpermute_b32 v85, v179, v84
	s_waitcnt lgkmcnt(0)
	v_add_f32_e32 v84, v84, v85
	ds_bpermute_b32 v85, v180, v84
	s_waitcnt lgkmcnt(0)
	v_add_f32_e32 v84, v84, v85
	v_mov_b32_e32 v130, 0x358637bd
	v_fmamk_f32 v84, v84, 0x3a000000, v130
	v_cmp_gt_f32_e32 vcc, s92, v84
	v_mul_f32_e32 v85, 0x4b800000, v84
	s_nop 0
	v_cndmask_b32_e32 v84, v84, v85, vcc
	v_rsq_f32_e32 v84, v84
	s_nop 0
	v_mul_f32_e32 v85, 0x45800000, v84
	v_cndmask_b32_e32 v84, v84, v85, vcc
	v_mul_f32_e32 v128, 0.5, v84
	v_mov_b32_e32 v85, v184
	v_mov_b32_e32 v184, v183
	v_mov_b32_e32 v84, v182
	v_pk_mul_f32 v[86:87], v[128:129], v[184:185] op_sel_hi:[0,1]
	flat_load_dwordx4 v[182:185], v[100:101]
	v_pk_mul_f32 v[84:85], v[128:129], v[84:85] op_sel_hi:[0,1]
	s_waitcnt vmcnt(0) lgkmcnt(0)
	v_pk_fma_f32 v[84:85], v[182:183], v[84:85], v[52:53]
	v_mov_b32_e32 v52, v80
	v_mov_b32_e32 v53, v82
	v_pk_fma_f32 v[86:87], v[184:185], v[86:87], v[54:55]
	v_pk_mul_f32 v[182:183], v[128:129], v[52:53] op_sel_hi:[0,1]
	flat_load_dwordx4 v[52:55], v[100:101] offset:16
	v_mov_b32_e32 v82, v81
	v_pk_mul_f32 v[80:81], v[128:129], v[82:83] op_sel_hi:[0,1]
	s_waitcnt vmcnt(0) lgkmcnt(0)
	v_pk_fma_f32 v[82:83], v[54:55], v[80:81], v[50:51]
	v_pk_fma_f32 v[80:81], v[52:53], v[182:183], v[48:49]
	v_mov_b32_e32 v48, v166
	v_mov_b32_e32 v49, v168
	v_pk_mul_f32 v[52:53], v[128:129], v[48:49] op_sel_hi:[0,1]
	flat_load_dwordx4 v[48:51], v[100:101] offset:2048
	v_mov_b32_e32 v168, v167
	v_pk_mul_f32 v[54:55], v[128:129], v[168:169] op_sel_hi:[0,1]
	s_waitcnt vmcnt(0) lgkmcnt(0)
	v_pk_fma_f32 v[52:53], v[48:49], v[52:53], v[64:65]
	v_mov_b32_e32 v48, v162
	v_mov_b32_e32 v49, v164
	v_pk_fma_f32 v[54:55], v[50:51], v[54:55], v[66:67]
	v_pk_mul_f32 v[64:65], v[128:129], v[48:49] op_sel_hi:[0,1]
	flat_load_dwordx4 v[48:51], v[100:101] offset:2064
	v_mov_b32_e32 v164, v163
	v_pk_mul_f32 v[66:67], v[128:129], v[164:165] op_sel_hi:[0,1]
	s_waitcnt vmcnt(0) lgkmcnt(0)
	v_pk_fma_f32 v[62:63], v[50:51], v[66:67], v[62:63]
	v_pk_fma_f32 v[60:61], v[48:49], v[64:65], v[60:61]
	flat_load_dwordx4 v[48:51], v[114:115]
	v_pk_mul_f32 v[64:65], v[128:129], v[158:159] op_sel_hi:[0,1]
	v_pk_mul_f32 v[66:67], v[128:129], v[160:161] op_sel_hi:[0,1]
	s_waitcnt vmcnt(0) lgkmcnt(0)
	v_pk_fma_f32 v[50:51], v[50:51], v[66:67], v[70:71]
	v_pk_fma_f32 v[48:49], v[48:49], v[64:65], v[68:69]
	flat_load_dwordx4 v[68:71], v[116:117]
	v_pk_mul_f32 v[64:65], v[128:129], v[154:155] op_sel_hi:[0,1]
	v_pk_mul_f32 v[66:67], v[128:129], v[156:157] op_sel_hi:[0,1]
	s_waitcnt vmcnt(0) lgkmcnt(0)
	v_pk_fma_f32 v[66:67], v[70:71], v[66:67], v[58:59]
	v_pk_fma_f32 v[64:65], v[68:69], v[64:65], v[56:57]
	flat_load_dwordx4 v[56:59], v[118:119]
	v_pk_mul_f32 v[68:69], v[128:129], v[150:151] op_sel_hi:[0,1]
	v_pk_mul_f32 v[70:71], v[128:129], v[152:153] op_sel_hi:[0,1]
	s_waitcnt vmcnt(0) lgkmcnt(0)
	v_pk_fma_f32 v[58:59], v[58:59], v[70:71], v[78:79]
	v_pk_fma_f32 v[56:57], v[56:57], v[68:69], v[76:77]
	flat_load_dwordx4 v[68:71], v[120:121]
	v_pk_mul_f32 v[76:77], v[128:129], v[146:147] op_sel_hi:[0,1]
	v_pk_mul_f32 v[78:79], v[128:129], v[148:149] op_sel_hi:[0,1]
	s_waitcnt vmcnt(0) lgkmcnt(0)
	v_pk_fma_f32 v[70:71], v[70:71], v[78:79], v[74:75]
	v_pk_fma_f32 v[68:69], v[68:69], v[76:77], v[72:73]
	s_and_saveexec_b64 s[0:1], s[12:13]
	s_xor_b64 s[2:3], exec, s[0:1]
	s_cbranch_execz .LBB0_798
	v_lshlrev_b64 v[72:73], 13, v[144:145]
	v_lshl_add_u64 v[72:73], v[102:103], 0, v[72:73]
	flat_store_dwordx4 v[72:73], v[84:87]
	flat_store_dwordx4 v[72:73], v[80:83] offset:16
	flat_store_dwordx4 v[72:73], v[52:55] offset:2048
	flat_store_dwordx4 v[72:73], v[60:63] offset:2064
	s_nop 0
	v_add_co_u32_e32 v52, vcc, 0x1000, v72
	s_nop 1
	v_addc_co_u32_e32 v53, vcc, 0, v73, vcc
	flat_store_dwordx4 v[52:53], v[48:51]
	flat_store_dwordx4 v[52:53], v[64:67] offset:16
	flat_store_dwordx4 v[52:53], v[56:59] offset:2048
	flat_store_dwordx4 v[52:53], v[68:71] offset:2064
	s_andn2_saveexec_b64 s[2:3], s[2:3]
	s_cbranch_execnz .LBB0_799

; __device__ __forceinline__ float dot4(f32x4 a) { return (a.x * a.x + a.y * a.y) + (a.z * a.z + a.w * a.w); }
; __device__ __forceinline__ void normres_phase(const bf16_t* hf, const float* xsrc, const float* gprev, bf16_t* HI, bf16_t* LO, float* RS, float* xdst, const float* gpost, float w, const float* gpre, ...
;     ...
;                 ss2 += dot4(xv[q][2 * c]) + dot4(xv[q][2 * c + 1]); }
;             if (xdst) {
;                 f32x4* xo = (f32x4*)(xdst + (size_t)rr * D) + 2 * lane;
; #pragma unroll
;                 for (int c = 0; c < 4; ++c) { xo[128 * c] = xv[q][2 * c]; xo[128 * c + 1] = xv[q][2 * c + 1]; }
;             } else {
;                 const float rs2 = rsqrtf(wave_sum(ss2) * (1.f / D) + EPS);
;                 const f32x4* gn4 = (const f32x4*)gpre + 2 * lane; u32x4* oh = (u32x4*)(HI + (size_t)rr * D) + lane;
; #pragma unroll
;                 for (int c = 0; c < 4; ++c) { const f32x4 y0 = xv[q][2 * c] * rs2 * gn4[128 * c], y1 = xv[q][2 * c + 1] * rs2 * gn4[128 * c + 1];
;                     oh[64 * c] = (u32x4){pk2(y0.x, y0.y), pk2(y0.z, y0.w), pk2(y1.x, y1.y), pk2(y1.z, y1.w)}; }
;                 if (lane == 0) RS[rr] = rs2;
.LBB0_799:
	v_pk_mul_f32 v[72:73], v[86:87], v[86:87]
	v_pk_mul_f32 v[74:75], v[84:85], v[84:85]
	s_nop 0
	v_pk_mov_b32 v[76:77], v[74:75], v[72:73] op_sel:[1,0]
	v_mov_b32_e32 v75, v73
	v_pk_add_f32 v[72:73], v[76:77], v[74:75]
	v_pk_mul_f32 v[74:75], v[82:83], v[82:83]
	v_pk_mul_f32 v[76:77], v[80:81], v[80:81]
	v_pk_add_f32 v[72:73], v[72:73], v[72:73] op_sel_hi:[0,1]
	v_pk_mov_b32 v[78:79], v[76:77], v[74:75] op_sel:[1,0]
	v_mov_b32_e32 v77, v75
	v_pk_add_f32 v[74:75], v[78:79], v[76:77]
	v_pk_mul_f32 v[76:77], v[54:55], v[54:55]
	v_pk_mul_f32 v[78:79], v[52:53], v[52:53]
	v_mul_f32_e32 v72, v48, v48
	v_pk_mov_b32 v[146:147], v[78:79], v[76:77] op_sel:[1,0]
	v_mov_b32_e32 v79, v77
	v_pk_add_f32 v[76:77], v[146:147], v[78:79]
	v_pk_mul_f32 v[78:79], v[62:63], v[62:63]
	v_pk_mul_f32 v[146:147], v[60:61], v[60:61]
	v_pk_add_f32 v[74:75], v[74:75], v[74:75] op_sel_hi:[0,1]
	v_pk_mov_b32 v[148:149], v[146:147], v[78:79] op_sel:[1,0]
	v_mov_b32_e32 v147, v79
	v_pk_add_f32 v[78:79], v[148:149], v[146:147]
	v_pk_fma_f32 v[146:147], v[48:49], v[48:49], v[72:73] op_sel_hi:[1,1,0]
	v_mul_f32_e32 v72, v50, v50
	v_pk_fma_f32 v[148:149], v[50:51], v[50:51], v[72:73] op_sel_hi:[1,1,0]
	v_mul_f32_e32 v72, v64, v64
	v_pk_add_f32 v[76:77], v[76:77], v[76:77] op_sel_hi:[0,1]
	v_pk_add_f32 v[78:79], v[78:79], v[78:79] op_sel_hi:[0,1]
	v_pk_fma_f32 v[150:151], v[64:65], v[64:65], v[72:73] op_sel_hi:[1,1,0]
	v_mul_f32_e32 v72, v66, v66
	v_pk_fma_f32 v[152:153], v[66:67], v[66:67], v[72:73] op_sel_hi:[1,1,0]
	v_mul_f32_e32 v72, v68, v68
	v_mul_f32_e32 v74, v69, v69
	v_mul_f32_e32 v76, v70, v70
	v_mul_f32_e32 v78, v71, v71
	v_pk_add_f32 v[72:73], v[72:73], v[74:75]
	v_pk_add_f32 v[74:75], v[76:77], v[78:79]
	flat_load_dwordx4 v[76:79], v[104:105]
	v_mul_f32_e32 v146, v56, v56
	v_mul_f32_e32 v148, v57, v57
	v_mul_f32_e32 v150, v58, v58
	v_mul_f32_e32 v152, v59, v59
	v_pk_add_f32 v[146:147], v[146:147], v[148:149]
	v_pk_add_f32 v[148:149], v[150:151], v[152:153]
	v_pk_add_f32 v[72:73], v[72:73], v[74:75]
	v_pk_add_f32 v[146:147], v[146:147], v[148:149]
	v_lshlrev_b64 v[74:75], 12, v[144:145]
	v_pk_add_f32 v[72:73], v[146:147], v[72:73]
	v_lshl_add_u64 v[74:75], v[96:97], 0, v[74:75]
	v_add_f32_e32 v72, v72, v73
	ds_bpermute_b32 v73, v175, v72
	s_waitcnt lgkmcnt(0)
	v_add_f32_e32 v72, v72, v73
	ds_bpermute_b32 v73, v176, v72
	s_waitcnt lgkmcnt(0)
	v_add_f32_e32 v72, v72, v73
	ds_bpermute_b32 v73, v177, v72
	s_waitcnt lgkmcnt(0)
	v_add_f32_e32 v72, v72, v73
	ds_bpermute_b32 v73, v178, v72
	s_waitcnt lgkmcnt(0)
	v_add_f32_e32 v72, v72, v73
	ds_bpermute_b32 v73, v179, v72
	s_waitcnt lgkmcnt(0)
	v_add_f32_e32 v72, v72, v73
	ds_bpermute_b32 v73, v180, v72
	s_waitcnt lgkmcnt(0)
	v_add_f32_e32 v72, v72, v73
	v_mov_b32_e32 v130, 0x358637bd
	v_fmamk_f32 v72, v72, 0x3a000000, v130
	v_cmp_gt_f32_e32 vcc, s92, v72
	v_mul_f32_e32 v73, 0x4b800000, v72
	s_nop 0
	v_cndmask_b32_e32 v72, v72, v73, vcc
	v_rsq_f32_e32 v72, v72
	s_nop 0
	v_mul_f32_e32 v73, 0x45800000, v72
	v_cndmask_b32_e32 v72, v72, v73, vcc
	v_pk_mul_f32 v[84:85], v[84:85], v[72:73] op_sel_hi:[1,0]
	v_pk_mul_f32 v[86:87], v[86:87], v[72:73] op_sel_hi:[1,0]
	v_pk_mul_f32 v[80:81], v[80:81], v[72:73] op_sel_hi:[1,0]
	v_pk_mul_f32 v[82:83], v[82:83], v[72:73] op_sel_hi:[1,0]
	v_pk_mul_f32 v[60:61], v[60:61], v[72:73] op_sel_hi:[1,0]
	v_pk_mul_f32 v[62:63], v[62:63], v[72:73] op_sel_hi:[1,0]
	s_waitcnt vmcnt(0)
	v_pk_mul_f32 v[86:87], v[78:79], v[86:87]
	v_pk_mul_f32 v[84:85], v[76:77], v[84:85]
	flat_load_dwordx4 v[76:79], v[104:105] offset:16
	s_waitcnt vmcnt(0) lgkmcnt(0)
	v_pk_mul_f32 v[82:83], v[78:79], v[82:83]
	v_pk_mul_f32 v[78:79], v[76:77], v[80:81]
	v_cvt_pk_bf16_f32 v76, v84, v85
	v_cvt_pk_bf16_f32 v77, v86, v87
	v_cvt_pk_bf16_f32 v78, v78, v79
	v_cvt_pk_bf16_f32 v79, v82, v83
	flat_store_dwordx4 v[74:75], v[76:79]
	s_nop 1
	v_pk_mul_f32 v[76:77], v[52:53], v[72:73] op_sel_hi:[1,0]
	v_pk_mul_f32 v[78:79], v[54:55], v[72:73] op_sel_hi:[1,0]
	flat_load_dwordx4 v[52:55], v[104:105] offset:2048
	s_waitcnt vmcnt(0) lgkmcnt(0)
	v_pk_mul_f32 v[78:79], v[54:55], v[78:79]
	v_pk_mul_f32 v[76:77], v[52:53], v[76:77]
	flat_load_dwordx4 v[52:55], v[104:105] offset:2064
	s_waitcnt vmcnt(0) lgkmcnt(0)
	v_pk_mul_f32 v[62:63], v[54:55], v[62:63]
	v_pk_mul_f32 v[54:55], v[52:53], v[60:61]
	v_cvt_pk_bf16_f32 v52, v76, v77
	v_cvt_pk_bf16_f32 v53, v78, v79
	v_cvt_pk_bf16_f32 v54, v54, v55
	v_cvt_pk_bf16_f32 v55, v62, v63
	flat_store_dwordx4 v[74:75], v[52:55] offset:1024
	v_pk_mul_f32 v[60:61], v[64:65], v[72:73] op_sel_hi:[1,0]
	v_pk_mul_f32 v[62:63], v[66:67], v[72:73] op_sel_hi:[1,0]
	v_pk_mul_f32 v[52:53], v[48:49], v[72:73] op_sel_hi:[1,0]
	v_pk_mul_f32 v[54:55], v[50:51], v[72:73] op_sel_hi:[1,0]
	flat_load_dwordx4 v[48:51], v[122:123]
	s_waitcnt vmcnt(0) lgkmcnt(0)
	v_pk_mul_f32 v[54:55], v[50:51], v[54:55]
	v_pk_mul_f32 v[52:53], v[48:49], v[52:53]
	flat_load_dwordx4 v[48:51], v[124:125]
	s_waitcnt vmcnt(0) lgkmcnt(0)
	v_pk_mul_f32 v[62:63], v[50:51], v[62:63]
	v_pk_mul_f32 v[50:51], v[48:49], v[60:61]
	v_cvt_pk_bf16_f32 v48, v52, v53
	v_cvt_pk_bf16_f32 v49, v54, v55
	v_cvt_pk_bf16_f32 v50, v50, v51
	v_cvt_pk_bf16_f32 v51, v62, v63
	flat_store_dwordx4 v[74:75], v[48:51] offset:2048
	flat_load_dwordx4 v[48:51], v[126:127]
	v_pk_mul_f32 v[52:53], v[56:57], v[72:73] op_sel_hi:[1,0]
	v_pk_mul_f32 v[54:55], v[58:59], v[72:73] op_sel_hi:[1,0]
	v_pk_mul_f32 v[56:57], v[68:69], v[72:73] op_sel_hi:[1,0]
	v_pk_mul_f32 v[58:59], v[70:71], v[72:73] op_sel_hi:[1,0]
	s_waitcnt vmcnt(0) lgkmcnt(0)
	v_pk_mul_f32 v[54:55], v[50:51], v[54:55]
	v_pk_mul_f32 v[52:53], v[48:49], v[52:53]
	flat_load_dwordx4 v[48:51], v[140:141]
	s_waitcnt vmcnt(0) lgkmcnt(0)
	v_pk_mul_f32 v[58:59], v[50:51], v[58:59]
	v_pk_mul_f32 v[50:51], v[48:49], v[56:57]
	v_cvt_pk_bf16_f32 v48, v52, v53
	v_cvt_pk_bf16_f32 v49, v54, v55
	v_cvt_pk_bf16_f32 v50, v50, v51
	v_cvt_pk_bf16_f32 v51, v58, v59
	flat_store_dwordx4 v[74:75], v[48:51] offset:3072
	s_and_saveexec_b64 s[22:23], s[8:9]
	s_cbranch_execz .LBB0_801
	v_lshl_add_u64 v[48:49], v[144:145], 2, v[88:89]
	flat_store_dword v[48:49], v72

; __device__ __forceinline__ float dot4(f32x4 a) { return (a.x * a.x + a.y * a.y) + (a.z * a.z + a.w * a.w); }
; __device__ __forceinline__ f32x4 bf4lo(u32x4 w) { return (f32x4){bflo(w.x), bfhi(w.x), bflo(w.y), bfhi(w.y)}; }
; __device__ __forceinline__ f32x4 bf4hi(u32x4 w) { return (f32x4){bflo(w.z), bfhi(w.z), bflo(w.w), bfhi(w.w)}; }
; __device__ __forceinline__ void normres_phase(const bf16_t* hf, const float* xsrc, const float* gprev, bf16_t* HI, bf16_t* LO, float* RS, float* xdst, const float* gpost, float w, const float* gpre, ...
;     ...
;         for (int q = 0; q < 2; ++q) { if (q == 1 && !two) break; const int rr = q ? rowb : row;
;             float ss = 0.f;
; #pragma unroll
;             for (int c = 0; c < 4; ++c) ss += dot4(bf4lo(hw[q][c])) + dot4(bf4hi(hw[q][c]));
;             const float rs = rsqrtf(wave_sum(ss) * (1.f / D) + EPS) * w; float ss2 = 0.f;
;             const f32x4* gp4 = (const f32x4*)gpost + 2 * lane;
; #pragma unroll
;             for (int c = 0; c < 4; ++c) { xv[q][2 * c] = xv[q][2 * c] + bf4lo(hw[q][c]) * rs * gp4[128 * c]; xv[q][2 * c + 1] = xv[q][2 * c + 1] + bf4hi(hw[q][c]) * rs * gp4[128 * c + 1];
;                 ss2 += dot4(xv[q][2 * c]) + dot4(xv[q][2 * c + 1]); }
;             if (xdst) {
;                 f32x4* xo = (f32x4*)(xdst + (size_t)rr * D) + 2 * lane;
; #pragma unroll
;                 for (int c = 0; c < 4; ++c) { xo[128 * c] = xv[q][2 * c]; xo[128 * c + 1] = xv[q][2 * c + 1]; }
.LBB0_802:
	v_lshlrev_b32_e32 v54, 16, v36
	v_and_b32_e32 v73, 0xffff0000, v45
	v_and_b32_e32 v72, 0xffff0000, v44
	v_and_b32_e32 v55, 0xffff0000, v36
	v_mul_f32_e32 v36, v54, v54
	v_lshlrev_b32_e32 v56, 16, v37
	v_lshlrev_b32_e32 v71, 16, v45
	v_lshlrev_b32_e32 v70, 16, v44
	v_pk_mul_f32 v[44:45], v[72:73], v[72:73]
	v_and_b32_e32 v65, 0xffff0000, v41
	v_and_b32_e32 v64, 0xffff0000, v40
	v_pk_fma_f32 v[80:81], v[54:55], v[54:55], v[36:37] op_sel_hi:[1,1,0]
	v_and_b32_e32 v57, 0xffff0000, v37
	v_mul_f32_e32 v36, v56, v56
	v_pk_fma_f32 v[44:45], v[70:71], v[70:71], v[44:45]
	v_and_b32_e32 v69, 0xffff0000, v47
	v_and_b32_e32 v68, 0xffff0000, v46
	v_lshlrev_b32_e32 v63, 16, v41
	v_lshlrev_b32_e32 v62, 16, v40
	v_pk_mul_f32 v[40:41], v[64:65], v[64:65]
	v_pk_fma_f32 v[36:37], v[56:57], v[56:57], v[36:37] op_sel_hi:[1,1,0]
	v_lshlrev_b32_e32 v50, 16, v38
	v_pk_add_f32 v[48:49], v[44:45], v[44:45] op_sel_hi:[0,1]
	v_lshlrev_b32_e32 v67, 16, v47
	v_lshlrev_b32_e32 v66, 16, v46
	v_pk_mul_f32 v[44:45], v[68:69], v[68:69]
	v_pk_fma_f32 v[40:41], v[62:63], v[62:63], v[40:41]
	v_and_b32_e32 v61, 0xffff0000, v43
	v_and_b32_e32 v60, 0xffff0000, v42
	v_and_b32_e32 v51, 0xffff0000, v38
	v_mul_f32_e32 v36, v50, v50
	v_lshlrev_b32_e32 v52, 16, v39
	v_pk_fma_f32 v[44:45], v[66:67], v[66:67], v[44:45]
	v_pk_add_f32 v[76:77], v[40:41], v[40:41] op_sel_hi:[0,1]
	v_lshlrev_b32_e32 v59, 16, v43
	v_lshlrev_b32_e32 v58, 16, v42
	v_pk_mul_f32 v[40:41], v[60:61], v[60:61]
	v_pk_fma_f32 v[82:83], v[50:51], v[50:51], v[36:37] op_sel_hi:[1,1,0]
	v_and_b32_e32 v53, 0xffff0000, v39
	v_mul_f32_e32 v36, v52, v52
	v_pk_add_f32 v[74:75], v[44:45], v[44:45] op_sel_hi:[0,1]
	v_pk_fma_f32 v[40:41], v[58:59], v[58:59], v[40:41]
	v_pk_fma_f32 v[38:39], v[52:53], v[52:53], v[36:37] op_sel_hi:[1,1,0]
	v_lshlrev_b32_e32 v44, 16, v32
	v_and_b32_e32 v45, 0xffff0000, v32
	v_lshlrev_b32_e32 v46, 16, v33
	v_and_b32_e32 v47, 0xffff0000, v33
	v_pk_add_f32 v[78:79], v[40:41], v[40:41] op_sel_hi:[0,1]
	v_mul_f32_e32 v80, v44, v44
	v_mul_f32_e32 v36, v45, v45
	v_mul_f32_e32 v82, v46, v46
	v_mul_f32_e32 v38, v47, v47
	v_lshlrev_b32_e32 v40, 16, v34
	v_and_b32_e32 v41, 0xffff0000, v34
	v_lshlrev_b32_e32 v42, 16, v35
	v_and_b32_e32 v43, 0xffff0000, v35
	v_mul_f32_e32 v76, v40, v40
	v_mul_f32_e32 v78, v41, v41
	v_mul_f32_e32 v48, v42, v42
	v_mul_f32_e32 v74, v43, v43
	v_pk_add_f32 v[32:33], v[80:81], v[36:37]
	v_pk_add_f32 v[34:35], v[82:83], v[38:39]
	v_pk_add_f32 v[36:37], v[48:49], v[74:75]
	v_pk_add_f32 v[32:33], v[32:33], v[34:35]
	v_pk_add_f32 v[34:35], v[76:77], v[78:79]
	s_nop 0
	v_pk_add_f32 v[34:35], v[34:35], v[36:37]
	s_nop 0
	v_pk_add_f32 v[32:33], v[32:33], v[34:35]
	s_nop 0
	v_add_f32_e32 v32, v32, v33
	ds_bpermute_b32 v33, v175, v32
	s_waitcnt lgkmcnt(0)
	v_add_f32_e32 v32, v32, v33
	ds_bpermute_b32 v33, v176, v32
	s_waitcnt lgkmcnt(0)
	v_add_f32_e32 v32, v32, v33
	ds_bpermute_b32 v33, v177, v32
	s_waitcnt lgkmcnt(0)
	v_add_f32_e32 v32, v32, v33
	ds_bpermute_b32 v33, v178, v32
	s_waitcnt lgkmcnt(0)
	v_add_f32_e32 v32, v32, v33
	ds_bpermute_b32 v33, v179, v32
	s_waitcnt lgkmcnt(0)
	v_add_f32_e32 v32, v32, v33
	ds_bpermute_b32 v33, v180, v32
	s_waitcnt lgkmcnt(0)
	v_add_f32_e32 v32, v32, v33
	v_mov_b32_e32 v130, 0x358637bd
	v_fmamk_f32 v32, v32, 0x3a000000, v130
	v_cmp_gt_f32_e32 vcc, s92, v32
	v_mul_f32_e32 v33, 0x4b800000, v32
	s_nop 0
	v_cndmask_b32_e32 v32, v32, v33, vcc
	v_rsq_f32_e32 v32, v32
	s_nop 0
	v_mul_f32_e32 v33, 0x45800000, v32
	v_cndmask_b32_e32 v32, v32, v33, vcc
	v_mul_f32_e32 v48, 0.5, v32
	v_mov_b32_e32 v32, v70
	v_mov_b32_e32 v33, v72
	v_pk_mul_f32 v[36:37], v[48:49], v[32:33] op_sel_hi:[0,1]
	flat_load_dwordx4 v[32:35], v[100:101]
	v_mov_b32_e32 v72, v71
	v_pk_mul_f32 v[38:39], v[48:49], v[72:73] op_sel_hi:[0,1]
	s_waitcnt vmcnt(0) lgkmcnt(0)
	v_pk_fma_f32 v[36:37], v[32:33], v[36:37], v[4:5]
	v_mov_b32_e32 v4, v66
	v_mov_b32_e32 v5, v68
	v_pk_fma_f32 v[38:39], v[34:35], v[38:39], v[6:7]
	v_pk_mul_f32 v[32:33], v[48:49], v[4:5] op_sel_hi:[0,1]
	flat_load_dwordx4 v[4:7], v[100:101] offset:16
	v_mov_b32_e32 v68, v67
	v_pk_mul_f32 v[34:35], v[48:49], v[68:69] op_sel_hi:[0,1]
	s_waitcnt vmcnt(0) lgkmcnt(0)
	v_pk_fma_f32 v[32:33], v[4:5], v[32:33], v[0:1]
	v_mov_b32_e32 v0, v62
	v_mov_b32_e32 v1, v64
	v_pk_fma_f32 v[34:35], v[6:7], v[34:35], v[2:3]
	v_pk_mul_f32 v[4:5], v[48:49], v[0:1] op_sel_hi:[0,1]
	flat_load_dwordx4 v[0:3], v[100:101] offset:2048
	v_mov_b32_e32 v64, v63
	v_pk_mul_f32 v[6:7], v[48:49], v[64:65] op_sel_hi:[0,1]
	s_waitcnt vmcnt(0) lgkmcnt(0)
	v_pk_fma_f32 v[0:1], v[0:1], v[4:5], v[12:13]
	v_mov_b32_e32 v4, v58
	v_mov_b32_e32 v5, v60
	v_pk_fma_f32 v[2:3], v[2:3], v[6:7], v[14:15]
	v_pk_mul_f32 v[12:13], v[48:49], v[4:5] op_sel_hi:[0,1]
	flat_load_dwordx4 v[4:7], v[100:101] offset:2064
	v_mov_b32_e32 v60, v59
	v_pk_mul_f32 v[14:15], v[48:49], v[60:61] op_sel_hi:[0,1]
	s_waitcnt vmcnt(0) lgkmcnt(0)
	v_pk_fma_f32 v[14:15], v[6:7], v[14:15], v[10:11]
	v_pk_fma_f32 v[12:13], v[4:5], v[12:13], v[8:9]
	flat_load_dwordx4 v[4:7], v[114:115]
	v_pk_mul_f32 v[8:9], v[48:49], v[54:55] op_sel_hi:[0,1]
	v_pk_mul_f32 v[10:11], v[48:49], v[56:57] op_sel_hi:[0,1]
	s_waitcnt vmcnt(0) lgkmcnt(0)
	v_pk_fma_f32 v[6:7], v[6:7], v[10:11], v[22:23]
	v_pk_fma_f32 v[4:5], v[4:5], v[8:9], v[20:21]
	flat_load_dwordx4 v[8:11], v[116:117]
	v_pk_mul_f32 v[20:21], v[48:49], v[50:51] op_sel_hi:[0,1]
	v_pk_mul_f32 v[22:23], v[48:49], v[52:53] op_sel_hi:[0,1]
	s_waitcnt vmcnt(0) lgkmcnt(0)
	v_pk_fma_f32 v[18:19], v[10:11], v[22:23], v[18:19]
	v_pk_fma_f32 v[16:17], v[8:9], v[20:21], v[16:17]
	flat_load_dwordx4 v[8:11], v[118:119]
	v_pk_mul_f32 v[20:21], v[48:49], v[44:45] op_sel_hi:[0,1]
	v_pk_mul_f32 v[22:23], v[48:49], v[46:47] op_sel_hi:[0,1]
	s_waitcnt vmcnt(0) lgkmcnt(0)
	v_pk_fma_f32 v[10:11], v[10:11], v[22:23], v[30:31]
	v_pk_fma_f32 v[8:9], v[8:9], v[20:21], v[28:29]
	flat_load_dwordx4 v[28:31], v[120:121]
	v_pk_mul_f32 v[20:21], v[48:49], v[40:41] op_sel_hi:[0,1]
	v_pk_mul_f32 v[22:23], v[48:49], v[42:43] op_sel_hi:[0,1]
	s_waitcnt vmcnt(0) lgkmcnt(0)
	v_pk_fma_f32 v[22:23], v[30:31], v[22:23], v[26:27]
	v_pk_fma_f32 v[20:21], v[28:29], v[20:21], v[24:25]
	s_and_saveexec_b64 s[0:1], s[12:13]
	s_xor_b64 s[2:3], exec, s[0:1]
	s_cbranch_execz .LBB0_804
	v_lshlrev_b64 v[24:25], 13, v[142:143]
	v_lshl_add_u64 v[24:25], v[102:103], 0, v[24:25]
	flat_store_dwordx4 v[24:25], v[36:39]
	flat_store_dwordx4 v[24:25], v[32:35] offset:16
	flat_store_dwordx4 v[24:25], v[0:3] offset:2048
	flat_store_dwordx4 v[24:25], v[12:15] offset:2064
	s_nop 0
	v_add_co_u32_e32 v0, vcc, 0x1000, v24
	s_nop 1
	v_addc_co_u32_e32 v1, vcc, 0, v25, vcc
	flat_store_dwordx4 v[0:1], v[4:7]
	flat_store_dwordx4 v[0:1], v[16:19] offset:16
	flat_store_dwordx4 v[0:1], v[8:11] offset:2048
	flat_store_dwordx4 v[0:1], v[20:23] offset:2064
; __device__ __forceinline__ float dot4(f32x4 a) { return (a.x * a.x + a.y * a.y) + (a.z * a.z + a.w * a.w); }
; __device__ __forceinline__ void normres_phase(const bf16_t* hf, const float* xsrc, const float* gprev, bf16_t* HI, bf16_t* LO, float* RS, float* xdst, const float* gpost, float w, const float* gpre, ...
;     ...
;                 ss2 += dot4(xv[q][2 * c]) + dot4(xv[q][2 * c + 1]); }
;             if (xdst) {
;                 f32x4* xo = (f32x4*)(xdst + (size_t)rr * D) + 2 * lane;
; #pragma unroll
;                 for (int c = 0; c < 4; ++c) { xo[128 * c] = xv[q][2 * c]; xo[128 * c + 1] = xv[q][2 * c + 1]; }
;             } else {
;                 const float rs2 = rsqrtf(wave_sum(ss2) * (1.f / D) + EPS);
;                 const f32x4* gn4 = (const f32x4*)gpre + 2 * lane; u32x4* oh = (u32x4*)(HI + (size_t)rr * D) + lane;
; #pragma unroll
;                 for (int c = 0; c < 4; ++c) { const f32x4 y0 = xv[q][2 * c] * rs2 * gn4[128 * c], y1 = xv[q][2 * c + 1] * rs2 * gn4[128 * c + 1];
;                     oh[64 * c] = (u32x4){pk2(y0.x, y0.y), pk2(y0.z, y0.w), pk2(y1.x, y1.y), pk2(y1.z, y1.w)}; }
;                 if (lane == 0) RS[rr] = rs2;
.LBB0_804:
	s_andn2_saveexec_b64 s[2:3], s[2:3]
	s_cbranch_execz .LBB0_773
	v_pk_mul_f32 v[24:25], v[38:39], v[38:39]
	v_pk_mul_f32 v[26:27], v[36:37], v[36:37]
	s_nop 0
	v_pk_mov_b32 v[28:29], v[26:27], v[24:25] op_sel:[1,0]
	v_mov_b32_e32 v27, v25
	v_pk_add_f32 v[24:25], v[28:29], v[26:27]
	v_pk_mul_f32 v[26:27], v[34:35], v[34:35]
	v_pk_mul_f32 v[28:29], v[32:33], v[32:33]
	v_pk_add_f32 v[24:25], v[24:25], v[24:25] op_sel_hi:[0,1]
	v_pk_mov_b32 v[30:31], v[28:29], v[26:27] op_sel:[1,0]
	v_mov_b32_e32 v29, v27
	v_pk_add_f32 v[26:27], v[30:31], v[28:29]
	v_pk_mul_f32 v[28:29], v[2:3], v[2:3]
	v_pk_mul_f32 v[30:31], v[0:1], v[0:1]
	v_mul_f32_e32 v24, v4, v4
	v_pk_mov_b32 v[40:41], v[30:31], v[28:29] op_sel:[1,0]
	v_mov_b32_e32 v31, v29
	v_pk_add_f32 v[28:29], v[40:41], v[30:31]
	v_pk_mul_f32 v[30:31], v[14:15], v[14:15]
	v_pk_mul_f32 v[40:41], v[12:13], v[12:13]
	v_pk_add_f32 v[26:27], v[26:27], v[26:27] op_sel_hi:[0,1]
	v_pk_mov_b32 v[42:43], v[40:41], v[30:31] op_sel:[1,0]
	v_mov_b32_e32 v41, v31
	v_pk_add_f32 v[30:31], v[42:43], v[40:41]
	v_pk_fma_f32 v[40:41], v[4:5], v[4:5], v[24:25] op_sel_hi:[1,1,0]
	v_mul_f32_e32 v24, v6, v6
	v_pk_fma_f32 v[42:43], v[6:7], v[6:7], v[24:25] op_sel_hi:[1,1,0]
	v_mul_f32_e32 v24, v16, v16
	v_pk_add_f32 v[28:29], v[28:29], v[28:29] op_sel_hi:[0,1]
	v_pk_add_f32 v[30:31], v[30:31], v[30:31] op_sel_hi:[0,1]
	v_pk_fma_f32 v[44:45], v[16:17], v[16:17], v[24:25] op_sel_hi:[1,1,0]
	v_mul_f32_e32 v24, v18, v18
	v_pk_fma_f32 v[46:47], v[18:19], v[18:19], v[24:25] op_sel_hi:[1,1,0]
	v_mul_f32_e32 v24, v20, v20
	v_mul_f32_e32 v26, v21, v21
	v_mul_f32_e32 v28, v22, v22
	v_mul_f32_e32 v30, v23, v23
	v_pk_add_f32 v[24:25], v[24:25], v[26:27]
	v_pk_add_f32 v[26:27], v[28:29], v[30:31]
	flat_load_dwordx4 v[28:31], v[104:105]
	v_mul_f32_e32 v40, v8, v8
	v_mul_f32_e32 v42, v9, v9
	v_mul_f32_e32 v44, v10, v10
	v_mul_f32_e32 v46, v11, v11
	v_pk_add_f32 v[40:41], v[40:41], v[42:43]
	v_pk_add_f32 v[42:43], v[44:45], v[46:47]
	v_pk_add_f32 v[24:25], v[24:25], v[26:27]
	v_pk_add_f32 v[40:41], v[40:41], v[42:43]
	v_lshlrev_b64 v[26:27], 12, v[142:143]
	v_pk_add_f32 v[24:25], v[40:41], v[24:25]
	v_lshl_add_u64 v[26:27], v[96:97], 0, v[26:27]
	v_add_f32_e32 v24, v24, v25
	ds_bpermute_b32 v25, v175, v24
	s_waitcnt lgkmcnt(0)
	v_add_f32_e32 v24, v24, v25
	ds_bpermute_b32 v25, v176, v24
	s_waitcnt lgkmcnt(0)
	v_add_f32_e32 v24, v24, v25
	ds_bpermute_b32 v25, v177, v24
	s_waitcnt lgkmcnt(0)
	v_add_f32_e32 v24, v24, v25
	ds_bpermute_b32 v25, v178, v24
	s_waitcnt lgkmcnt(0)
	v_add_f32_e32 v24, v24, v25
	ds_bpermute_b32 v25, v179, v24
	s_waitcnt lgkmcnt(0)
	v_add_f32_e32 v24, v24, v25
	ds_bpermute_b32 v25, v180, v24
	s_waitcnt lgkmcnt(0)
	v_add_f32_e32 v24, v24, v25
	v_mov_b32_e32 v130, 0x358637bd
	v_fmamk_f32 v24, v24, 0x3a000000, v130
	v_cmp_gt_f32_e32 vcc, s92, v24
	v_mul_f32_e32 v25, 0x4b800000, v24
	s_nop 0
	v_cndmask_b32_e32 v24, v24, v25, vcc
	v_rsq_f32_e32 v24, v24
	s_nop 0
	v_mul_f32_e32 v25, 0x45800000, v24
	v_cndmask_b32_e32 v24, v24, v25, vcc
	v_pk_mul_f32 v[36:37], v[36:37], v[24:25] op_sel_hi:[1,0]
	v_pk_mul_f32 v[38:39], v[38:39], v[24:25] op_sel_hi:[1,0]
	v_pk_mul_f32 v[32:33], v[32:33], v[24:25] op_sel_hi:[1,0]
	v_pk_mul_f32 v[34:35], v[34:35], v[24:25] op_sel_hi:[1,0]
	v_pk_mul_f32 v[12:13], v[12:13], v[24:25] op_sel_hi:[1,0]
	v_pk_mul_f32 v[14:15], v[14:15], v[24:25] op_sel_hi:[1,0]
	v_pk_mul_f32 v[4:5], v[4:5], v[24:25] op_sel_hi:[1,0]
	v_pk_mul_f32 v[6:7], v[6:7], v[24:25] op_sel_hi:[1,0]
	s_waitcnt vmcnt(0)
	v_pk_mul_f32 v[38:39], v[30:31], v[38:39]
	v_pk_mul_f32 v[36:37], v[28:29], v[36:37]
	flat_load_dwordx4 v[28:31], v[104:105] offset:16
	s_waitcnt vmcnt(0) lgkmcnt(0)
	v_pk_mul_f32 v[34:35], v[30:31], v[34:35]
	v_pk_mul_f32 v[30:31], v[28:29], v[32:33]
	v_cvt_pk_bf16_f32 v28, v36, v37
	v_cvt_pk_bf16_f32 v29, v38, v39
	v_cvt_pk_bf16_f32 v30, v30, v31
	v_cvt_pk_bf16_f32 v31, v34, v35
	flat_store_dwordx4 v[26:27], v[28:31]
	s_nop 1
	v_pk_mul_f32 v[28:29], v[0:1], v[24:25] op_sel_hi:[1,0]
	v_pk_mul_f32 v[30:31], v[2:3], v[24:25] op_sel_hi:[1,0]
	flat_load_dwordx4 v[0:3], v[104:105] offset:2048
	s_waitcnt vmcnt(0) lgkmcnt(0)
	v_pk_mul_f32 v[30:31], v[2:3], v[30:31]
	v_pk_mul_f32 v[28:29], v[0:1], v[28:29]
	flat_load_dwordx4 v[0:3], v[104:105] offset:2064
	s_waitcnt vmcnt(0) lgkmcnt(0)
	v_pk_mul_f32 v[14:15], v[2:3], v[14:15]
	v_pk_mul_f32 v[2:3], v[0:1], v[12:13]
	v_cvt_pk_bf16_f32 v0, v28, v29
	v_cvt_pk_bf16_f32 v1, v30, v31
	v_cvt_pk_bf16_f32 v2, v2, v3
	v_cvt_pk_bf16_f32 v3, v14, v15
	flat_store_dwordx4 v[26:27], v[0:3] offset:1024
	flat_load_dwordx4 v[0:3], v[122:123]
	v_pk_mul_f32 v[12:13], v[16:17], v[24:25] op_sel_hi:[1,0]
	v_pk_mul_f32 v[14:15], v[18:19], v[24:25] op_sel_hi:[1,0]
	s_waitcnt vmcnt(0) lgkmcnt(0)
	v_pk_mul_f32 v[6:7], v[2:3], v[6:7]
	v_pk_mul_f32 v[4:5], v[0:1], v[4:5]
	flat_load_dwordx4 v[0:3], v[124:125]
	s_waitcnt vmcnt(0) lgkmcnt(0)
	v_pk_mul_f32 v[14:15], v[2:3], v[14:15]
	v_pk_mul_f32 v[2:3], v[0:1], v[12:13]
	v_cvt_pk_bf16_f32 v0, v4, v5
	v_cvt_pk_bf16_f32 v1, v6, v7
	v_cvt_pk_bf16_f32 v2, v2, v3
	v_cvt_pk_bf16_f32 v3, v14, v15
	flat_store_dwordx4 v[26:27], v[0:3] offset:2048
	flat_load_dwordx4 v[0:3], v[126:127]
	v_pk_mul_f32 v[4:5], v[8:9], v[24:25] op_sel_hi:[1,0]
	v_pk_mul_f32 v[6:7], v[10:11], v[24:25] op_sel_hi:[1,0]
	v_pk_mul_f32 v[8:9], v[20:21], v[24:25] op_sel_hi:[1,0]
	v_pk_mul_f32 v[10:11], v[22:23], v[24:25] op_sel_hi:[1,0]
	s_waitcnt vmcnt(0) lgkmcnt(0)
	v_pk_mul_f32 v[6:7], v[2:3], v[6:7]
	v_pk_mul_f32 v[4:5], v[0:1], v[4:5]
	flat_load_dwordx4 v[0:3], v[140:141]
	s_waitcnt vmcnt(0) lgkmcnt(0)
	v_pk_mul_f32 v[10:11], v[2:3], v[10:11]
	v_pk_mul_f32 v[2:3], v[0:1], v[8:9]
	v_cvt_pk_bf16_f32 v0, v4, v5
	v_cvt_pk_bf16_f32 v1, v6, v7
	v_cvt_pk_bf16_f32 v2, v2, v3
	v_cvt_pk_bf16_f32 v3, v10, v11
	flat_store_dwordx4 v[26:27], v[0:3] offset:3072
	s_and_saveexec_b64 s[24:25], s[8:9]
	s_cbranch_execz .LBB0_772
	v_lshl_add_u64 v[0:1], v[142:143], 2, v[88:89]
	flat_store_dword v[0:1], v24
	s_branch .LBB0_772

; __global__ void __launch_bounds__(NTHREADS) fwd_megakernel(Params p_unused) {
;     extern __shared__ __attribute__((aligned(16))) unsigned char lds_raw[];
	.amdhsa_kernel _Z14fwd_megakernel6Params
		.amdhsa_group_segment_fixed_size 0
		.amdhsa_private_segment_fixed_size 0
		.amdhsa_kernarg_size 400
		.amdhsa_user_sgpr_count 2
		.amdhsa_user_sgpr_dispatch_ptr 0
		.amdhsa_user_sgpr_queue_ptr 0
		.amdhsa_user_sgpr_kernarg_segment_ptr 1
		.amdhsa_user_sgpr_dispatch_id 0
		.amdhsa_user_sgpr_kernarg_preload_length 0
		.amdhsa_user_sgpr_kernarg_preload_offset 0
		.amdhsa_user_sgpr_private_segment_size 0
		.amdhsa_uses_dynamic_stack 0
		.amdhsa_enable_private_segment 0
		.amdhsa_system_sgpr_workgroup_id_x 1
		.amdhsa_system_sgpr_workgroup_id_y 0
		.amdhsa_system_sgpr_workgroup_id_z 0
		.amdhsa_system_sgpr_workgroup_info 0
		.amdhsa_system_vgpr_workitem_id 2
		.amdhsa_next_free_vgpr 256
		.amdhsa_next_free_sgpr 102
		.amdhsa_accum_offset 256
		.amdhsa_reserve_vcc 1
		.amdhsa_float_round_mode_32 0
		.amdhsa_float_round_mode_16_64 0
		.amdhsa_float_denorm_mode_32 3
		.amdhsa_float_denorm_mode_16_64 3
		.amdhsa_dx10_clamp 1
		.amdhsa_ieee_mode 1
		.amdhsa_fp16_overflow 0
		.amdhsa_tg_split 0
		.amdhsa_exception_fp_ieee_invalid_op 0
		.amdhsa_exception_fp_denorm_src 0
		.amdhsa_exception_fp_ieee_div_zero 0
		.amdhsa_exception_fp_ieee_overflow 0
		.amdhsa_exception_fp_ieee_underflow 0
		.amdhsa_exception_fp_ieee_inexact 0
		.amdhsa_exception_int_div_zero 0
	.end_amdhsa_kernel
